# v13 with 1-deep residual prefetch (next block's loads issued after the current block's data is consumed)
# speedup vs baseline: 1.0104x; 1.0104x over previous
;     __device__ __forceinline__ void operator()(const f32x4 (&acc)[2][2][4][2], const Unit& u, int wr, int wc, int fr, int fq) const {
;         const int row0 = u.pm * BM + wr * 64 + fr, col0 = u.pn * BM + wc * 32 + 4 * fq;
;         const float* rbase = (u.pm * BM < SEQ_P) ? resA : (resB - (size_t)SEQ_P * ldc);
;         f32x4 wv[2][2];
;         if (xn) {
; #pragma unroll
;             for (int bj = 0; bj < 2; ++bj)
; #pragma unroll
;                 for (int n = 0; n < 2; ++n) wv[bj][n] = *(const f32x4*)(wn + col0 + bj * HALF + n * 16);
;         }
; #pragma unroll
;         for (int ai = 0; ai < 2; ++ai)
; #pragma unroll
;             for (int m = 0; m < 4; ++m) {
;                 const int row = row0 + ai * HALF + m * 16;
;                 const size_t off = (size_t)row * ldc + col0;
;                 float q = 0.f;
; #pragma unroll
;                 for (int bj = 0; bj < 2; ++bj)
; #pragma unroll
;                     for (int n = 0; n < 2; ++n) {
;                         const f32x4 rv = *(const f32x4*)(rbase + off + bj * HALF + n * 16);
;                         const f32x4 v = rv + acc[ai][bj][m][n] * scale;
;                         if (out) *(f32x4*)(out + off + bj * HALF + n * 16) = v;
;                         if (xn) { q += (v.x * v.x + v.y * v.y) + (v.z * v.z + v.w * v.w); const f32x4 o = v * wv[bj][n];
;                             u32x2 p; p.x = pk2(o.x, o.y); p.y = pk2(o.z, o.w); *(u32x2*)(xn + off + bj * HALF + n * 16) = p; }
;                     }
;                 if (xn) { q += __shfl_xor(q, 16); q += __shfl_xor(q, 32); if (fq == 0) (void)__hip_atomic_fetch_add(ss + row, q, __ATOMIC_RELAXED, __HIP_MEMORY_SCOPE_AGENT); }
;             }
;     }
.LBB0_312:
	v_lshl_add_u32 v196, s62, 8, v168
	v_lshl_or_b32 v198, s61, 8, v170
	v_and_b32_e32 v227, 8, v174
	v_mov_b32_e32 v197, 0
	v_cmp_eq_u32_e64 s[34:35], 0, v227
	v_lshlrev_b32_e32 v219, 1, v227
	v_add_u32_e32 v200, v198, v219
	v_sub_u32_e32 v224, 16, v219
	v_add_u32_e32 v224, v198, v224
	v_mov_b32_e32 v198, v200
	v_mov_b32_e32 v200, v224
	v_mov_b32_e32 v199, 0
	v_mov_b32_e32 v201, 0
	v_sub_u32_e32 v194, v196, v227
	v_mov_b32_e32 v195, 0
	v_lshlrev_b64 v[192:193], 11, v[194:195]
	v_add_u32_e32 v194, 8, v194
	v_lshlrev_b64 v[194:195], 11, v[194:195]
	s_cmp_lt_i32 s62, 32
	s_cselect_b32 s31, s2, s54
	s_cselect_b32 s30, s33, s53
	v_lshl_add_u64 v[192:193], v[192:193], 0, v[198:199]
	v_lshl_add_u64 v[194:195], v[194:195], 0, v[200:201]
	v_lshl_add_u64 v[164:165], v[192:193], 2, s[30:31]
	v_lshl_add_u64 v[184:185], v[194:195], 2, s[30:31]
	v_lshl_add_u64 v[186:187], v[198:199], 2, s[10:11]
	v_lshl_add_u64 v[188:189], v[200:201], 2, s[10:11]
	global_load_dwordx4 v[64:67], v[186:187], off
	global_load_dwordx4 v[72:75], v[186:187], off offset:512
	global_load_dwordx4 v[80:83], v[188:189], off
	global_load_dwordx4 v[84:87], v[188:189], off offset:512
	global_load_dwordx4 v[156:159], v[164:165], off
	global_load_dwordx4 v[160:163], v[164:165], off offset:512
	global_load_dwordx4 v[176:179], v[184:185], off
	global_load_dwordx4 v[180:183], v[184:185], off offset:512
	s_mov_b64 vcc, 0x20000
	v_lshl_add_u64 v[164:165], v[164:165], 0, vcc
	v_lshl_add_u64 v[184:185], v[184:185], 0, vcc
	v_lshl_add_u64 v[202:203], v[192:193], 2, s[8:9]
	v_lshl_add_u64 v[204:205], v[194:195], 2, s[8:9]
	v_lshl_add_u64 v[186:187], v[192:193], 1, s[14:15]
	v_lshl_add_u64 v[188:189], v[194:195], 1, s[14:15]
	v_lshl_add_u64 v[190:191], v[196:197], 2, s[18:19]
	v_xor_b32_e32 v225, 16, v174
	v_xor_b32_e32 v226, 32, v174
	v_lshlrev_b32_e32 v225, 2, v225
	v_lshlrev_b32_e32 v226, 2, v226
	v_mov_b32_dpp v220, v136 row_ror:8 row_mask:0xf bank_mask:0xf
	v_mov_b32_dpp v221, v137 row_ror:8 row_mask:0xf bank_mask:0xf
	v_mov_b32_dpp v222, v138 row_ror:8 row_mask:0xf bank_mask:0xf
	v_mov_b32_dpp v223, v139 row_ror:8 row_mask:0xf bank_mask:0xf
	v_cndmask_b32_e64 v136, v220, v140, s[34:35]
	v_cndmask_b32_e64 v137, v221, v141, s[34:35]
	v_cndmask_b32_e64 v138, v222, v142, s[34:35]
	v_cndmask_b32_e64 v139, v223, v143, s[34:35]
	v_cndmask_b32_e64 v140, v140, v220, s[34:35]
	v_cndmask_b32_e64 v141, v141, v221, s[34:35]
	v_cndmask_b32_e64 v142, v142, v222, s[34:35]
	v_cndmask_b32_e64 v143, v143, v223, s[34:35]
	v_mov_b32_dpp v220, v128 row_ror:8 row_mask:0xf bank_mask:0xf
	v_mov_b32_dpp v221, v129 row_ror:8 row_mask:0xf bank_mask:0xf
	v_mov_b32_dpp v222, v130 row_ror:8 row_mask:0xf bank_mask:0xf
	v_mov_b32_dpp v223, v131 row_ror:8 row_mask:0xf bank_mask:0xf
	v_cndmask_b32_e64 v128, v220, v132, s[34:35]
	v_cndmask_b32_e64 v129, v221, v133, s[34:35]
	v_cndmask_b32_e64 v130, v222, v134, s[34:35]
	v_cndmask_b32_e64 v131, v223, v135, s[34:35]
	v_cndmask_b32_e64 v132, v132, v220, s[34:35]
	v_cndmask_b32_e64 v133, v133, v221, s[34:35]
	v_cndmask_b32_e64 v134, v134, v222, s[34:35]
	v_cndmask_b32_e64 v135, v135, v223, s[34:35]
	s_waitcnt vmcnt(0)
	v_pk_fma_f32 v[138:139], v[138:139], 0.5, v[158:159] op_sel_hi:[1,0,1]
	v_pk_fma_f32 v[136:137], v[136:137], 0.5, v[156:157] op_sel_hi:[1,0,1]
	global_store_dwordx4 v[202:203], v[136:139], off
	v_pk_mul_f32 v[208:209], v[64:65], v[136:137]
	v_pk_mul_f32 v[210:211], v[66:67], v[138:139]
	v_mul_f32_e32 v219, v136, v136
	v_add_u32_e32 v208, 0x8000, v208
	v_add_u32_e32 v209, 0x8000, v209
	v_add_u32_e32 v210, 0x8000, v210
	v_add_u32_e32 v211, 0x8000, v211
	v_fmac_f32_e32 v219, v137, v137
	v_fmac_f32_e32 v219, v138, v138
	v_fmac_f32_e32 v219, v139, v139
	v_perm_b32 v206, v209, v208, s58
	v_perm_b32 v207, v211, v210, s58
	global_store_dwordx2 v[186:187], v[206:207], off
	v_pk_fma_f32 v[130:131], v[130:131], 0.5, v[162:163] op_sel_hi:[1,0,1]
	v_pk_fma_f32 v[128:129], v[128:129], 0.5, v[160:161] op_sel_hi:[1,0,1]
	global_store_dwordx4 v[202:203], v[128:131], off offset:512
	v_pk_mul_f32 v[212:213], v[72:73], v[128:129]
	v_pk_mul_f32 v[214:215], v[74:75], v[130:131]
	v_fmac_f32_e32 v219, v128, v128
	v_add_u32_e32 v212, 0x8000, v212
	v_add_u32_e32 v213, 0x8000, v213
	v_add_u32_e32 v214, 0x8000, v214
	v_add_u32_e32 v215, 0x8000, v215
	v_fmac_f32_e32 v219, v129, v129
	v_fmac_f32_e32 v219, v130, v130
	v_fmac_f32_e32 v219, v131, v131
	v_perm_b32 v216, v213, v212, s58
	v_perm_b32 v217, v215, v214, s58
	global_store_dwordx2 v[186:187], v[216:217], off offset:256
	v_pk_fma_f32 v[142:143], v[142:143], 0.5, v[178:179] op_sel_hi:[1,0,1]
	v_pk_fma_f32 v[140:141], v[140:141], 0.5, v[176:177] op_sel_hi:[1,0,1]
	global_store_dwordx4 v[204:205], v[140:143], off
	v_pk_mul_f32 v[208:209], v[80:81], v[140:141]
	v_pk_mul_f32 v[210:211], v[82:83], v[142:143]
	v_mul_f32_e32 v224, v140, v140
	v_add_u32_e32 v208, 0x8000, v208
	v_add_u32_e32 v209, 0x8000, v209
	v_add_u32_e32 v210, 0x8000, v210
	v_add_u32_e32 v211, 0x8000, v211
	v_fmac_f32_e32 v224, v141, v141
	v_fmac_f32_e32 v224, v142, v142
	v_fmac_f32_e32 v224, v143, v143
	v_perm_b32 v206, v209, v208, s58
	v_perm_b32 v207, v211, v210, s58
	global_store_dwordx2 v[188:189], v[206:207], off
	v_pk_fma_f32 v[134:135], v[134:135], 0.5, v[182:183] op_sel_hi:[1,0,1]
	v_pk_fma_f32 v[132:133], v[132:133], 0.5, v[180:181] op_sel_hi:[1,0,1]
	global_store_dwordx4 v[204:205], v[132:135], off offset:512
	v_pk_mul_f32 v[212:213], v[84:85], v[132:133]
	v_pk_mul_f32 v[214:215], v[86:87], v[134:135]
	v_fmac_f32_e32 v224, v132, v132
	v_add_u32_e32 v212, 0x8000, v212
	v_add_u32_e32 v213, 0x8000, v213
	v_add_u32_e32 v214, 0x8000, v214
	v_add_u32_e32 v215, 0x8000, v215
	v_fmac_f32_e32 v224, v133, v133
	v_fmac_f32_e32 v224, v134, v134
	v_fmac_f32_e32 v224, v135, v135
	v_perm_b32 v216, v213, v212, s58
	v_perm_b32 v217, v215, v214, s58
	global_store_dwordx2 v[188:189], v[216:217], off offset:256
	s_nop 1
	v_mov_b32_dpp v175, v219 row_ror:8 row_mask:0xf bank_mask:0xf
	v_mov_b32_dpp v218, v224 row_ror:8 row_mask:0xf bank_mask:0xf
	v_add_f32_e32 v219, v219, v175
	v_add_f32_e32 v224, v224, v218
	v_cndmask_b32_e64 v219, v224, v219, s[34:35]
	s_nop 0
	ds_bpermute_b32 v175, v225, v219
	global_load_dwordx4 v[156:159], v[164:165], off
	global_load_dwordx4 v[160:163], v[164:165], off offset:512
	global_load_dwordx4 v[176:179], v[184:185], off
	global_load_dwordx4 v[180:183], v[184:185], off offset:512
	s_mov_b64 vcc, 0x20000
	v_lshl_add_u64 v[164:165], v[164:165], 0, vcc
	v_lshl_add_u64 v[184:185], v[184:185], 0, vcc
	s_mov_b64 vcc, 0x20000
	v_lshl_add_u64 v[202:203], v[202:203], 0, vcc
	v_lshl_add_u64 v[204:205], v[204:205], 0, vcc
	s_mov_b64 vcc, 0x10000
	v_lshl_add_u64 v[186:187], v[186:187], 0, vcc
	v_lshl_add_u64 v[188:189], v[188:189], 0, vcc
	s_waitcnt lgkmcnt(0)
;     __device__ __forceinline__ void operator()(const f32x4 (&acc)[2][2][4][2], const Unit& u, int wr, int wc, int fr, int fq) const {
;         const int row0 = u.pm * BM + wr * 64 + fr, col0 = u.pn * BM + wc * 32 + 4 * fq;
;         const float* rbase = (u.pm * BM < SEQ_P) ? resA : (resB - (size_t)SEQ_P * ldc);
;         f32x4 wv[2][2];
;         if (xn) {
; #pragma unroll
;             for (int bj = 0; bj < 2; ++bj)
; #pragma unroll
;                 for (int n = 0; n < 2; ++n) wv[bj][n] = *(const f32x4*)(wn + col0 + bj * HALF + n * 16);
;         }
; #pragma unroll
;         for (int ai = 0; ai < 2; ++ai)
; #pragma unroll
;             for (int m = 0; m < 4; ++m) {
;                 const int row = row0 + ai * HALF + m * 16;
;                 const size_t off = (size_t)row * ldc + col0;
;                 float q = 0.f;
; #pragma unroll
;                 for (int bj = 0; bj < 2; ++bj)
; #pragma unroll
;                     for (int n = 0; n < 2; ++n) {
;                         const f32x4 rv = *(const f32x4*)(rbase + off + bj * HALF + n * 16);
;                         const f32x4 v = rv + acc[ai][bj][m][n] * scale;
;                         if (out) *(f32x4*)(out + off + bj * HALF + n * 16) = v;
;                         if (xn) { q += (v.x * v.x + v.y * v.y) + (v.z * v.z + v.w * v.w); const f32x4 o = v * wv[bj][n];
;                             u32x2 p; p.x = pk2(o.x, o.y); p.y = pk2(o.z, o.w); *(u32x2*)(xn + off + bj * HALF + n * 16) = p; }
;                     }
;                 if (xn) { q += __shfl_xor(q, 16); q += __shfl_xor(q, 32); if (fq == 0) (void)__hip_atomic_fetch_add(ss + row, q, __ATOMIC_RELAXED, __HIP_MEMORY_SCOPE_AGENT); }
;             }
;     }
	v_add_f32_e32 v219, v219, v175
	s_nop 0
	ds_bpermute_b32 v218, v226, v219
	s_waitcnt lgkmcnt(0)
	v_add_f32_e32 v219, v219, v218
	s_mov_b64 exec, s[0:1]
	global_atomic_add_f32 v[190:191], v219, off
	s_mov_b64 exec, -1
	s_mov_b64 vcc, 64
	v_lshl_add_u64 v[190:191], v[190:191], 0, vcc
	v_mov_b32_dpp v220, v120 row_ror:8 row_mask:0xf bank_mask:0xf
	v_mov_b32_dpp v221, v121 row_ror:8 row_mask:0xf bank_mask:0xf
	v_mov_b32_dpp v222, v122 row_ror:8 row_mask:0xf bank_mask:0xf
	v_mov_b32_dpp v223, v123 row_ror:8 row_mask:0xf bank_mask:0xf
	v_cndmask_b32_e64 v120, v220, v124, s[34:35]
	v_cndmask_b32_e64 v121, v221, v125, s[34:35]
	v_cndmask_b32_e64 v122, v222, v126, s[34:35]
	v_cndmask_b32_e64 v123, v223, v127, s[34:35]
	v_cndmask_b32_e64 v124, v124, v220, s[34:35]
	v_cndmask_b32_e64 v125, v125, v221, s[34:35]
	v_cndmask_b32_e64 v126, v126, v222, s[34:35]
	v_cndmask_b32_e64 v127, v127, v223, s[34:35]
	v_mov_b32_dpp v220, v112 row_ror:8 row_mask:0xf bank_mask:0xf
	v_mov_b32_dpp v221, v113 row_ror:8 row_mask:0xf bank_mask:0xf
	v_mov_b32_dpp v222, v114 row_ror:8 row_mask:0xf bank_mask:0xf
	v_mov_b32_dpp v223, v115 row_ror:8 row_mask:0xf bank_mask:0xf
	v_cndmask_b32_e64 v112, v220, v116, s[34:35]
	v_cndmask_b32_e64 v113, v221, v117, s[34:35]
	v_cndmask_b32_e64 v114, v222, v118, s[34:35]
	v_cndmask_b32_e64 v115, v223, v119, s[34:35]
	v_cndmask_b32_e64 v116, v116, v220, s[34:35]
	v_cndmask_b32_e64 v117, v117, v221, s[34:35]
	v_cndmask_b32_e64 v118, v118, v222, s[34:35]
	v_cndmask_b32_e64 v119, v119, v223, s[34:35]
	s_waitcnt vmcnt(1)
	v_pk_fma_f32 v[122:123], v[122:123], 0.5, v[158:159] op_sel_hi:[1,0,1]
	v_pk_fma_f32 v[120:121], v[120:121], 0.5, v[156:157] op_sel_hi:[1,0,1]
	global_store_dwordx4 v[202:203], v[120:123], off
	v_pk_mul_f32 v[208:209], v[64:65], v[120:121]
	v_pk_mul_f32 v[210:211], v[66:67], v[122:123]
	v_mul_f32_e32 v219, v120, v120
	v_add_u32_e32 v208, 0x8000, v208
	v_add_u32_e32 v209, 0x8000, v209
	v_add_u32_e32 v210, 0x8000, v210
	v_add_u32_e32 v211, 0x8000, v211
	v_fmac_f32_e32 v219, v121, v121
	v_fmac_f32_e32 v219, v122, v122
	v_fmac_f32_e32 v219, v123, v123
	v_perm_b32 v206, v209, v208, s58
	v_perm_b32 v207, v211, v210, s58
	global_store_dwordx2 v[186:187], v[206:207], off
	v_pk_fma_f32 v[114:115], v[114:115], 0.5, v[162:163] op_sel_hi:[1,0,1]
	v_pk_fma_f32 v[112:113], v[112:113], 0.5, v[160:161] op_sel_hi:[1,0,1]
	global_store_dwordx4 v[202:203], v[112:115], off offset:512
	v_pk_mul_f32 v[212:213], v[72:73], v[112:113]
	v_pk_mul_f32 v[214:215], v[74:75], v[114:115]
	v_fmac_f32_e32 v219, v112, v112
	v_add_u32_e32 v212, 0x8000, v212
	v_add_u32_e32 v213, 0x8000, v213
	v_add_u32_e32 v214, 0x8000, v214
	v_add_u32_e32 v215, 0x8000, v215
	v_fmac_f32_e32 v219, v113, v113
	v_fmac_f32_e32 v219, v114, v114
	v_fmac_f32_e32 v219, v115, v115
	v_perm_b32 v216, v213, v212, s58
	v_perm_b32 v217, v215, v214, s58
	global_store_dwordx2 v[186:187], v[216:217], off offset:256
	v_pk_fma_f32 v[126:127], v[126:127], 0.5, v[178:179] op_sel_hi:[1,0,1]
	v_pk_fma_f32 v[124:125], v[124:125], 0.5, v[176:177] op_sel_hi:[1,0,1]
	global_store_dwordx4 v[204:205], v[124:127], off
	v_pk_mul_f32 v[208:209], v[80:81], v[124:125]
	v_pk_mul_f32 v[210:211], v[82:83], v[126:127]
	v_mul_f32_e32 v224, v124, v124
	v_add_u32_e32 v208, 0x8000, v208
	v_add_u32_e32 v209, 0x8000, v209
	v_add_u32_e32 v210, 0x8000, v210
	v_add_u32_e32 v211, 0x8000, v211
	v_fmac_f32_e32 v224, v125, v125
	v_fmac_f32_e32 v224, v126, v126
	v_fmac_f32_e32 v224, v127, v127
	v_perm_b32 v206, v209, v208, s58
	v_perm_b32 v207, v211, v210, s58
	global_store_dwordx2 v[188:189], v[206:207], off
	v_pk_fma_f32 v[118:119], v[118:119], 0.5, v[182:183] op_sel_hi:[1,0,1]
	v_pk_fma_f32 v[116:117], v[116:117], 0.5, v[180:181] op_sel_hi:[1,0,1]
	global_store_dwordx4 v[204:205], v[116:119], off offset:512
	v_pk_mul_f32 v[212:213], v[84:85], v[116:117]
	v_pk_mul_f32 v[214:215], v[86:87], v[118:119]
	v_fmac_f32_e32 v224, v116, v116
	v_add_u32_e32 v212, 0x8000, v212
	v_add_u32_e32 v213, 0x8000, v213
	v_add_u32_e32 v214, 0x8000, v214
	v_add_u32_e32 v215, 0x8000, v215
	v_fmac_f32_e32 v224, v117, v117
	v_fmac_f32_e32 v224, v118, v118
	v_fmac_f32_e32 v224, v119, v119
	v_perm_b32 v216, v213, v212, s58
	v_perm_b32 v217, v215, v214, s58
	global_store_dwordx2 v[188:189], v[216:217], off offset:256
	s_nop 1
	v_mov_b32_dpp v175, v219 row_ror:8 row_mask:0xf bank_mask:0xf
	v_mov_b32_dpp v218, v224 row_ror:8 row_mask:0xf bank_mask:0xf
	v_add_f32_e32 v219, v219, v175
	v_add_f32_e32 v224, v224, v218
	v_cndmask_b32_e64 v219, v224, v219, s[34:35]
	s_nop 0
	ds_bpermute_b32 v175, v225, v219
	global_load_dwordx4 v[156:159], v[164:165], off
	global_load_dwordx4 v[160:163], v[164:165], off offset:512
	global_load_dwordx4 v[176:179], v[184:185], off
	global_load_dwordx4 v[180:183], v[184:185], off offset:512
	s_mov_b64 vcc, 0x20000
	v_lshl_add_u64 v[164:165], v[164:165], 0, vcc
	v_lshl_add_u64 v[184:185], v[184:185], 0, vcc
	s_mov_b64 vcc, 0x20000
	v_lshl_add_u64 v[202:203], v[202:203], 0, vcc
	v_lshl_add_u64 v[204:205], v[204:205], 0, vcc
	s_mov_b64 vcc, 0x10000
	v_lshl_add_u64 v[186:187], v[186:187], 0, vcc
	v_lshl_add_u64 v[188:189], v[188:189], 0, vcc
	s_waitcnt lgkmcnt(0)
	v_add_f32_e32 v219, v219, v175
	s_nop 0
	ds_bpermute_b32 v218, v226, v219
	s_waitcnt lgkmcnt(0)
;     __device__ __forceinline__ void operator()(const f32x4 (&acc)[2][2][4][2], const Unit& u, int wr, int wc, int fr, int fq) const {
;         const int row0 = u.pm * BM + wr * 64 + fr, col0 = u.pn * BM + wc * 32 + 4 * fq;
;         const float* rbase = (u.pm * BM < SEQ_P) ? resA : (resB - (size_t)SEQ_P * ldc);
;         f32x4 wv[2][2];
;         if (xn) {
; #pragma unroll
;             for (int bj = 0; bj < 2; ++bj)
; #pragma unroll
;                 for (int n = 0; n < 2; ++n) wv[bj][n] = *(const f32x4*)(wn + col0 + bj * HALF + n * 16);
;         }
; #pragma unroll
;         for (int ai = 0; ai < 2; ++ai)
; #pragma unroll
;             for (int m = 0; m < 4; ++m) {
;                 const int row = row0 + ai * HALF + m * 16;
;                 const size_t off = (size_t)row * ldc + col0;
;                 float q = 0.f;
; #pragma unroll
;                 for (int bj = 0; bj < 2; ++bj)
; #pragma unroll
;                     for (int n = 0; n < 2; ++n) {
;                         const f32x4 rv = *(const f32x4*)(rbase + off + bj * HALF + n * 16);
;                         const f32x4 v = rv + acc[ai][bj][m][n] * scale;
;                         if (out) *(f32x4*)(out + off + bj * HALF + n * 16) = v;
;                         if (xn) { q += (v.x * v.x + v.y * v.y) + (v.z * v.z + v.w * v.w); const f32x4 o = v * wv[bj][n];
;                             u32x2 p; p.x = pk2(o.x, o.y); p.y = pk2(o.z, o.w); *(u32x2*)(xn + off + bj * HALF + n * 16) = p; }
;                     }
;                 if (xn) { q += __shfl_xor(q, 16); q += __shfl_xor(q, 32); if (fq == 0) (void)__hip_atomic_fetch_add(ss + row, q, __ATOMIC_RELAXED, __HIP_MEMORY_SCOPE_AGENT); }
;             }
;     }
	v_add_f32_e32 v219, v219, v218
	s_mov_b64 exec, s[0:1]
	global_atomic_add_f32 v[190:191], v219, off
	s_mov_b64 exec, -1
	s_mov_b64 vcc, 64
	v_lshl_add_u64 v[190:191], v[190:191], 0, vcc
	v_mov_b32_dpp v220, v104 row_ror:8 row_mask:0xf bank_mask:0xf
	v_mov_b32_dpp v221, v105 row_ror:8 row_mask:0xf bank_mask:0xf
	v_mov_b32_dpp v222, v106 row_ror:8 row_mask:0xf bank_mask:0xf
	v_mov_b32_dpp v223, v107 row_ror:8 row_mask:0xf bank_mask:0xf
	v_cndmask_b32_e64 v104, v220, v108, s[34:35]
	v_cndmask_b32_e64 v105, v221, v109, s[34:35]
	v_cndmask_b32_e64 v106, v222, v110, s[34:35]
	v_cndmask_b32_e64 v107, v223, v111, s[34:35]
	v_cndmask_b32_e64 v108, v108, v220, s[34:35]
	v_cndmask_b32_e64 v109, v109, v221, s[34:35]
	v_cndmask_b32_e64 v110, v110, v222, s[34:35]
	v_cndmask_b32_e64 v111, v111, v223, s[34:35]
	v_mov_b32_dpp v220, v96 row_ror:8 row_mask:0xf bank_mask:0xf
	v_mov_b32_dpp v221, v97 row_ror:8 row_mask:0xf bank_mask:0xf
	v_mov_b32_dpp v222, v98 row_ror:8 row_mask:0xf bank_mask:0xf
	v_mov_b32_dpp v223, v99 row_ror:8 row_mask:0xf bank_mask:0xf
	v_cndmask_b32_e64 v96, v220, v100, s[34:35]
	v_cndmask_b32_e64 v97, v221, v101, s[34:35]
	v_cndmask_b32_e64 v98, v222, v102, s[34:35]
	v_cndmask_b32_e64 v99, v223, v103, s[34:35]
	v_cndmask_b32_e64 v100, v100, v220, s[34:35]
	v_cndmask_b32_e64 v101, v101, v221, s[34:35]
	v_cndmask_b32_e64 v102, v102, v222, s[34:35]
	v_cndmask_b32_e64 v103, v103, v223, s[34:35]
	s_waitcnt vmcnt(1)
	v_pk_fma_f32 v[106:107], v[106:107], 0.5, v[158:159] op_sel_hi:[1,0,1]
	v_pk_fma_f32 v[104:105], v[104:105], 0.5, v[156:157] op_sel_hi:[1,0,1]
	global_store_dwordx4 v[202:203], v[104:107], off
	v_pk_mul_f32 v[208:209], v[64:65], v[104:105]
	v_pk_mul_f32 v[210:211], v[66:67], v[106:107]
	v_mul_f32_e32 v219, v104, v104
	v_add_u32_e32 v208, 0x8000, v208
	v_add_u32_e32 v209, 0x8000, v209
	v_add_u32_e32 v210, 0x8000, v210
	v_add_u32_e32 v211, 0x8000, v211
	v_fmac_f32_e32 v219, v105, v105
	v_fmac_f32_e32 v219, v106, v106
	v_fmac_f32_e32 v219, v107, v107
	v_perm_b32 v206, v209, v208, s58
	v_perm_b32 v207, v211, v210, s58
	global_store_dwordx2 v[186:187], v[206:207], off
	v_pk_fma_f32 v[98:99], v[98:99], 0.5, v[162:163] op_sel_hi:[1,0,1]
	v_pk_fma_f32 v[96:97], v[96:97], 0.5, v[160:161] op_sel_hi:[1,0,1]
	global_store_dwordx4 v[202:203], v[96:99], off offset:512
	v_pk_mul_f32 v[212:213], v[72:73], v[96:97]
	v_pk_mul_f32 v[214:215], v[74:75], v[98:99]
	v_fmac_f32_e32 v219, v96, v96
	v_add_u32_e32 v212, 0x8000, v212
	v_add_u32_e32 v213, 0x8000, v213
	v_add_u32_e32 v214, 0x8000, v214
	v_add_u32_e32 v215, 0x8000, v215
	v_fmac_f32_e32 v219, v97, v97
	v_fmac_f32_e32 v219, v98, v98
	v_fmac_f32_e32 v219, v99, v99
	v_perm_b32 v216, v213, v212, s58
	v_perm_b32 v217, v215, v214, s58
	global_store_dwordx2 v[186:187], v[216:217], off offset:256
	v_pk_fma_f32 v[110:111], v[110:111], 0.5, v[178:179] op_sel_hi:[1,0,1]
	v_pk_fma_f32 v[108:109], v[108:109], 0.5, v[176:177] op_sel_hi:[1,0,1]
	global_store_dwordx4 v[204:205], v[108:111], off
	v_pk_mul_f32 v[208:209], v[80:81], v[108:109]
	v_pk_mul_f32 v[210:211], v[82:83], v[110:111]
	v_mul_f32_e32 v224, v108, v108
	v_add_u32_e32 v208, 0x8000, v208
	v_add_u32_e32 v209, 0x8000, v209
	v_add_u32_e32 v210, 0x8000, v210
	v_add_u32_e32 v211, 0x8000, v211
	v_fmac_f32_e32 v224, v109, v109
	v_fmac_f32_e32 v224, v110, v110
	v_fmac_f32_e32 v224, v111, v111
	v_perm_b32 v206, v209, v208, s58
	v_perm_b32 v207, v211, v210, s58
	global_store_dwordx2 v[188:189], v[206:207], off
	v_pk_fma_f32 v[102:103], v[102:103], 0.5, v[182:183] op_sel_hi:[1,0,1]
	v_pk_fma_f32 v[100:101], v[100:101], 0.5, v[180:181] op_sel_hi:[1,0,1]
	global_store_dwordx4 v[204:205], v[100:103], off offset:512
	v_pk_mul_f32 v[212:213], v[84:85], v[100:101]
	v_pk_mul_f32 v[214:215], v[86:87], v[102:103]
	v_fmac_f32_e32 v224, v100, v100
	v_add_u32_e32 v212, 0x8000, v212
	v_add_u32_e32 v213, 0x8000, v213
	v_add_u32_e32 v214, 0x8000, v214
	v_add_u32_e32 v215, 0x8000, v215
	v_fmac_f32_e32 v224, v101, v101
	v_fmac_f32_e32 v224, v102, v102
	v_fmac_f32_e32 v224, v103, v103
	v_perm_b32 v216, v213, v212, s58
	v_perm_b32 v217, v215, v214, s58
	global_store_dwordx2 v[188:189], v[216:217], off offset:256
	s_nop 1
	v_mov_b32_dpp v175, v219 row_ror:8 row_mask:0xf bank_mask:0xf
	v_mov_b32_dpp v218, v224 row_ror:8 row_mask:0xf bank_mask:0xf
	v_add_f32_e32 v219, v219, v175
	v_add_f32_e32 v224, v224, v218
	v_cndmask_b32_e64 v219, v224, v219, s[34:35]
	s_nop 0
	ds_bpermute_b32 v175, v225, v219
	global_load_dwordx4 v[156:159], v[164:165], off
	global_load_dwordx4 v[160:163], v[164:165], off offset:512
	global_load_dwordx4 v[176:179], v[184:185], off
	global_load_dwordx4 v[180:183], v[184:185], off offset:512
	s_mov_b64 vcc, 0xa0000
	v_lshl_add_u64 v[164:165], v[164:165], 0, vcc
	v_lshl_add_u64 v[184:185], v[184:185], 0, vcc
	s_mov_b64 vcc, 0x20000
	v_lshl_add_u64 v[202:203], v[202:203], 0, vcc
	v_lshl_add_u64 v[204:205], v[204:205], 0, vcc
	s_mov_b64 vcc, 0x10000
	v_lshl_add_u64 v[186:187], v[186:187], 0, vcc
	v_lshl_add_u64 v[188:189], v[188:189], 0, vcc
	s_waitcnt lgkmcnt(0)
	v_add_f32_e32 v219, v219, v175
	s_nop 0
	ds_bpermute_b32 v218, v226, v219
	s_waitcnt lgkmcnt(0)
;     __device__ __forceinline__ void operator()(const f32x4 (&acc)[2][2][4][2], const Unit& u, int wr, int wc, int fr, int fq) const {
;         const int row0 = u.pm * BM + wr * 64 + fr, col0 = u.pn * BM + wc * 32 + 4 * fq;
;         const float* rbase = (u.pm * BM < SEQ_P) ? resA : (resB - (size_t)SEQ_P * ldc);
;         f32x4 wv[2][2];
;         if (xn) {
; #pragma unroll
;             for (int bj = 0; bj < 2; ++bj)
; #pragma unroll
;                 for (int n = 0; n < 2; ++n) wv[bj][n] = *(const f32x4*)(wn + col0 + bj * HALF + n * 16);
;         }
; #pragma unroll
;         for (int ai = 0; ai < 2; ++ai)
; #pragma unroll
;             for (int m = 0; m < 4; ++m) {
;                 const int row = row0 + ai * HALF + m * 16;
;                 const size_t off = (size_t)row * ldc + col0;
;                 float q = 0.f;
; #pragma unroll
;                 for (int bj = 0; bj < 2; ++bj)
; #pragma unroll
;                     for (int n = 0; n < 2; ++n) {
;                         const f32x4 rv = *(const f32x4*)(rbase + off + bj * HALF + n * 16);
;                         const f32x4 v = rv + acc[ai][bj][m][n] * scale;
;                         if (out) *(f32x4*)(out + off + bj * HALF + n * 16) = v;
;                         if (xn) { q += (v.x * v.x + v.y * v.y) + (v.z * v.z + v.w * v.w); const f32x4 o = v * wv[bj][n];
;                             u32x2 p; p.x = pk2(o.x, o.y); p.y = pk2(o.z, o.w); *(u32x2*)(xn + off + bj * HALF + n * 16) = p; }
;                     }
;                 if (xn) { q += __shfl_xor(q, 16); q += __shfl_xor(q, 32); if (fq == 0) (void)__hip_atomic_fetch_add(ss + row, q, __ATOMIC_RELAXED, __HIP_MEMORY_SCOPE_AGENT); }
;             }
;     }
	v_add_f32_e32 v219, v219, v218
	s_mov_b64 exec, s[0:1]
	global_atomic_add_f32 v[190:191], v219, off
	s_mov_b64 exec, -1
	s_mov_b64 vcc, 64
	v_lshl_add_u64 v[190:191], v[190:191], 0, vcc
	v_mov_b32_dpp v220, v88 row_ror:8 row_mask:0xf bank_mask:0xf
	v_mov_b32_dpp v221, v89 row_ror:8 row_mask:0xf bank_mask:0xf
	v_mov_b32_dpp v222, v90 row_ror:8 row_mask:0xf bank_mask:0xf
	v_mov_b32_dpp v223, v91 row_ror:8 row_mask:0xf bank_mask:0xf
	v_cndmask_b32_e64 v88, v220, v92, s[34:35]
	v_cndmask_b32_e64 v89, v221, v93, s[34:35]
	v_cndmask_b32_e64 v90, v222, v94, s[34:35]
	v_cndmask_b32_e64 v91, v223, v95, s[34:35]
	v_cndmask_b32_e64 v92, v92, v220, s[34:35]
	v_cndmask_b32_e64 v93, v93, v221, s[34:35]
	v_cndmask_b32_e64 v94, v94, v222, s[34:35]
	v_cndmask_b32_e64 v95, v95, v223, s[34:35]
	v_mov_b32_dpp v220, v68 row_ror:8 row_mask:0xf bank_mask:0xf
	v_mov_b32_dpp v221, v69 row_ror:8 row_mask:0xf bank_mask:0xf
	v_mov_b32_dpp v222, v70 row_ror:8 row_mask:0xf bank_mask:0xf
	v_mov_b32_dpp v223, v71 row_ror:8 row_mask:0xf bank_mask:0xf
	v_cndmask_b32_e64 v68, v220, v76, s[34:35]
	v_cndmask_b32_e64 v69, v221, v77, s[34:35]
	v_cndmask_b32_e64 v70, v222, v78, s[34:35]
	v_cndmask_b32_e64 v71, v223, v79, s[34:35]
	v_cndmask_b32_e64 v76, v76, v220, s[34:35]
	v_cndmask_b32_e64 v77, v77, v221, s[34:35]
	v_cndmask_b32_e64 v78, v78, v222, s[34:35]
	v_cndmask_b32_e64 v79, v79, v223, s[34:35]
	s_waitcnt vmcnt(1)
	v_pk_fma_f32 v[90:91], v[90:91], 0.5, v[158:159] op_sel_hi:[1,0,1]
	v_pk_fma_f32 v[88:89], v[88:89], 0.5, v[156:157] op_sel_hi:[1,0,1]
	global_store_dwordx4 v[202:203], v[88:91], off
	v_pk_mul_f32 v[208:209], v[64:65], v[88:89]
	v_pk_mul_f32 v[210:211], v[66:67], v[90:91]
	v_mul_f32_e32 v219, v88, v88
	v_add_u32_e32 v208, 0x8000, v208
	v_add_u32_e32 v209, 0x8000, v209
	v_add_u32_e32 v210, 0x8000, v210
	v_add_u32_e32 v211, 0x8000, v211
	v_fmac_f32_e32 v219, v89, v89
	v_fmac_f32_e32 v219, v90, v90
	v_fmac_f32_e32 v219, v91, v91
	v_perm_b32 v206, v209, v208, s58
	v_perm_b32 v207, v211, v210, s58
	global_store_dwordx2 v[186:187], v[206:207], off
	v_pk_fma_f32 v[70:71], v[70:71], 0.5, v[162:163] op_sel_hi:[1,0,1]
	v_pk_fma_f32 v[68:69], v[68:69], 0.5, v[160:161] op_sel_hi:[1,0,1]
	global_store_dwordx4 v[202:203], v[68:71], off offset:512
	v_pk_mul_f32 v[212:213], v[72:73], v[68:69]
	v_pk_mul_f32 v[214:215], v[74:75], v[70:71]
	v_fmac_f32_e32 v219, v68, v68
	v_add_u32_e32 v212, 0x8000, v212
	v_add_u32_e32 v213, 0x8000, v213
	v_add_u32_e32 v214, 0x8000, v214
	v_add_u32_e32 v215, 0x8000, v215
	v_fmac_f32_e32 v219, v69, v69
	v_fmac_f32_e32 v219, v70, v70
	v_fmac_f32_e32 v219, v71, v71
	v_perm_b32 v216, v213, v212, s58
	v_perm_b32 v217, v215, v214, s58
	global_store_dwordx2 v[186:187], v[216:217], off offset:256
	v_pk_fma_f32 v[94:95], v[94:95], 0.5, v[178:179] op_sel_hi:[1,0,1]
	v_pk_fma_f32 v[92:93], v[92:93], 0.5, v[176:177] op_sel_hi:[1,0,1]
	global_store_dwordx4 v[204:205], v[92:95], off
	v_pk_mul_f32 v[208:209], v[80:81], v[92:93]
	v_pk_mul_f32 v[210:211], v[82:83], v[94:95]
	v_mul_f32_e32 v224, v92, v92
	v_add_u32_e32 v208, 0x8000, v208
	v_add_u32_e32 v209, 0x8000, v209
	v_add_u32_e32 v210, 0x8000, v210
	v_add_u32_e32 v211, 0x8000, v211
	v_fmac_f32_e32 v224, v93, v93
	v_fmac_f32_e32 v224, v94, v94
	v_fmac_f32_e32 v224, v95, v95
	v_perm_b32 v206, v209, v208, s58
	v_perm_b32 v207, v211, v210, s58
	global_store_dwordx2 v[188:189], v[206:207], off
	v_pk_fma_f32 v[78:79], v[78:79], 0.5, v[182:183] op_sel_hi:[1,0,1]
	v_pk_fma_f32 v[76:77], v[76:77], 0.5, v[180:181] op_sel_hi:[1,0,1]
	global_store_dwordx4 v[204:205], v[76:79], off offset:512
	v_pk_mul_f32 v[212:213], v[84:85], v[76:77]
	v_pk_mul_f32 v[214:215], v[86:87], v[78:79]
	v_fmac_f32_e32 v224, v76, v76
	v_add_u32_e32 v212, 0x8000, v212
	v_add_u32_e32 v213, 0x8000, v213
	v_add_u32_e32 v214, 0x8000, v214
	v_add_u32_e32 v215, 0x8000, v215
	v_fmac_f32_e32 v224, v77, v77
	v_fmac_f32_e32 v224, v78, v78
	v_fmac_f32_e32 v224, v79, v79
	v_perm_b32 v216, v213, v212, s58
	v_perm_b32 v217, v215, v214, s58
	global_store_dwordx2 v[188:189], v[216:217], off offset:256
	s_nop 1
	v_mov_b32_dpp v175, v219 row_ror:8 row_mask:0xf bank_mask:0xf
	v_mov_b32_dpp v218, v224 row_ror:8 row_mask:0xf bank_mask:0xf
	v_add_f32_e32 v219, v219, v175
	v_add_f32_e32 v224, v224, v218
	v_cndmask_b32_e64 v219, v224, v219, s[34:35]
	s_nop 0
	ds_bpermute_b32 v175, v225, v219
	global_load_dwordx4 v[156:159], v[164:165], off
	global_load_dwordx4 v[160:163], v[164:165], off offset:512
	global_load_dwordx4 v[176:179], v[184:185], off
	global_load_dwordx4 v[180:183], v[184:185], off offset:512
	s_mov_b64 vcc, 0x20000
	v_lshl_add_u64 v[164:165], v[164:165], 0, vcc
	v_lshl_add_u64 v[184:185], v[184:185], 0, vcc
	s_mov_b64 vcc, 0xa0000
	v_lshl_add_u64 v[202:203], v[202:203], 0, vcc
	v_lshl_add_u64 v[204:205], v[204:205], 0, vcc
	s_mov_b64 vcc, 0x50000
	v_lshl_add_u64 v[186:187], v[186:187], 0, vcc
	v_lshl_add_u64 v[188:189], v[188:189], 0, vcc
	s_waitcnt lgkmcnt(0)
	v_add_f32_e32 v219, v219, v175
	s_nop 0
	ds_bpermute_b32 v218, v226, v219
	s_waitcnt lgkmcnt(0)
;     __device__ __forceinline__ void operator()(const f32x4 (&acc)[2][2][4][2], const Unit& u, int wr, int wc, int fr, int fq) const {
;         const int row0 = u.pm * BM + wr * 64 + fr, col0 = u.pn * BM + wc * 32 + 4 * fq;
;         const float* rbase = (u.pm * BM < SEQ_P) ? resA : (resB - (size_t)SEQ_P * ldc);
;         f32x4 wv[2][2];
;         if (xn) {
; #pragma unroll
;             for (int bj = 0; bj < 2; ++bj)
; #pragma unroll
;                 for (int n = 0; n < 2; ++n) wv[bj][n] = *(const f32x4*)(wn + col0 + bj * HALF + n * 16);
;         }
; #pragma unroll
;         for (int ai = 0; ai < 2; ++ai)
; #pragma unroll
;             for (int m = 0; m < 4; ++m) {
;                 const int row = row0 + ai * HALF + m * 16;
;                 const size_t off = (size_t)row * ldc + col0;
;                 float q = 0.f;
; #pragma unroll
;                 for (int bj = 0; bj < 2; ++bj)
; #pragma unroll
;                     for (int n = 0; n < 2; ++n) {
;                         const f32x4 rv = *(const f32x4*)(rbase + off + bj * HALF + n * 16);
;                         const f32x4 v = rv + acc[ai][bj][m][n] * scale;
;                         if (out) *(f32x4*)(out + off + bj * HALF + n * 16) = v;
;                         if (xn) { q += (v.x * v.x + v.y * v.y) + (v.z * v.z + v.w * v.w); const f32x4 o = v * wv[bj][n];
;                             u32x2 p; p.x = pk2(o.x, o.y); p.y = pk2(o.z, o.w); *(u32x2*)(xn + off + bj * HALF + n * 16) = p; }
;                     }
;                 if (xn) { q += __shfl_xor(q, 16); q += __shfl_xor(q, 32); if (fq == 0) (void)__hip_atomic_fetch_add(ss + row, q, __ATOMIC_RELAXED, __HIP_MEMORY_SCOPE_AGENT); }
;             }
;     }
	v_add_f32_e32 v219, v219, v218
	s_mov_b64 exec, s[0:1]
	global_atomic_add_f32 v[190:191], v219, off
	s_mov_b64 exec, -1
	s_mov_b64 vcc, 320
	v_lshl_add_u64 v[190:191], v[190:191], 0, vcc
	v_mov_b32_dpp v220, v56 row_ror:8 row_mask:0xf bank_mask:0xf
	v_mov_b32_dpp v221, v57 row_ror:8 row_mask:0xf bank_mask:0xf
	v_mov_b32_dpp v222, v58 row_ror:8 row_mask:0xf bank_mask:0xf
	v_mov_b32_dpp v223, v59 row_ror:8 row_mask:0xf bank_mask:0xf
	v_cndmask_b32_e64 v56, v220, v60, s[34:35]
	v_cndmask_b32_e64 v57, v221, v61, s[34:35]
	v_cndmask_b32_e64 v58, v222, v62, s[34:35]
	v_cndmask_b32_e64 v59, v223, v63, s[34:35]
	v_cndmask_b32_e64 v60, v60, v220, s[34:35]
	v_cndmask_b32_e64 v61, v61, v221, s[34:35]
	v_cndmask_b32_e64 v62, v62, v222, s[34:35]
	v_cndmask_b32_e64 v63, v63, v223, s[34:35]
	v_mov_b32_dpp v220, v48 row_ror:8 row_mask:0xf bank_mask:0xf
	v_mov_b32_dpp v221, v49 row_ror:8 row_mask:0xf bank_mask:0xf
	v_mov_b32_dpp v222, v50 row_ror:8 row_mask:0xf bank_mask:0xf
	v_mov_b32_dpp v223, v51 row_ror:8 row_mask:0xf bank_mask:0xf
	v_cndmask_b32_e64 v48, v220, v52, s[34:35]
	v_cndmask_b32_e64 v49, v221, v53, s[34:35]
	v_cndmask_b32_e64 v50, v222, v54, s[34:35]
	v_cndmask_b32_e64 v51, v223, v55, s[34:35]
	v_cndmask_b32_e64 v52, v52, v220, s[34:35]
	v_cndmask_b32_e64 v53, v53, v221, s[34:35]
	v_cndmask_b32_e64 v54, v54, v222, s[34:35]
	v_cndmask_b32_e64 v55, v55, v223, s[34:35]
	s_waitcnt vmcnt(1)
	v_pk_fma_f32 v[58:59], v[58:59], 0.5, v[158:159] op_sel_hi:[1,0,1]
	v_pk_fma_f32 v[56:57], v[56:57], 0.5, v[156:157] op_sel_hi:[1,0,1]
	global_store_dwordx4 v[202:203], v[56:59], off
	v_pk_mul_f32 v[208:209], v[64:65], v[56:57]
	v_pk_mul_f32 v[210:211], v[66:67], v[58:59]
	v_mul_f32_e32 v219, v56, v56
	v_add_u32_e32 v208, 0x8000, v208
	v_add_u32_e32 v209, 0x8000, v209
	v_add_u32_e32 v210, 0x8000, v210
	v_add_u32_e32 v211, 0x8000, v211
	v_fmac_f32_e32 v219, v57, v57
	v_fmac_f32_e32 v219, v58, v58
	v_fmac_f32_e32 v219, v59, v59
	v_perm_b32 v206, v209, v208, s58
	v_perm_b32 v207, v211, v210, s58
	global_store_dwordx2 v[186:187], v[206:207], off
	v_pk_fma_f32 v[50:51], v[50:51], 0.5, v[162:163] op_sel_hi:[1,0,1]
	v_pk_fma_f32 v[48:49], v[48:49], 0.5, v[160:161] op_sel_hi:[1,0,1]
	global_store_dwordx4 v[202:203], v[48:51], off offset:512
	v_pk_mul_f32 v[212:213], v[72:73], v[48:49]
	v_pk_mul_f32 v[214:215], v[74:75], v[50:51]
	v_fmac_f32_e32 v219, v48, v48
	v_add_u32_e32 v212, 0x8000, v212
	v_add_u32_e32 v213, 0x8000, v213
	v_add_u32_e32 v214, 0x8000, v214
	v_add_u32_e32 v215, 0x8000, v215
	v_fmac_f32_e32 v219, v49, v49
	v_fmac_f32_e32 v219, v50, v50
	v_fmac_f32_e32 v219, v51, v51
	v_perm_b32 v216, v213, v212, s58
	v_perm_b32 v217, v215, v214, s58
	global_store_dwordx2 v[186:187], v[216:217], off offset:256
	v_pk_fma_f32 v[62:63], v[62:63], 0.5, v[178:179] op_sel_hi:[1,0,1]
	v_pk_fma_f32 v[60:61], v[60:61], 0.5, v[176:177] op_sel_hi:[1,0,1]
	global_store_dwordx4 v[204:205], v[60:63], off
	v_pk_mul_f32 v[208:209], v[80:81], v[60:61]
	v_pk_mul_f32 v[210:211], v[82:83], v[62:63]
	v_mul_f32_e32 v224, v60, v60
	v_add_u32_e32 v208, 0x8000, v208
	v_add_u32_e32 v209, 0x8000, v209
	v_add_u32_e32 v210, 0x8000, v210
	v_add_u32_e32 v211, 0x8000, v211
	v_fmac_f32_e32 v224, v61, v61
	v_fmac_f32_e32 v224, v62, v62
	v_fmac_f32_e32 v224, v63, v63
	v_perm_b32 v206, v209, v208, s58
	v_perm_b32 v207, v211, v210, s58
	global_store_dwordx2 v[188:189], v[206:207], off
	v_pk_fma_f32 v[54:55], v[54:55], 0.5, v[182:183] op_sel_hi:[1,0,1]
	v_pk_fma_f32 v[52:53], v[52:53], 0.5, v[180:181] op_sel_hi:[1,0,1]
	global_store_dwordx4 v[204:205], v[52:55], off offset:512
	v_pk_mul_f32 v[212:213], v[84:85], v[52:53]
	v_pk_mul_f32 v[214:215], v[86:87], v[54:55]
	v_fmac_f32_e32 v224, v52, v52
	v_add_u32_e32 v212, 0x8000, v212
	v_add_u32_e32 v213, 0x8000, v213
	v_add_u32_e32 v214, 0x8000, v214
	v_add_u32_e32 v215, 0x8000, v215
	v_fmac_f32_e32 v224, v53, v53
	v_fmac_f32_e32 v224, v54, v54
	v_fmac_f32_e32 v224, v55, v55
	v_perm_b32 v216, v213, v212, s58
	v_perm_b32 v217, v215, v214, s58
	global_store_dwordx2 v[188:189], v[216:217], off offset:256
	s_nop 1
	v_mov_b32_dpp v175, v219 row_ror:8 row_mask:0xf bank_mask:0xf
	v_mov_b32_dpp v218, v224 row_ror:8 row_mask:0xf bank_mask:0xf
	v_add_f32_e32 v219, v219, v175
	v_add_f32_e32 v224, v224, v218
	v_cndmask_b32_e64 v219, v224, v219, s[34:35]
	s_nop 0
	ds_bpermute_b32 v175, v225, v219
	global_load_dwordx4 v[156:159], v[164:165], off
	global_load_dwordx4 v[160:163], v[164:165], off offset:512
	global_load_dwordx4 v[176:179], v[184:185], off
	global_load_dwordx4 v[180:183], v[184:185], off offset:512
	s_mov_b64 vcc, 0x20000
	v_lshl_add_u64 v[164:165], v[164:165], 0, vcc
	v_lshl_add_u64 v[184:185], v[184:185], 0, vcc
	s_mov_b64 vcc, 0x20000
	v_lshl_add_u64 v[202:203], v[202:203], 0, vcc
	v_lshl_add_u64 v[204:205], v[204:205], 0, vcc
	s_mov_b64 vcc, 0x10000
	v_lshl_add_u64 v[186:187], v[186:187], 0, vcc
	v_lshl_add_u64 v[188:189], v[188:189], 0, vcc
	s_waitcnt lgkmcnt(0)
	v_add_f32_e32 v219, v219, v175
	s_nop 0
	ds_bpermute_b32 v218, v226, v219
	s_waitcnt lgkmcnt(0)
;     __device__ __forceinline__ void operator()(const f32x4 (&acc)[2][2][4][2], const Unit& u, int wr, int wc, int fr, int fq) const {
;         const int row0 = u.pm * BM + wr * 64 + fr, col0 = u.pn * BM + wc * 32 + 4 * fq;
;         const float* rbase = (u.pm * BM < SEQ_P) ? resA : (resB - (size_t)SEQ_P * ldc);
;         f32x4 wv[2][2];
;         if (xn) {
; #pragma unroll
;             for (int bj = 0; bj < 2; ++bj)
; #pragma unroll
;                 for (int n = 0; n < 2; ++n) wv[bj][n] = *(const f32x4*)(wn + col0 + bj * HALF + n * 16);
;         }
; #pragma unroll
;         for (int ai = 0; ai < 2; ++ai)
; #pragma unroll
;             for (int m = 0; m < 4; ++m) {
;                 const int row = row0 + ai * HALF + m * 16;
;                 const size_t off = (size_t)row * ldc + col0;
;                 float q = 0.f;
; #pragma unroll
;                 for (int bj = 0; bj < 2; ++bj)
; #pragma unroll
;                     for (int n = 0; n < 2; ++n) {
;                         const f32x4 rv = *(const f32x4*)(rbase + off + bj * HALF + n * 16);
;                         const f32x4 v = rv + acc[ai][bj][m][n] * scale;
;                         if (out) *(f32x4*)(out + off + bj * HALF + n * 16) = v;
;                         if (xn) { q += (v.x * v.x + v.y * v.y) + (v.z * v.z + v.w * v.w); const f32x4 o = v * wv[bj][n];
;                             u32x2 p; p.x = pk2(o.x, o.y); p.y = pk2(o.z, o.w); *(u32x2*)(xn + off + bj * HALF + n * 16) = p; }
;                     }
;                 if (xn) { q += __shfl_xor(q, 16); q += __shfl_xor(q, 32); if (fq == 0) (void)__hip_atomic_fetch_add(ss + row, q, __ATOMIC_RELAXED, __HIP_MEMORY_SCOPE_AGENT); }
;             }
;     }
	v_add_f32_e32 v219, v219, v218
	s_mov_b64 exec, s[0:1]
	global_atomic_add_f32 v[190:191], v219, off
	s_mov_b64 exec, -1
	s_mov_b64 vcc, 64
	v_lshl_add_u64 v[190:191], v[190:191], 0, vcc
	v_mov_b32_dpp v220, v40 row_ror:8 row_mask:0xf bank_mask:0xf
	v_mov_b32_dpp v221, v41 row_ror:8 row_mask:0xf bank_mask:0xf
	v_mov_b32_dpp v222, v42 row_ror:8 row_mask:0xf bank_mask:0xf
	v_mov_b32_dpp v223, v43 row_ror:8 row_mask:0xf bank_mask:0xf
	v_cndmask_b32_e64 v40, v220, v44, s[34:35]
	v_cndmask_b32_e64 v41, v221, v45, s[34:35]
	v_cndmask_b32_e64 v42, v222, v46, s[34:35]
	v_cndmask_b32_e64 v43, v223, v47, s[34:35]
	v_cndmask_b32_e64 v44, v44, v220, s[34:35]
	v_cndmask_b32_e64 v45, v45, v221, s[34:35]
	v_cndmask_b32_e64 v46, v46, v222, s[34:35]
	v_cndmask_b32_e64 v47, v47, v223, s[34:35]
	v_mov_b32_dpp v220, v32 row_ror:8 row_mask:0xf bank_mask:0xf
	v_mov_b32_dpp v221, v33 row_ror:8 row_mask:0xf bank_mask:0xf
	v_mov_b32_dpp v222, v34 row_ror:8 row_mask:0xf bank_mask:0xf
	v_mov_b32_dpp v223, v35 row_ror:8 row_mask:0xf bank_mask:0xf
	v_cndmask_b32_e64 v32, v220, v36, s[34:35]
	v_cndmask_b32_e64 v33, v221, v37, s[34:35]
	v_cndmask_b32_e64 v34, v222, v38, s[34:35]
	v_cndmask_b32_e64 v35, v223, v39, s[34:35]
	v_cndmask_b32_e64 v36, v36, v220, s[34:35]
	v_cndmask_b32_e64 v37, v37, v221, s[34:35]
	v_cndmask_b32_e64 v38, v38, v222, s[34:35]
	v_cndmask_b32_e64 v39, v39, v223, s[34:35]
	s_waitcnt vmcnt(1)
	v_pk_fma_f32 v[42:43], v[42:43], 0.5, v[158:159] op_sel_hi:[1,0,1]
	v_pk_fma_f32 v[40:41], v[40:41], 0.5, v[156:157] op_sel_hi:[1,0,1]
	global_store_dwordx4 v[202:203], v[40:43], off
	v_pk_mul_f32 v[208:209], v[64:65], v[40:41]
	v_pk_mul_f32 v[210:211], v[66:67], v[42:43]
	v_mul_f32_e32 v219, v40, v40
	v_add_u32_e32 v208, 0x8000, v208
	v_add_u32_e32 v209, 0x8000, v209
	v_add_u32_e32 v210, 0x8000, v210
	v_add_u32_e32 v211, 0x8000, v211
	v_fmac_f32_e32 v219, v41, v41
	v_fmac_f32_e32 v219, v42, v42
	v_fmac_f32_e32 v219, v43, v43
	v_perm_b32 v206, v209, v208, s58
	v_perm_b32 v207, v211, v210, s58
	global_store_dwordx2 v[186:187], v[206:207], off
	v_pk_fma_f32 v[34:35], v[34:35], 0.5, v[162:163] op_sel_hi:[1,0,1]
	v_pk_fma_f32 v[32:33], v[32:33], 0.5, v[160:161] op_sel_hi:[1,0,1]
	global_store_dwordx4 v[202:203], v[32:35], off offset:512
	v_pk_mul_f32 v[212:213], v[72:73], v[32:33]
	v_pk_mul_f32 v[214:215], v[74:75], v[34:35]
	v_fmac_f32_e32 v219, v32, v32
	v_add_u32_e32 v212, 0x8000, v212
	v_add_u32_e32 v213, 0x8000, v213
	v_add_u32_e32 v214, 0x8000, v214
	v_add_u32_e32 v215, 0x8000, v215
	v_fmac_f32_e32 v219, v33, v33
	v_fmac_f32_e32 v219, v34, v34
	v_fmac_f32_e32 v219, v35, v35
	v_perm_b32 v216, v213, v212, s58
	v_perm_b32 v217, v215, v214, s58
	global_store_dwordx2 v[186:187], v[216:217], off offset:256
	v_pk_fma_f32 v[46:47], v[46:47], 0.5, v[178:179] op_sel_hi:[1,0,1]
	v_pk_fma_f32 v[44:45], v[44:45], 0.5, v[176:177] op_sel_hi:[1,0,1]
	global_store_dwordx4 v[204:205], v[44:47], off
	v_pk_mul_f32 v[208:209], v[80:81], v[44:45]
	v_pk_mul_f32 v[210:211], v[82:83], v[46:47]
	v_mul_f32_e32 v224, v44, v44
	v_add_u32_e32 v208, 0x8000, v208
	v_add_u32_e32 v209, 0x8000, v209
	v_add_u32_e32 v210, 0x8000, v210
	v_add_u32_e32 v211, 0x8000, v211
	v_fmac_f32_e32 v224, v45, v45
	v_fmac_f32_e32 v224, v46, v46
	v_fmac_f32_e32 v224, v47, v47
	v_perm_b32 v206, v209, v208, s58
	v_perm_b32 v207, v211, v210, s58
	global_store_dwordx2 v[188:189], v[206:207], off
	v_pk_fma_f32 v[38:39], v[38:39], 0.5, v[182:183] op_sel_hi:[1,0,1]
	v_pk_fma_f32 v[36:37], v[36:37], 0.5, v[180:181] op_sel_hi:[1,0,1]
	global_store_dwordx4 v[204:205], v[36:39], off offset:512
	v_pk_mul_f32 v[212:213], v[84:85], v[36:37]
	v_pk_mul_f32 v[214:215], v[86:87], v[38:39]
	v_fmac_f32_e32 v224, v36, v36
	v_add_u32_e32 v212, 0x8000, v212
	v_add_u32_e32 v213, 0x8000, v213
	v_add_u32_e32 v214, 0x8000, v214
	v_add_u32_e32 v215, 0x8000, v215
	v_fmac_f32_e32 v224, v37, v37
	v_fmac_f32_e32 v224, v38, v38
	v_fmac_f32_e32 v224, v39, v39
	v_perm_b32 v216, v213, v212, s58
	v_perm_b32 v217, v215, v214, s58
	global_store_dwordx2 v[188:189], v[216:217], off offset:256
	s_nop 1
	v_mov_b32_dpp v175, v219 row_ror:8 row_mask:0xf bank_mask:0xf
	v_mov_b32_dpp v218, v224 row_ror:8 row_mask:0xf bank_mask:0xf
	v_add_f32_e32 v219, v219, v175
	v_add_f32_e32 v224, v224, v218
	v_cndmask_b32_e64 v219, v224, v219, s[34:35]
	s_nop 0
	ds_bpermute_b32 v175, v225, v219
	global_load_dwordx4 v[156:159], v[164:165], off
	global_load_dwordx4 v[160:163], v[164:165], off offset:512
	global_load_dwordx4 v[176:179], v[184:185], off
	global_load_dwordx4 v[180:183], v[184:185], off offset:512
	s_mov_b64 vcc, 0x20000
	v_lshl_add_u64 v[164:165], v[164:165], 0, vcc
	v_lshl_add_u64 v[184:185], v[184:185], 0, vcc
	s_mov_b64 vcc, 0x20000
	v_lshl_add_u64 v[202:203], v[202:203], 0, vcc
	v_lshl_add_u64 v[204:205], v[204:205], 0, vcc
	s_mov_b64 vcc, 0x10000
	v_lshl_add_u64 v[186:187], v[186:187], 0, vcc
	v_lshl_add_u64 v[188:189], v[188:189], 0, vcc
	s_waitcnt lgkmcnt(0)
	v_add_f32_e32 v219, v219, v175
	s_nop 0
	ds_bpermute_b32 v218, v226, v219
	s_waitcnt lgkmcnt(0)
;     __device__ __forceinline__ void operator()(const f32x4 (&acc)[2][2][4][2], const Unit& u, int wr, int wc, int fr, int fq) const {
;         const int row0 = u.pm * BM + wr * 64 + fr, col0 = u.pn * BM + wc * 32 + 4 * fq;
;         const float* rbase = (u.pm * BM < SEQ_P) ? resA : (resB - (size_t)SEQ_P * ldc);
;         f32x4 wv[2][2];
;         if (xn) {
; #pragma unroll
;             for (int bj = 0; bj < 2; ++bj)
; #pragma unroll
;                 for (int n = 0; n < 2; ++n) wv[bj][n] = *(const f32x4*)(wn + col0 + bj * HALF + n * 16);
;         }
; #pragma unroll
;         for (int ai = 0; ai < 2; ++ai)
; #pragma unroll
;             for (int m = 0; m < 4; ++m) {
;                 const int row = row0 + ai * HALF + m * 16;
;                 const size_t off = (size_t)row * ldc + col0;
;                 float q = 0.f;
; #pragma unroll
;                 for (int bj = 0; bj < 2; ++bj)
; #pragma unroll
;                     for (int n = 0; n < 2; ++n) {
;                         const f32x4 rv = *(const f32x4*)(rbase + off + bj * HALF + n * 16);
;                         const f32x4 v = rv + acc[ai][bj][m][n] * scale;
;                         if (out) *(f32x4*)(out + off + bj * HALF + n * 16) = v;
;                         if (xn) { q += (v.x * v.x + v.y * v.y) + (v.z * v.z + v.w * v.w); const f32x4 o = v * wv[bj][n];
;                             u32x2 p; p.x = pk2(o.x, o.y); p.y = pk2(o.z, o.w); *(u32x2*)(xn + off + bj * HALF + n * 16) = p; }
;                     }
;                 if (xn) { q += __shfl_xor(q, 16); q += __shfl_xor(q, 32); if (fq == 0) (void)__hip_atomic_fetch_add(ss + row, q, __ATOMIC_RELAXED, __HIP_MEMORY_SCOPE_AGENT); }
;             }
;     }
	v_add_f32_e32 v219, v219, v218
	s_mov_b64 exec, s[0:1]
	global_atomic_add_f32 v[190:191], v219, off
	s_mov_b64 exec, -1
	s_mov_b64 vcc, 64
	v_lshl_add_u64 v[190:191], v[190:191], 0, vcc
	v_mov_b32_dpp v220, v24 row_ror:8 row_mask:0xf bank_mask:0xf
	v_mov_b32_dpp v221, v25 row_ror:8 row_mask:0xf bank_mask:0xf
	v_mov_b32_dpp v222, v26 row_ror:8 row_mask:0xf bank_mask:0xf
	v_mov_b32_dpp v223, v27 row_ror:8 row_mask:0xf bank_mask:0xf
	v_cndmask_b32_e64 v24, v220, v28, s[34:35]
	v_cndmask_b32_e64 v25, v221, v29, s[34:35]
	v_cndmask_b32_e64 v26, v222, v30, s[34:35]
	v_cndmask_b32_e64 v27, v223, v31, s[34:35]
	v_cndmask_b32_e64 v28, v28, v220, s[34:35]
	v_cndmask_b32_e64 v29, v29, v221, s[34:35]
	v_cndmask_b32_e64 v30, v30, v222, s[34:35]
	v_cndmask_b32_e64 v31, v31, v223, s[34:35]
	v_mov_b32_dpp v220, v16 row_ror:8 row_mask:0xf bank_mask:0xf
	v_mov_b32_dpp v221, v17 row_ror:8 row_mask:0xf bank_mask:0xf
	v_mov_b32_dpp v222, v18 row_ror:8 row_mask:0xf bank_mask:0xf
	v_mov_b32_dpp v223, v19 row_ror:8 row_mask:0xf bank_mask:0xf
	v_cndmask_b32_e64 v16, v220, v20, s[34:35]
	v_cndmask_b32_e64 v17, v221, v21, s[34:35]
	v_cndmask_b32_e64 v18, v222, v22, s[34:35]
	v_cndmask_b32_e64 v19, v223, v23, s[34:35]
	v_cndmask_b32_e64 v20, v20, v220, s[34:35]
	v_cndmask_b32_e64 v21, v21, v221, s[34:35]
	v_cndmask_b32_e64 v22, v22, v222, s[34:35]
	v_cndmask_b32_e64 v23, v23, v223, s[34:35]
	s_waitcnt vmcnt(1)
	v_pk_fma_f32 v[26:27], v[26:27], 0.5, v[158:159] op_sel_hi:[1,0,1]
	v_pk_fma_f32 v[24:25], v[24:25], 0.5, v[156:157] op_sel_hi:[1,0,1]
	global_store_dwordx4 v[202:203], v[24:27], off
	v_pk_mul_f32 v[208:209], v[64:65], v[24:25]
	v_pk_mul_f32 v[210:211], v[66:67], v[26:27]
	v_mul_f32_e32 v219, v24, v24
	v_add_u32_e32 v208, 0x8000, v208
	v_add_u32_e32 v209, 0x8000, v209
	v_add_u32_e32 v210, 0x8000, v210
	v_add_u32_e32 v211, 0x8000, v211
	v_fmac_f32_e32 v219, v25, v25
	v_fmac_f32_e32 v219, v26, v26
	v_fmac_f32_e32 v219, v27, v27
	v_perm_b32 v206, v209, v208, s58
	v_perm_b32 v207, v211, v210, s58
	global_store_dwordx2 v[186:187], v[206:207], off
	v_pk_fma_f32 v[18:19], v[18:19], 0.5, v[162:163] op_sel_hi:[1,0,1]
	v_pk_fma_f32 v[16:17], v[16:17], 0.5, v[160:161] op_sel_hi:[1,0,1]
	global_store_dwordx4 v[202:203], v[16:19], off offset:512
	v_pk_mul_f32 v[212:213], v[72:73], v[16:17]
	v_pk_mul_f32 v[214:215], v[74:75], v[18:19]
	v_fmac_f32_e32 v219, v16, v16
	v_add_u32_e32 v212, 0x8000, v212
	v_add_u32_e32 v213, 0x8000, v213
	v_add_u32_e32 v214, 0x8000, v214
	v_add_u32_e32 v215, 0x8000, v215
	v_fmac_f32_e32 v219, v17, v17
	v_fmac_f32_e32 v219, v18, v18
	v_fmac_f32_e32 v219, v19, v19
	v_perm_b32 v216, v213, v212, s58
	v_perm_b32 v217, v215, v214, s58
	global_store_dwordx2 v[186:187], v[216:217], off offset:256
	v_pk_fma_f32 v[30:31], v[30:31], 0.5, v[178:179] op_sel_hi:[1,0,1]
	v_pk_fma_f32 v[28:29], v[28:29], 0.5, v[176:177] op_sel_hi:[1,0,1]
	global_store_dwordx4 v[204:205], v[28:31], off
	v_pk_mul_f32 v[208:209], v[80:81], v[28:29]
	v_pk_mul_f32 v[210:211], v[82:83], v[30:31]
	v_mul_f32_e32 v224, v28, v28
	v_add_u32_e32 v208, 0x8000, v208
	v_add_u32_e32 v209, 0x8000, v209
	v_add_u32_e32 v210, 0x8000, v210
	v_add_u32_e32 v211, 0x8000, v211
	v_fmac_f32_e32 v224, v29, v29
	v_fmac_f32_e32 v224, v30, v30
	v_fmac_f32_e32 v224, v31, v31
	v_perm_b32 v206, v209, v208, s58
	v_perm_b32 v207, v211, v210, s58
	global_store_dwordx2 v[188:189], v[206:207], off
	v_pk_fma_f32 v[22:23], v[22:23], 0.5, v[182:183] op_sel_hi:[1,0,1]
	v_pk_fma_f32 v[20:21], v[20:21], 0.5, v[180:181] op_sel_hi:[1,0,1]
	global_store_dwordx4 v[204:205], v[20:23], off offset:512
	v_pk_mul_f32 v[212:213], v[84:85], v[20:21]
	v_pk_mul_f32 v[214:215], v[86:87], v[22:23]
	v_fmac_f32_e32 v224, v20, v20
	v_add_u32_e32 v212, 0x8000, v212
	v_add_u32_e32 v213, 0x8000, v213
	v_add_u32_e32 v214, 0x8000, v214
	v_add_u32_e32 v215, 0x8000, v215
	v_fmac_f32_e32 v224, v21, v21
	v_fmac_f32_e32 v224, v22, v22
	v_fmac_f32_e32 v224, v23, v23
	v_perm_b32 v216, v213, v212, s58
	v_perm_b32 v217, v215, v214, s58
	global_store_dwordx2 v[188:189], v[216:217], off offset:256
	s_nop 1
	v_mov_b32_dpp v175, v219 row_ror:8 row_mask:0xf bank_mask:0xf
	v_mov_b32_dpp v218, v224 row_ror:8 row_mask:0xf bank_mask:0xf
	v_add_f32_e32 v219, v219, v175
	v_add_f32_e32 v224, v224, v218
	v_cndmask_b32_e64 v219, v224, v219, s[34:35]
	s_nop 0
	ds_bpermute_b32 v175, v225, v219
	global_load_dwordx4 v[156:159], v[164:165], off
	global_load_dwordx4 v[160:163], v[164:165], off offset:512
	global_load_dwordx4 v[176:179], v[184:185], off
	global_load_dwordx4 v[180:183], v[184:185], off offset:512
	s_mov_b64 vcc, 0x20000
	v_lshl_add_u64 v[202:203], v[202:203], 0, vcc
	v_lshl_add_u64 v[204:205], v[204:205], 0, vcc
	s_mov_b64 vcc, 0x10000
	v_lshl_add_u64 v[186:187], v[186:187], 0, vcc
	v_lshl_add_u64 v[188:189], v[188:189], 0, vcc
	s_waitcnt lgkmcnt(0)
;     __device__ __forceinline__ void operator()(const f32x4 (&acc)[2][2][4][2], const Unit& u, int wr, int wc, int fr, int fq) const {
;         const int row0 = u.pm * BM + wr * 64 + fr, col0 = u.pn * BM + wc * 32 + 4 * fq;
;         const float* rbase = (u.pm * BM < SEQ_P) ? resA : (resB - (size_t)SEQ_P * ldc);
;         f32x4 wv[2][2];
;         if (xn) {
; #pragma unroll
;             for (int bj = 0; bj < 2; ++bj)
; #pragma unroll
;                 for (int n = 0; n < 2; ++n) wv[bj][n] = *(const f32x4*)(wn + col0 + bj * HALF + n * 16);
;         }
; #pragma unroll
;         for (int ai = 0; ai < 2; ++ai)
; #pragma unroll
;             for (int m = 0; m < 4; ++m) {
;                 const int row = row0 + ai * HALF + m * 16;
;                 const size_t off = (size_t)row * ldc + col0;
;                 float q = 0.f;
; #pragma unroll
;                 for (int bj = 0; bj < 2; ++bj)
; #pragma unroll
;                     for (int n = 0; n < 2; ++n) {
;                         const f32x4 rv = *(const f32x4*)(rbase + off + bj * HALF + n * 16);
;                         const f32x4 v = rv + acc[ai][bj][m][n] * scale;
;                         if (out) *(f32x4*)(out + off + bj * HALF + n * 16) = v;
;                         if (xn) { q += (v.x * v.x + v.y * v.y) + (v.z * v.z + v.w * v.w); const f32x4 o = v * wv[bj][n];
;                             u32x2 p; p.x = pk2(o.x, o.y); p.y = pk2(o.z, o.w); *(u32x2*)(xn + off + bj * HALF + n * 16) = p; }
;                     }
;                 if (xn) { q += __shfl_xor(q, 16); q += __shfl_xor(q, 32); if (fq == 0) (void)__hip_atomic_fetch_add(ss + row, q, __ATOMIC_RELAXED, __HIP_MEMORY_SCOPE_AGENT); }
;             }
;     }
; template <class Epi, bool ALIGN_EPI>
; __device__ __forceinline__ void gemm_phase(LAS unsigned char* lds, const Gemm g, const StaticOrder& S, const Epi& E) {
;     ...
;         if constexpr (ALIGN_EPI) { if (wr == 0) PG8_BAR; }
;         E(acc, cur, wr, wc, fr, fq);
;         if (!has_next) break;
; #pragma unroll
;         for (int a = 0; a < 2; ++a)
; #pragma unroll
;             for (int b = 0; b < 2; ++b)
; #pragma unroll
;                 for (int m = 0; m < 4; ++m)
; #pragma unroll
;                     for (int n = 0; n < 2; ++n) acc[a][b][m][n] = (f32x4){0.f, 0.f, 0.f, 0.f};
;         cur = nxt; cA = nA; cB = nB; ++ui;
;         if constexpr (ALIGN_EPI) { if (wr == 1) PG8_BAR; }
	v_add_f32_e32 v219, v219, v175
	s_nop 0
	ds_bpermute_b32 v218, v226, v219
	s_waitcnt lgkmcnt(0)
	v_add_f32_e32 v219, v219, v218
	s_mov_b64 exec, s[0:1]
	global_atomic_add_f32 v[190:191], v219, off
	s_mov_b64 exec, -1
	s_mov_b64 vcc, 64
	v_lshl_add_u64 v[190:191], v[190:191], 0, vcc
	v_mov_b32_dpp v220, v8 row_ror:8 row_mask:0xf bank_mask:0xf
	v_mov_b32_dpp v221, v9 row_ror:8 row_mask:0xf bank_mask:0xf
	v_mov_b32_dpp v222, v10 row_ror:8 row_mask:0xf bank_mask:0xf
	v_mov_b32_dpp v223, v11 row_ror:8 row_mask:0xf bank_mask:0xf
	v_cndmask_b32_e64 v8, v220, v12, s[34:35]
	v_cndmask_b32_e64 v9, v221, v13, s[34:35]
	v_cndmask_b32_e64 v10, v222, v14, s[34:35]
	v_cndmask_b32_e64 v11, v223, v15, s[34:35]
	v_cndmask_b32_e64 v12, v12, v220, s[34:35]
	v_cndmask_b32_e64 v13, v13, v221, s[34:35]
	v_cndmask_b32_e64 v14, v14, v222, s[34:35]
	v_cndmask_b32_e64 v15, v15, v223, s[34:35]
	v_mov_b32_dpp v220, v0 row_ror:8 row_mask:0xf bank_mask:0xf
	v_mov_b32_dpp v221, v1 row_ror:8 row_mask:0xf bank_mask:0xf
	v_mov_b32_dpp v222, v2 row_ror:8 row_mask:0xf bank_mask:0xf
	v_mov_b32_dpp v223, v3 row_ror:8 row_mask:0xf bank_mask:0xf
	v_cndmask_b32_e64 v0, v220, v4, s[34:35]
	v_cndmask_b32_e64 v1, v221, v5, s[34:35]
	v_cndmask_b32_e64 v2, v222, v6, s[34:35]
	v_cndmask_b32_e64 v3, v223, v7, s[34:35]
	v_cndmask_b32_e64 v4, v4, v220, s[34:35]
	v_cndmask_b32_e64 v5, v5, v221, s[34:35]
	v_cndmask_b32_e64 v6, v6, v222, s[34:35]
	v_cndmask_b32_e64 v7, v7, v223, s[34:35]
	s_waitcnt vmcnt(1)
	v_pk_fma_f32 v[10:11], v[10:11], 0.5, v[158:159] op_sel_hi:[1,0,1]
	v_pk_fma_f32 v[8:9], v[8:9], 0.5, v[156:157] op_sel_hi:[1,0,1]
	global_store_dwordx4 v[202:203], v[8:11], off
	v_pk_mul_f32 v[208:209], v[64:65], v[8:9]
	v_pk_mul_f32 v[210:211], v[66:67], v[10:11]
	v_mul_f32_e32 v219, v8, v8
	v_add_u32_e32 v208, 0x8000, v208
	v_add_u32_e32 v209, 0x8000, v209
	v_add_u32_e32 v210, 0x8000, v210
	v_add_u32_e32 v211, 0x8000, v211
	v_fmac_f32_e32 v219, v9, v9
	v_fmac_f32_e32 v219, v10, v10
	v_fmac_f32_e32 v219, v11, v11
	v_perm_b32 v206, v209, v208, s58
	v_perm_b32 v207, v211, v210, s58
	global_store_dwordx2 v[186:187], v[206:207], off
	v_pk_fma_f32 v[2:3], v[2:3], 0.5, v[162:163] op_sel_hi:[1,0,1]
	v_pk_fma_f32 v[0:1], v[0:1], 0.5, v[160:161] op_sel_hi:[1,0,1]
	global_store_dwordx4 v[202:203], v[0:3], off offset:512
	v_pk_mul_f32 v[212:213], v[72:73], v[0:1]
	v_pk_mul_f32 v[214:215], v[74:75], v[2:3]
	v_fmac_f32_e32 v219, v0, v0
	v_add_u32_e32 v212, 0x8000, v212
	v_add_u32_e32 v213, 0x8000, v213
	v_add_u32_e32 v214, 0x8000, v214
	v_add_u32_e32 v215, 0x8000, v215
	v_fmac_f32_e32 v219, v1, v1
	v_fmac_f32_e32 v219, v2, v2
	v_fmac_f32_e32 v219, v3, v3
	v_perm_b32 v216, v213, v212, s58
	v_perm_b32 v217, v215, v214, s58
	global_store_dwordx2 v[186:187], v[216:217], off offset:256
	v_pk_fma_f32 v[14:15], v[14:15], 0.5, v[178:179] op_sel_hi:[1,0,1]
	v_pk_fma_f32 v[12:13], v[12:13], 0.5, v[176:177] op_sel_hi:[1,0,1]
	global_store_dwordx4 v[204:205], v[12:15], off
	v_pk_mul_f32 v[208:209], v[80:81], v[12:13]
	v_pk_mul_f32 v[210:211], v[82:83], v[14:15]
	v_mul_f32_e32 v224, v12, v12
	v_add_u32_e32 v208, 0x8000, v208
	v_add_u32_e32 v209, 0x8000, v209
	v_add_u32_e32 v210, 0x8000, v210
	v_add_u32_e32 v211, 0x8000, v211
	v_fmac_f32_e32 v224, v13, v13
	v_fmac_f32_e32 v224, v14, v14
	v_fmac_f32_e32 v224, v15, v15
	v_perm_b32 v206, v209, v208, s58
	v_perm_b32 v207, v211, v210, s58
	global_store_dwordx2 v[188:189], v[206:207], off
	v_pk_fma_f32 v[6:7], v[6:7], 0.5, v[182:183] op_sel_hi:[1,0,1]
	v_pk_fma_f32 v[4:5], v[4:5], 0.5, v[180:181] op_sel_hi:[1,0,1]
	global_store_dwordx4 v[204:205], v[4:7], off offset:512
	v_pk_mul_f32 v[212:213], v[84:85], v[4:5]
	v_pk_mul_f32 v[214:215], v[86:87], v[6:7]
	v_fmac_f32_e32 v224, v4, v4
	v_add_u32_e32 v212, 0x8000, v212
	v_add_u32_e32 v213, 0x8000, v213
	v_add_u32_e32 v214, 0x8000, v214
	v_add_u32_e32 v215, 0x8000, v215
	v_fmac_f32_e32 v224, v5, v5
	v_fmac_f32_e32 v224, v6, v6
	v_fmac_f32_e32 v224, v7, v7
	v_perm_b32 v216, v213, v212, s58
	v_perm_b32 v217, v215, v214, s58
	global_store_dwordx2 v[188:189], v[216:217], off offset:256
	s_nop 1
	v_mov_b32_dpp v175, v219 row_ror:8 row_mask:0xf bank_mask:0xf
	v_mov_b32_dpp v218, v224 row_ror:8 row_mask:0xf bank_mask:0xf
	v_add_f32_e32 v219, v219, v175
	v_add_f32_e32 v224, v224, v218
	v_cndmask_b32_e64 v219, v224, v219, s[34:35]
	s_nop 0
	ds_bpermute_b32 v175, v225, v219
	s_waitcnt lgkmcnt(0)
	v_add_f32_e32 v219, v219, v175
	s_nop 0
	ds_bpermute_b32 v218, v226, v219
	s_waitcnt lgkmcnt(0)
	v_add_f32_e32 v219, v219, v218
	s_mov_b64 exec, s[0:1]
	global_atomic_add_f32 v[190:191], v219, off
	s_mov_b64 exec, -1
	s_and_b64 vcc, exec, s[6:7]
	s_mov_b64 s[4:5], -1
	s_cbranch_vccnz .LBB0_301
	s_andn2_b64 vcc, exec, s[12:13]
	s_cbranch_vccnz .LBB0_300
	s_barrier
	s_branch .LBB0_300

;     __device__ __forceinline__ void operator()(const f32x4 (&acc)[2][2][4][2], const Unit& u, int wr, int wc, int fr, int fq) const {
;         const int row0 = u.pm * BM + wr * 64 + fr, col0 = u.pn * BM + wc * 32 + 4 * fq;
;         const float* rbase = (u.pm * BM < SEQ_P) ? resA : (resB - (size_t)SEQ_P * ldc);
;         f32x4 wv[2][2];
;         if (xn) {
; #pragma unroll
;             for (int bj = 0; bj < 2; ++bj)
; #pragma unroll
;                 for (int n = 0; n < 2; ++n) wv[bj][n] = *(const f32x4*)(wn + col0 + bj * HALF + n * 16);
;         }
; #pragma unroll
;         for (int ai = 0; ai < 2; ++ai)
; #pragma unroll
;             for (int m = 0; m < 4; ++m) {
;                 const int row = row0 + ai * HALF + m * 16;
;                 const size_t off = (size_t)row * ldc + col0;
;                 float q = 0.f;
; #pragma unroll
;                 for (int bj = 0; bj < 2; ++bj)
; #pragma unroll
;                     for (int n = 0; n < 2; ++n) {
;                         const f32x4 rv = *(const f32x4*)(rbase + off + bj * HALF + n * 16);
;                         const f32x4 v = rv + acc[ai][bj][m][n] * scale;
;                         if (out) *(f32x4*)(out + off + bj * HALF + n * 16) = v;
;                         if (xn) { q += (v.x * v.x + v.y * v.y) + (v.z * v.z + v.w * v.w); const f32x4 o = v * wv[bj][n];
;                             u32x2 p; p.x = pk2(o.x, o.y); p.y = pk2(o.z, o.w); *(u32x2*)(xn + off + bj * HALF + n * 16) = p; }
;                     }
;                 if (xn) { q += __shfl_xor(q, 16); q += __shfl_xor(q, 32); if (fq == 0) (void)__hip_atomic_fetch_add(ss + row, q, __ATOMIC_RELAXED, __HIP_MEMORY_SCOPE_AGENT); }
;             }
;     }
.LBB0_1085:
	v_lshl_add_u32 v196, s34, 8, v164
	v_lshl_or_b32 v198, s4, 8, v168
	v_and_b32_e32 v227, 8, v172
	v_mov_b32_e32 v197, 0
	v_cmp_eq_u32_e64 s[34:35], 0, v227
	v_lshlrev_b32_e32 v219, 1, v227
	v_add_u32_e32 v200, v198, v219
	v_sub_u32_e32 v224, 16, v219
	v_add_u32_e32 v224, v198, v224
	v_mov_b32_e32 v198, v200
	v_mov_b32_e32 v200, v224
	v_mov_b32_e32 v199, 0
	v_mov_b32_e32 v201, 0
	v_sub_u32_e32 v194, v196, v227
	v_mov_b32_e32 v195, 0
	v_lshlrev_b64 v[192:193], 11, v[194:195]
	v_add_u32_e32 v194, 8, v194
	v_lshlrev_b64 v[194:195], 11, v[194:195]
	v_lshl_add_u64 v[192:193], v[192:193], 0, v[198:199]
	v_lshl_add_u64 v[194:195], v[194:195], 0, v[200:201]
	v_lshl_add_u64 v[174:175], v[192:193], 2, s[8:9]
	v_lshl_add_u64 v[184:185], v[194:195], 2, s[8:9]
	v_lshl_add_u64 v[186:187], v[198:199], 2, s[10:11]
	v_lshl_add_u64 v[188:189], v[200:201], 2, s[10:11]
	global_load_dwordx4 v[64:67], v[186:187], off
	global_load_dwordx4 v[72:75], v[186:187], off offset:512
	global_load_dwordx4 v[76:79], v[188:189], off
	global_load_dwordx4 v[84:87], v[188:189], off offset:512
	global_load_dwordx4 v[156:159], v[174:175], off
	global_load_dwordx4 v[160:163], v[174:175], off offset:512
	global_load_dwordx4 v[176:179], v[184:185], off
	global_load_dwordx4 v[180:183], v[184:185], off offset:512
	s_mov_b64 vcc, 0x20000
	v_lshl_add_u64 v[174:175], v[174:175], 0, vcc
	v_lshl_add_u64 v[184:185], v[184:185], 0, vcc
	v_lshl_add_u64 v[202:203], v[192:193], 2, s[8:9]
	v_lshl_add_u64 v[204:205], v[194:195], 2, s[8:9]
	v_lshl_add_u64 v[186:187], v[192:193], 1, s[14:15]
	v_lshl_add_u64 v[188:189], v[194:195], 1, s[14:15]
	v_lshl_add_u64 v[190:191], v[196:197], 2, s[16:17]
	v_xor_b32_e32 v225, 16, v172
	v_xor_b32_e32 v226, 32, v172
	v_lshlrev_b32_e32 v225, 2, v225
	v_lshlrev_b32_e32 v226, 2, v226
	v_mov_b32_dpp v220, v136 row_ror:8 row_mask:0xf bank_mask:0xf
	v_mov_b32_dpp v221, v137 row_ror:8 row_mask:0xf bank_mask:0xf
	v_mov_b32_dpp v222, v138 row_ror:8 row_mask:0xf bank_mask:0xf
	v_mov_b32_dpp v223, v139 row_ror:8 row_mask:0xf bank_mask:0xf
	v_cndmask_b32_e64 v136, v220, v140, s[34:35]
	v_cndmask_b32_e64 v137, v221, v141, s[34:35]
	v_cndmask_b32_e64 v138, v222, v142, s[34:35]
	v_cndmask_b32_e64 v139, v223, v143, s[34:35]
	v_cndmask_b32_e64 v140, v140, v220, s[34:35]
	v_cndmask_b32_e64 v141, v141, v221, s[34:35]
	v_cndmask_b32_e64 v142, v142, v222, s[34:35]
	v_cndmask_b32_e64 v143, v143, v223, s[34:35]
	v_mov_b32_dpp v220, v128 row_ror:8 row_mask:0xf bank_mask:0xf
	v_mov_b32_dpp v221, v129 row_ror:8 row_mask:0xf bank_mask:0xf
	v_mov_b32_dpp v222, v130 row_ror:8 row_mask:0xf bank_mask:0xf
	v_mov_b32_dpp v223, v131 row_ror:8 row_mask:0xf bank_mask:0xf
	v_cndmask_b32_e64 v128, v220, v132, s[34:35]
	v_cndmask_b32_e64 v129, v221, v133, s[34:35]
	v_cndmask_b32_e64 v130, v222, v134, s[34:35]
	v_cndmask_b32_e64 v131, v223, v135, s[34:35]
	v_cndmask_b32_e64 v132, v132, v220, s[34:35]
	v_cndmask_b32_e64 v133, v133, v221, s[34:35]
	v_cndmask_b32_e64 v134, v134, v222, s[34:35]
	v_cndmask_b32_e64 v135, v135, v223, s[34:35]
	s_waitcnt vmcnt(0)
	v_pk_add_f32 v[138:139], v[138:139], v[158:159]
	v_pk_add_f32 v[136:137], v[136:137], v[156:157]
	global_store_dwordx4 v[202:203], v[136:139], off
	v_pk_mul_f32 v[208:209], v[64:65], v[136:137]
	v_pk_mul_f32 v[210:211], v[66:67], v[138:139]
	v_mul_f32_e32 v219, v136, v136
	v_add_u32_e32 v208, 0x8000, v208
	v_add_u32_e32 v209, 0x8000, v209
	v_add_u32_e32 v210, 0x8000, v210
	v_add_u32_e32 v211, 0x8000, v211
	v_fmac_f32_e32 v219, v137, v137
	v_fmac_f32_e32 v219, v138, v138
	v_fmac_f32_e32 v219, v139, v139
	v_perm_b32 v206, v209, v208, s58
	v_perm_b32 v207, v211, v210, s58
	global_store_dwordx2 v[186:187], v[206:207], off
	v_pk_add_f32 v[130:131], v[130:131], v[162:163]
	v_pk_add_f32 v[128:129], v[128:129], v[160:161]
	global_store_dwordx4 v[202:203], v[128:131], off offset:512
	v_pk_mul_f32 v[212:213], v[72:73], v[128:129]
	v_pk_mul_f32 v[214:215], v[74:75], v[130:131]
	v_fmac_f32_e32 v219, v128, v128
	v_add_u32_e32 v212, 0x8000, v212
	v_add_u32_e32 v213, 0x8000, v213
	v_add_u32_e32 v214, 0x8000, v214
	v_add_u32_e32 v215, 0x8000, v215
	v_fmac_f32_e32 v219, v129, v129
	v_fmac_f32_e32 v219, v130, v130
	v_fmac_f32_e32 v219, v131, v131
	v_perm_b32 v216, v213, v212, s58
	v_perm_b32 v217, v215, v214, s58
	global_store_dwordx2 v[186:187], v[216:217], off offset:256
	v_pk_add_f32 v[142:143], v[142:143], v[178:179]
	v_pk_add_f32 v[140:141], v[140:141], v[176:177]
	global_store_dwordx4 v[204:205], v[140:143], off
	v_pk_mul_f32 v[208:209], v[76:77], v[140:141]
	v_pk_mul_f32 v[210:211], v[78:79], v[142:143]
	v_mul_f32_e32 v224, v140, v140
	v_add_u32_e32 v208, 0x8000, v208
	v_add_u32_e32 v209, 0x8000, v209
	v_add_u32_e32 v210, 0x8000, v210
	v_add_u32_e32 v211, 0x8000, v211
	v_fmac_f32_e32 v224, v141, v141
	v_fmac_f32_e32 v224, v142, v142
	v_fmac_f32_e32 v224, v143, v143
	v_perm_b32 v206, v209, v208, s58
	v_perm_b32 v207, v211, v210, s58
	global_store_dwordx2 v[188:189], v[206:207], off
	v_pk_add_f32 v[134:135], v[134:135], v[182:183]
	v_pk_add_f32 v[132:133], v[132:133], v[180:181]
	global_store_dwordx4 v[204:205], v[132:135], off offset:512
	v_pk_mul_f32 v[212:213], v[84:85], v[132:133]
	v_pk_mul_f32 v[214:215], v[86:87], v[134:135]
	v_fmac_f32_e32 v224, v132, v132
	v_add_u32_e32 v212, 0x8000, v212
	v_add_u32_e32 v213, 0x8000, v213
	v_add_u32_e32 v214, 0x8000, v214
	v_add_u32_e32 v215, 0x8000, v215
	v_fmac_f32_e32 v224, v133, v133
	v_fmac_f32_e32 v224, v134, v134
	v_fmac_f32_e32 v224, v135, v135
	v_perm_b32 v216, v213, v212, s58
	v_perm_b32 v217, v215, v214, s58
	global_store_dwordx2 v[188:189], v[216:217], off offset:256
	s_nop 1
	v_mov_b32_dpp v173, v219 row_ror:8 row_mask:0xf bank_mask:0xf
	v_mov_b32_dpp v218, v224 row_ror:8 row_mask:0xf bank_mask:0xf
	v_add_f32_e32 v219, v219, v173
	v_add_f32_e32 v224, v224, v218
	v_cndmask_b32_e64 v219, v224, v219, s[34:35]
	s_nop 0
	ds_bpermute_b32 v173, v225, v219
	global_load_dwordx4 v[156:159], v[174:175], off
	global_load_dwordx4 v[160:163], v[174:175], off offset:512
	global_load_dwordx4 v[176:179], v[184:185], off
	global_load_dwordx4 v[180:183], v[184:185], off offset:512
	s_mov_b64 vcc, 0x20000
	v_lshl_add_u64 v[174:175], v[174:175], 0, vcc
	v_lshl_add_u64 v[184:185], v[184:185], 0, vcc
	s_mov_b64 vcc, 0x20000
	v_lshl_add_u64 v[202:203], v[202:203], 0, vcc
	v_lshl_add_u64 v[204:205], v[204:205], 0, vcc
	s_mov_b64 vcc, 0x10000
	v_lshl_add_u64 v[186:187], v[186:187], 0, vcc
	v_lshl_add_u64 v[188:189], v[188:189], 0, vcc
	s_waitcnt lgkmcnt(0)
;     __device__ __forceinline__ void operator()(const f32x4 (&acc)[2][2][4][2], const Unit& u, int wr, int wc, int fr, int fq) const {
;         const int row0 = u.pm * BM + wr * 64 + fr, col0 = u.pn * BM + wc * 32 + 4 * fq;
;         const float* rbase = (u.pm * BM < SEQ_P) ? resA : (resB - (size_t)SEQ_P * ldc);
;         f32x4 wv[2][2];
;         if (xn) {
; #pragma unroll
;             for (int bj = 0; bj < 2; ++bj)
; #pragma unroll
;                 for (int n = 0; n < 2; ++n) wv[bj][n] = *(const f32x4*)(wn + col0 + bj * HALF + n * 16);
;         }
; #pragma unroll
;         for (int ai = 0; ai < 2; ++ai)
; #pragma unroll
;             for (int m = 0; m < 4; ++m) {
;                 const int row = row0 + ai * HALF + m * 16;
;                 const size_t off = (size_t)row * ldc + col0;
;                 float q = 0.f;
; #pragma unroll
;                 for (int bj = 0; bj < 2; ++bj)
; #pragma unroll
;                     for (int n = 0; n < 2; ++n) {
;                         const f32x4 rv = *(const f32x4*)(rbase + off + bj * HALF + n * 16);
;                         const f32x4 v = rv + acc[ai][bj][m][n] * scale;
;                         if (out) *(f32x4*)(out + off + bj * HALF + n * 16) = v;
;                         if (xn) { q += (v.x * v.x + v.y * v.y) + (v.z * v.z + v.w * v.w); const f32x4 o = v * wv[bj][n];
;                             u32x2 p; p.x = pk2(o.x, o.y); p.y = pk2(o.z, o.w); *(u32x2*)(xn + off + bj * HALF + n * 16) = p; }
;                     }
;                 if (xn) { q += __shfl_xor(q, 16); q += __shfl_xor(q, 32); if (fq == 0) (void)__hip_atomic_fetch_add(ss + row, q, __ATOMIC_RELAXED, __HIP_MEMORY_SCOPE_AGENT); }
;             }
;     }
	v_add_f32_e32 v219, v219, v173
	s_nop 0
	ds_bpermute_b32 v218, v226, v219
	s_waitcnt lgkmcnt(0)
	v_add_f32_e32 v219, v219, v218
	s_mov_b64 exec, s[0:1]
	global_atomic_add_f32 v[190:191], v219, off
	s_mov_b64 exec, -1
	s_mov_b64 vcc, 64
	v_lshl_add_u64 v[190:191], v[190:191], 0, vcc
	v_mov_b32_dpp v220, v120 row_ror:8 row_mask:0xf bank_mask:0xf
	v_mov_b32_dpp v221, v121 row_ror:8 row_mask:0xf bank_mask:0xf
	v_mov_b32_dpp v222, v122 row_ror:8 row_mask:0xf bank_mask:0xf
	v_mov_b32_dpp v223, v123 row_ror:8 row_mask:0xf bank_mask:0xf
	v_cndmask_b32_e64 v120, v220, v124, s[34:35]
	v_cndmask_b32_e64 v121, v221, v125, s[34:35]
	v_cndmask_b32_e64 v122, v222, v126, s[34:35]
	v_cndmask_b32_e64 v123, v223, v127, s[34:35]
	v_cndmask_b32_e64 v124, v124, v220, s[34:35]
	v_cndmask_b32_e64 v125, v125, v221, s[34:35]
	v_cndmask_b32_e64 v126, v126, v222, s[34:35]
	v_cndmask_b32_e64 v127, v127, v223, s[34:35]
	v_mov_b32_dpp v220, v112 row_ror:8 row_mask:0xf bank_mask:0xf
	v_mov_b32_dpp v221, v113 row_ror:8 row_mask:0xf bank_mask:0xf
	v_mov_b32_dpp v222, v114 row_ror:8 row_mask:0xf bank_mask:0xf
	v_mov_b32_dpp v223, v115 row_ror:8 row_mask:0xf bank_mask:0xf
	v_cndmask_b32_e64 v112, v220, v116, s[34:35]
	v_cndmask_b32_e64 v113, v221, v117, s[34:35]
	v_cndmask_b32_e64 v114, v222, v118, s[34:35]
	v_cndmask_b32_e64 v115, v223, v119, s[34:35]
	v_cndmask_b32_e64 v116, v116, v220, s[34:35]
	v_cndmask_b32_e64 v117, v117, v221, s[34:35]
	v_cndmask_b32_e64 v118, v118, v222, s[34:35]
	v_cndmask_b32_e64 v119, v119, v223, s[34:35]
	s_waitcnt vmcnt(1)
	v_pk_add_f32 v[122:123], v[122:123], v[158:159]
	v_pk_add_f32 v[120:121], v[120:121], v[156:157]
	global_store_dwordx4 v[202:203], v[120:123], off
	v_pk_mul_f32 v[208:209], v[64:65], v[120:121]
	v_pk_mul_f32 v[210:211], v[66:67], v[122:123]
	v_mul_f32_e32 v219, v120, v120
	v_add_u32_e32 v208, 0x8000, v208
	v_add_u32_e32 v209, 0x8000, v209
	v_add_u32_e32 v210, 0x8000, v210
	v_add_u32_e32 v211, 0x8000, v211
	v_fmac_f32_e32 v219, v121, v121
	v_fmac_f32_e32 v219, v122, v122
	v_fmac_f32_e32 v219, v123, v123
	v_perm_b32 v206, v209, v208, s58
	v_perm_b32 v207, v211, v210, s58
	global_store_dwordx2 v[186:187], v[206:207], off
	v_pk_add_f32 v[114:115], v[114:115], v[162:163]
	v_pk_add_f32 v[112:113], v[112:113], v[160:161]
	global_store_dwordx4 v[202:203], v[112:115], off offset:512
	v_pk_mul_f32 v[212:213], v[72:73], v[112:113]
	v_pk_mul_f32 v[214:215], v[74:75], v[114:115]
	v_fmac_f32_e32 v219, v112, v112
	v_add_u32_e32 v212, 0x8000, v212
	v_add_u32_e32 v213, 0x8000, v213
	v_add_u32_e32 v214, 0x8000, v214
	v_add_u32_e32 v215, 0x8000, v215
	v_fmac_f32_e32 v219, v113, v113
	v_fmac_f32_e32 v219, v114, v114
	v_fmac_f32_e32 v219, v115, v115
	v_perm_b32 v216, v213, v212, s58
	v_perm_b32 v217, v215, v214, s58
	global_store_dwordx2 v[186:187], v[216:217], off offset:256
	v_pk_add_f32 v[126:127], v[126:127], v[178:179]
	v_pk_add_f32 v[124:125], v[124:125], v[176:177]
	global_store_dwordx4 v[204:205], v[124:127], off
	v_pk_mul_f32 v[208:209], v[76:77], v[124:125]
	v_pk_mul_f32 v[210:211], v[78:79], v[126:127]
	v_mul_f32_e32 v224, v124, v124
	v_add_u32_e32 v208, 0x8000, v208
	v_add_u32_e32 v209, 0x8000, v209
	v_add_u32_e32 v210, 0x8000, v210
	v_add_u32_e32 v211, 0x8000, v211
	v_fmac_f32_e32 v224, v125, v125
	v_fmac_f32_e32 v224, v126, v126
	v_fmac_f32_e32 v224, v127, v127
	v_perm_b32 v206, v209, v208, s58
	v_perm_b32 v207, v211, v210, s58
	global_store_dwordx2 v[188:189], v[206:207], off
	v_pk_add_f32 v[118:119], v[118:119], v[182:183]
	v_pk_add_f32 v[116:117], v[116:117], v[180:181]
	global_store_dwordx4 v[204:205], v[116:119], off offset:512
	v_pk_mul_f32 v[212:213], v[84:85], v[116:117]
	v_pk_mul_f32 v[214:215], v[86:87], v[118:119]
	v_fmac_f32_e32 v224, v116, v116
	v_add_u32_e32 v212, 0x8000, v212
	v_add_u32_e32 v213, 0x8000, v213
	v_add_u32_e32 v214, 0x8000, v214
	v_add_u32_e32 v215, 0x8000, v215
	v_fmac_f32_e32 v224, v117, v117
	v_fmac_f32_e32 v224, v118, v118
	v_fmac_f32_e32 v224, v119, v119
	v_perm_b32 v216, v213, v212, s58
	v_perm_b32 v217, v215, v214, s58
	global_store_dwordx2 v[188:189], v[216:217], off offset:256
	s_nop 1
	v_mov_b32_dpp v173, v219 row_ror:8 row_mask:0xf bank_mask:0xf
	v_mov_b32_dpp v218, v224 row_ror:8 row_mask:0xf bank_mask:0xf
	v_add_f32_e32 v219, v219, v173
	v_add_f32_e32 v224, v224, v218
	v_cndmask_b32_e64 v219, v224, v219, s[34:35]
	s_nop 0
	ds_bpermute_b32 v173, v225, v219
	global_load_dwordx4 v[156:159], v[174:175], off
	global_load_dwordx4 v[160:163], v[174:175], off offset:512
	global_load_dwordx4 v[176:179], v[184:185], off
	global_load_dwordx4 v[180:183], v[184:185], off offset:512
	s_mov_b64 vcc, 0x20000
	v_lshl_add_u64 v[174:175], v[174:175], 0, vcc
	v_lshl_add_u64 v[184:185], v[184:185], 0, vcc
	s_mov_b64 vcc, 0x20000
	v_lshl_add_u64 v[202:203], v[202:203], 0, vcc
	v_lshl_add_u64 v[204:205], v[204:205], 0, vcc
	s_mov_b64 vcc, 0x10000
	v_lshl_add_u64 v[186:187], v[186:187], 0, vcc
	v_lshl_add_u64 v[188:189], v[188:189], 0, vcc
	s_waitcnt lgkmcnt(0)
	v_add_f32_e32 v219, v219, v173
	s_nop 0
	ds_bpermute_b32 v218, v226, v219
	s_waitcnt lgkmcnt(0)
;     __device__ __forceinline__ void operator()(const f32x4 (&acc)[2][2][4][2], const Unit& u, int wr, int wc, int fr, int fq) const {
;         const int row0 = u.pm * BM + wr * 64 + fr, col0 = u.pn * BM + wc * 32 + 4 * fq;
;         const float* rbase = (u.pm * BM < SEQ_P) ? resA : (resB - (size_t)SEQ_P * ldc);
;         f32x4 wv[2][2];
;         if (xn) {
; #pragma unroll
;             for (int bj = 0; bj < 2; ++bj)
; #pragma unroll
;                 for (int n = 0; n < 2; ++n) wv[bj][n] = *(const f32x4*)(wn + col0 + bj * HALF + n * 16);
;         }
; #pragma unroll
;         for (int ai = 0; ai < 2; ++ai)
; #pragma unroll
;             for (int m = 0; m < 4; ++m) {
;                 const int row = row0 + ai * HALF + m * 16;
;                 const size_t off = (size_t)row * ldc + col0;
;                 float q = 0.f;
; #pragma unroll
;                 for (int bj = 0; bj < 2; ++bj)
; #pragma unroll
;                     for (int n = 0; n < 2; ++n) {
;                         const f32x4 rv = *(const f32x4*)(rbase + off + bj * HALF + n * 16);
;                         const f32x4 v = rv + acc[ai][bj][m][n] * scale;
;                         if (out) *(f32x4*)(out + off + bj * HALF + n * 16) = v;
;                         if (xn) { q += (v.x * v.x + v.y * v.y) + (v.z * v.z + v.w * v.w); const f32x4 o = v * wv[bj][n];
;                             u32x2 p; p.x = pk2(o.x, o.y); p.y = pk2(o.z, o.w); *(u32x2*)(xn + off + bj * HALF + n * 16) = p; }
;                     }
;                 if (xn) { q += __shfl_xor(q, 16); q += __shfl_xor(q, 32); if (fq == 0) (void)__hip_atomic_fetch_add(ss + row, q, __ATOMIC_RELAXED, __HIP_MEMORY_SCOPE_AGENT); }
;             }
;     }
	v_add_f32_e32 v219, v219, v218
	s_mov_b64 exec, s[0:1]
	global_atomic_add_f32 v[190:191], v219, off
	s_mov_b64 exec, -1
	s_mov_b64 vcc, 64
	v_lshl_add_u64 v[190:191], v[190:191], 0, vcc
	v_mov_b32_dpp v220, v104 row_ror:8 row_mask:0xf bank_mask:0xf
	v_mov_b32_dpp v221, v105 row_ror:8 row_mask:0xf bank_mask:0xf
	v_mov_b32_dpp v222, v106 row_ror:8 row_mask:0xf bank_mask:0xf
	v_mov_b32_dpp v223, v107 row_ror:8 row_mask:0xf bank_mask:0xf
	v_cndmask_b32_e64 v104, v220, v108, s[34:35]
	v_cndmask_b32_e64 v105, v221, v109, s[34:35]
	v_cndmask_b32_e64 v106, v222, v110, s[34:35]
	v_cndmask_b32_e64 v107, v223, v111, s[34:35]
	v_cndmask_b32_e64 v108, v108, v220, s[34:35]
	v_cndmask_b32_e64 v109, v109, v221, s[34:35]
	v_cndmask_b32_e64 v110, v110, v222, s[34:35]
	v_cndmask_b32_e64 v111, v111, v223, s[34:35]
	v_mov_b32_dpp v220, v96 row_ror:8 row_mask:0xf bank_mask:0xf
	v_mov_b32_dpp v221, v97 row_ror:8 row_mask:0xf bank_mask:0xf
	v_mov_b32_dpp v222, v98 row_ror:8 row_mask:0xf bank_mask:0xf
	v_mov_b32_dpp v223, v99 row_ror:8 row_mask:0xf bank_mask:0xf
	v_cndmask_b32_e64 v96, v220, v100, s[34:35]
	v_cndmask_b32_e64 v97, v221, v101, s[34:35]
	v_cndmask_b32_e64 v98, v222, v102, s[34:35]
	v_cndmask_b32_e64 v99, v223, v103, s[34:35]
	v_cndmask_b32_e64 v100, v100, v220, s[34:35]
	v_cndmask_b32_e64 v101, v101, v221, s[34:35]
	v_cndmask_b32_e64 v102, v102, v222, s[34:35]
	v_cndmask_b32_e64 v103, v103, v223, s[34:35]
	s_waitcnt vmcnt(1)
	v_pk_add_f32 v[106:107], v[106:107], v[158:159]
	v_pk_add_f32 v[104:105], v[104:105], v[156:157]
	global_store_dwordx4 v[202:203], v[104:107], off
	v_pk_mul_f32 v[208:209], v[64:65], v[104:105]
	v_pk_mul_f32 v[210:211], v[66:67], v[106:107]
	v_mul_f32_e32 v219, v104, v104
	v_add_u32_e32 v208, 0x8000, v208
	v_add_u32_e32 v209, 0x8000, v209
	v_add_u32_e32 v210, 0x8000, v210
	v_add_u32_e32 v211, 0x8000, v211
	v_fmac_f32_e32 v219, v105, v105
	v_fmac_f32_e32 v219, v106, v106
	v_fmac_f32_e32 v219, v107, v107
	v_perm_b32 v206, v209, v208, s58
	v_perm_b32 v207, v211, v210, s58
	global_store_dwordx2 v[186:187], v[206:207], off
	v_pk_add_f32 v[98:99], v[98:99], v[162:163]
	v_pk_add_f32 v[96:97], v[96:97], v[160:161]
	global_store_dwordx4 v[202:203], v[96:99], off offset:512
	v_pk_mul_f32 v[212:213], v[72:73], v[96:97]
	v_pk_mul_f32 v[214:215], v[74:75], v[98:99]
	v_fmac_f32_e32 v219, v96, v96
	v_add_u32_e32 v212, 0x8000, v212
	v_add_u32_e32 v213, 0x8000, v213
	v_add_u32_e32 v214, 0x8000, v214
	v_add_u32_e32 v215, 0x8000, v215
	v_fmac_f32_e32 v219, v97, v97
	v_fmac_f32_e32 v219, v98, v98
	v_fmac_f32_e32 v219, v99, v99
	v_perm_b32 v216, v213, v212, s58
	v_perm_b32 v217, v215, v214, s58
	global_store_dwordx2 v[186:187], v[216:217], off offset:256
	v_pk_add_f32 v[110:111], v[110:111], v[178:179]
	v_pk_add_f32 v[108:109], v[108:109], v[176:177]
	global_store_dwordx4 v[204:205], v[108:111], off
	v_pk_mul_f32 v[208:209], v[76:77], v[108:109]
	v_pk_mul_f32 v[210:211], v[78:79], v[110:111]
	v_mul_f32_e32 v224, v108, v108
	v_add_u32_e32 v208, 0x8000, v208
	v_add_u32_e32 v209, 0x8000, v209
	v_add_u32_e32 v210, 0x8000, v210
	v_add_u32_e32 v211, 0x8000, v211
	v_fmac_f32_e32 v224, v109, v109
	v_fmac_f32_e32 v224, v110, v110
	v_fmac_f32_e32 v224, v111, v111
	v_perm_b32 v206, v209, v208, s58
	v_perm_b32 v207, v211, v210, s58
	global_store_dwordx2 v[188:189], v[206:207], off
	v_pk_add_f32 v[102:103], v[102:103], v[182:183]
	v_pk_add_f32 v[100:101], v[100:101], v[180:181]
	global_store_dwordx4 v[204:205], v[100:103], off offset:512
	v_pk_mul_f32 v[212:213], v[84:85], v[100:101]
	v_pk_mul_f32 v[214:215], v[86:87], v[102:103]
	v_fmac_f32_e32 v224, v100, v100
	v_add_u32_e32 v212, 0x8000, v212
	v_add_u32_e32 v213, 0x8000, v213
	v_add_u32_e32 v214, 0x8000, v214
	v_add_u32_e32 v215, 0x8000, v215
	v_fmac_f32_e32 v224, v101, v101
	v_fmac_f32_e32 v224, v102, v102
	v_fmac_f32_e32 v224, v103, v103
	v_perm_b32 v216, v213, v212, s58
	v_perm_b32 v217, v215, v214, s58
	global_store_dwordx2 v[188:189], v[216:217], off offset:256
	s_nop 1
	v_mov_b32_dpp v173, v219 row_ror:8 row_mask:0xf bank_mask:0xf
	v_mov_b32_dpp v218, v224 row_ror:8 row_mask:0xf bank_mask:0xf
	v_add_f32_e32 v219, v219, v173
	v_add_f32_e32 v224, v224, v218
	v_cndmask_b32_e64 v219, v224, v219, s[34:35]
	s_nop 0
	ds_bpermute_b32 v173, v225, v219
	global_load_dwordx4 v[156:159], v[174:175], off
	global_load_dwordx4 v[160:163], v[174:175], off offset:512
	global_load_dwordx4 v[176:179], v[184:185], off
	global_load_dwordx4 v[180:183], v[184:185], off offset:512
	s_mov_b64 vcc, 0xa0000
	v_lshl_add_u64 v[174:175], v[174:175], 0, vcc
	v_lshl_add_u64 v[184:185], v[184:185], 0, vcc
	s_mov_b64 vcc, 0x20000
	v_lshl_add_u64 v[202:203], v[202:203], 0, vcc
	v_lshl_add_u64 v[204:205], v[204:205], 0, vcc
	s_mov_b64 vcc, 0x10000
	v_lshl_add_u64 v[186:187], v[186:187], 0, vcc
	v_lshl_add_u64 v[188:189], v[188:189], 0, vcc
	s_waitcnt lgkmcnt(0)
	v_add_f32_e32 v219, v219, v173
	s_nop 0
	ds_bpermute_b32 v218, v226, v219
	s_waitcnt lgkmcnt(0)
;     __device__ __forceinline__ void operator()(const f32x4 (&acc)[2][2][4][2], const Unit& u, int wr, int wc, int fr, int fq) const {
;         const int row0 = u.pm * BM + wr * 64 + fr, col0 = u.pn * BM + wc * 32 + 4 * fq;
;         const float* rbase = (u.pm * BM < SEQ_P) ? resA : (resB - (size_t)SEQ_P * ldc);
;         f32x4 wv[2][2];
;         if (xn) {
; #pragma unroll
;             for (int bj = 0; bj < 2; ++bj)
; #pragma unroll
;                 for (int n = 0; n < 2; ++n) wv[bj][n] = *(const f32x4*)(wn + col0 + bj * HALF + n * 16);
;         }
; #pragma unroll
;         for (int ai = 0; ai < 2; ++ai)
; #pragma unroll
;             for (int m = 0; m < 4; ++m) {
;                 const int row = row0 + ai * HALF + m * 16;
;                 const size_t off = (size_t)row * ldc + col0;
;                 float q = 0.f;
; #pragma unroll
;                 for (int bj = 0; bj < 2; ++bj)
; #pragma unroll
;                     for (int n = 0; n < 2; ++n) {
;                         const f32x4 rv = *(const f32x4*)(rbase + off + bj * HALF + n * 16);
;                         const f32x4 v = rv + acc[ai][bj][m][n] * scale;
;                         if (out) *(f32x4*)(out + off + bj * HALF + n * 16) = v;
;                         if (xn) { q += (v.x * v.x + v.y * v.y) + (v.z * v.z + v.w * v.w); const f32x4 o = v * wv[bj][n];
;                             u32x2 p; p.x = pk2(o.x, o.y); p.y = pk2(o.z, o.w); *(u32x2*)(xn + off + bj * HALF + n * 16) = p; }
;                     }
;                 if (xn) { q += __shfl_xor(q, 16); q += __shfl_xor(q, 32); if (fq == 0) (void)__hip_atomic_fetch_add(ss + row, q, __ATOMIC_RELAXED, __HIP_MEMORY_SCOPE_AGENT); }
;             }
;     }
	v_add_f32_e32 v219, v219, v218
	s_mov_b64 exec, s[0:1]
	global_atomic_add_f32 v[190:191], v219, off
	s_mov_b64 exec, -1
	s_mov_b64 vcc, 64
	v_lshl_add_u64 v[190:191], v[190:191], 0, vcc
	v_mov_b32_dpp v220, v88 row_ror:8 row_mask:0xf bank_mask:0xf
	v_mov_b32_dpp v221, v89 row_ror:8 row_mask:0xf bank_mask:0xf
	v_mov_b32_dpp v222, v90 row_ror:8 row_mask:0xf bank_mask:0xf
	v_mov_b32_dpp v223, v91 row_ror:8 row_mask:0xf bank_mask:0xf
	v_cndmask_b32_e64 v88, v220, v92, s[34:35]
	v_cndmask_b32_e64 v89, v221, v93, s[34:35]
	v_cndmask_b32_e64 v90, v222, v94, s[34:35]
	v_cndmask_b32_e64 v91, v223, v95, s[34:35]
	v_cndmask_b32_e64 v92, v92, v220, s[34:35]
	v_cndmask_b32_e64 v93, v93, v221, s[34:35]
	v_cndmask_b32_e64 v94, v94, v222, s[34:35]
	v_cndmask_b32_e64 v95, v95, v223, s[34:35]
	v_mov_b32_dpp v220, v68 row_ror:8 row_mask:0xf bank_mask:0xf
	v_mov_b32_dpp v221, v69 row_ror:8 row_mask:0xf bank_mask:0xf
	v_mov_b32_dpp v222, v70 row_ror:8 row_mask:0xf bank_mask:0xf
	v_mov_b32_dpp v223, v71 row_ror:8 row_mask:0xf bank_mask:0xf
	v_cndmask_b32_e64 v68, v220, v80, s[34:35]
	v_cndmask_b32_e64 v69, v221, v81, s[34:35]
	v_cndmask_b32_e64 v70, v222, v82, s[34:35]
	v_cndmask_b32_e64 v71, v223, v83, s[34:35]
	v_cndmask_b32_e64 v80, v80, v220, s[34:35]
	v_cndmask_b32_e64 v81, v81, v221, s[34:35]
	v_cndmask_b32_e64 v82, v82, v222, s[34:35]
	v_cndmask_b32_e64 v83, v83, v223, s[34:35]
	s_waitcnt vmcnt(1)
	v_pk_add_f32 v[90:91], v[90:91], v[158:159]
	v_pk_add_f32 v[88:89], v[88:89], v[156:157]
	global_store_dwordx4 v[202:203], v[88:91], off
	v_pk_mul_f32 v[208:209], v[64:65], v[88:89]
	v_pk_mul_f32 v[210:211], v[66:67], v[90:91]
	v_mul_f32_e32 v219, v88, v88
	v_add_u32_e32 v208, 0x8000, v208
	v_add_u32_e32 v209, 0x8000, v209
	v_add_u32_e32 v210, 0x8000, v210
	v_add_u32_e32 v211, 0x8000, v211
	v_fmac_f32_e32 v219, v89, v89
	v_fmac_f32_e32 v219, v90, v90
	v_fmac_f32_e32 v219, v91, v91
	v_perm_b32 v206, v209, v208, s58
	v_perm_b32 v207, v211, v210, s58
	global_store_dwordx2 v[186:187], v[206:207], off
	v_pk_add_f32 v[70:71], v[70:71], v[162:163]
	v_pk_add_f32 v[68:69], v[68:69], v[160:161]
	global_store_dwordx4 v[202:203], v[68:71], off offset:512
	v_pk_mul_f32 v[212:213], v[72:73], v[68:69]
	v_pk_mul_f32 v[214:215], v[74:75], v[70:71]
	v_fmac_f32_e32 v219, v68, v68
	v_add_u32_e32 v212, 0x8000, v212
	v_add_u32_e32 v213, 0x8000, v213
	v_add_u32_e32 v214, 0x8000, v214
	v_add_u32_e32 v215, 0x8000, v215
	v_fmac_f32_e32 v219, v69, v69
	v_fmac_f32_e32 v219, v70, v70
	v_fmac_f32_e32 v219, v71, v71
	v_perm_b32 v216, v213, v212, s58
	v_perm_b32 v217, v215, v214, s58
	global_store_dwordx2 v[186:187], v[216:217], off offset:256
	v_pk_add_f32 v[94:95], v[94:95], v[178:179]
	v_pk_add_f32 v[92:93], v[92:93], v[176:177]
	global_store_dwordx4 v[204:205], v[92:95], off
	v_pk_mul_f32 v[208:209], v[76:77], v[92:93]
	v_pk_mul_f32 v[210:211], v[78:79], v[94:95]
	v_mul_f32_e32 v224, v92, v92
	v_add_u32_e32 v208, 0x8000, v208
	v_add_u32_e32 v209, 0x8000, v209
	v_add_u32_e32 v210, 0x8000, v210
	v_add_u32_e32 v211, 0x8000, v211
	v_fmac_f32_e32 v224, v93, v93
	v_fmac_f32_e32 v224, v94, v94
	v_fmac_f32_e32 v224, v95, v95
	v_perm_b32 v206, v209, v208, s58
	v_perm_b32 v207, v211, v210, s58
	global_store_dwordx2 v[188:189], v[206:207], off
	v_pk_add_f32 v[82:83], v[82:83], v[182:183]
	v_pk_add_f32 v[80:81], v[80:81], v[180:181]
	global_store_dwordx4 v[204:205], v[80:83], off offset:512
	v_pk_mul_f32 v[212:213], v[84:85], v[80:81]
	v_pk_mul_f32 v[214:215], v[86:87], v[82:83]
	v_fmac_f32_e32 v224, v80, v80
	v_add_u32_e32 v212, 0x8000, v212
	v_add_u32_e32 v213, 0x8000, v213
	v_add_u32_e32 v214, 0x8000, v214
	v_add_u32_e32 v215, 0x8000, v215
	v_fmac_f32_e32 v224, v81, v81
	v_fmac_f32_e32 v224, v82, v82
	v_fmac_f32_e32 v224, v83, v83
	v_perm_b32 v216, v213, v212, s58
	v_perm_b32 v217, v215, v214, s58
	global_store_dwordx2 v[188:189], v[216:217], off offset:256
	s_nop 1
	v_mov_b32_dpp v173, v219 row_ror:8 row_mask:0xf bank_mask:0xf
	v_mov_b32_dpp v218, v224 row_ror:8 row_mask:0xf bank_mask:0xf
	v_add_f32_e32 v219, v219, v173
	v_add_f32_e32 v224, v224, v218
	v_cndmask_b32_e64 v219, v224, v219, s[34:35]
	s_nop 0
	ds_bpermute_b32 v173, v225, v219
	global_load_dwordx4 v[156:159], v[174:175], off
	global_load_dwordx4 v[160:163], v[174:175], off offset:512
	global_load_dwordx4 v[176:179], v[184:185], off
	global_load_dwordx4 v[180:183], v[184:185], off offset:512
	s_mov_b64 vcc, 0x20000
	v_lshl_add_u64 v[174:175], v[174:175], 0, vcc
	v_lshl_add_u64 v[184:185], v[184:185], 0, vcc
	s_mov_b64 vcc, 0xa0000
	v_lshl_add_u64 v[202:203], v[202:203], 0, vcc
	v_lshl_add_u64 v[204:205], v[204:205], 0, vcc
	s_mov_b64 vcc, 0x50000
	v_lshl_add_u64 v[186:187], v[186:187], 0, vcc
	v_lshl_add_u64 v[188:189], v[188:189], 0, vcc
	s_waitcnt lgkmcnt(0)
	v_add_f32_e32 v219, v219, v173
	s_nop 0
	ds_bpermute_b32 v218, v226, v219
	s_waitcnt lgkmcnt(0)
	v_add_f32_e32 v219, v219, v218
	s_mov_b64 exec, s[0:1]
	global_atomic_add_f32 v[190:191], v219, off
	s_mov_b64 exec, -1
	s_mov_b64 vcc, 320
	v_lshl_add_u64 v[190:191], v[190:191], 0, vcc
	v_mov_b32_dpp v220, v56 row_ror:8 row_mask:0xf bank_mask:0xf
	v_mov_b32_dpp v221, v57 row_ror:8 row_mask:0xf bank_mask:0xf
	v_mov_b32_dpp v222, v58 row_ror:8 row_mask:0xf bank_mask:0xf
	v_mov_b32_dpp v223, v59 row_ror:8 row_mask:0xf bank_mask:0xf
	v_cndmask_b32_e64 v56, v220, v60, s[34:35]
	v_cndmask_b32_e64 v57, v221, v61, s[34:35]
	v_cndmask_b32_e64 v58, v222, v62, s[34:35]
	v_cndmask_b32_e64 v59, v223, v63, s[34:35]
	v_cndmask_b32_e64 v60, v60, v220, s[34:35]
	v_cndmask_b32_e64 v61, v61, v221, s[34:35]
	v_cndmask_b32_e64 v62, v62, v222, s[34:35]
	v_cndmask_b32_e64 v63, v63, v223, s[34:35]
	v_mov_b32_dpp v220, v48 row_ror:8 row_mask:0xf bank_mask:0xf
	v_mov_b32_dpp v221, v49 row_ror:8 row_mask:0xf bank_mask:0xf
	v_mov_b32_dpp v222, v50 row_ror:8 row_mask:0xf bank_mask:0xf
	v_mov_b32_dpp v223, v51 row_ror:8 row_mask:0xf bank_mask:0xf
	v_cndmask_b32_e64 v48, v220, v52, s[34:35]
	v_cndmask_b32_e64 v49, v221, v53, s[34:35]
	v_cndmask_b32_e64 v50, v222, v54, s[34:35]
	v_cndmask_b32_e64 v51, v223, v55, s[34:35]
	v_cndmask_b32_e64 v52, v52, v220, s[34:35]
	v_cndmask_b32_e64 v53, v53, v221, s[34:35]
	v_cndmask_b32_e64 v54, v54, v222, s[34:35]
	v_cndmask_b32_e64 v55, v55, v223, s[34:35]
	s_waitcnt vmcnt(1)
;     __device__ __forceinline__ void operator()(const f32x4 (&acc)[2][2][4][2], const Unit& u, int wr, int wc, int fr, int fq) const {
;         const int row0 = u.pm * BM + wr * 64 + fr, col0 = u.pn * BM + wc * 32 + 4 * fq;
;         const float* rbase = (u.pm * BM < SEQ_P) ? resA : (resB - (size_t)SEQ_P * ldc);
;         f32x4 wv[2][2];
;         if (xn) {
; #pragma unroll
;             for (int bj = 0; bj < 2; ++bj)
; #pragma unroll
;                 for (int n = 0; n < 2; ++n) wv[bj][n] = *(const f32x4*)(wn + col0 + bj * HALF + n * 16);
;         }
; #pragma unroll
;         for (int ai = 0; ai < 2; ++ai)
; #pragma unroll
;             for (int m = 0; m < 4; ++m) {
;                 const int row = row0 + ai * HALF + m * 16;
;                 const size_t off = (size_t)row * ldc + col0;
;                 float q = 0.f;
; #pragma unroll
;                 for (int bj = 0; bj < 2; ++bj)
; #pragma unroll
;                     for (int n = 0; n < 2; ++n) {
;                         const f32x4 rv = *(const f32x4*)(rbase + off + bj * HALF + n * 16);
;                         const f32x4 v = rv + acc[ai][bj][m][n] * scale;
;                         if (out) *(f32x4*)(out + off + bj * HALF + n * 16) = v;
;                         if (xn) { q += (v.x * v.x + v.y * v.y) + (v.z * v.z + v.w * v.w); const f32x4 o = v * wv[bj][n];
;                             u32x2 p; p.x = pk2(o.x, o.y); p.y = pk2(o.z, o.w); *(u32x2*)(xn + off + bj * HALF + n * 16) = p; }
;                     }
;                 if (xn) { q += __shfl_xor(q, 16); q += __shfl_xor(q, 32); if (fq == 0) (void)__hip_atomic_fetch_add(ss + row, q, __ATOMIC_RELAXED, __HIP_MEMORY_SCOPE_AGENT); }
;             }
;     }
	v_pk_add_f32 v[58:59], v[58:59], v[158:159]
	v_pk_add_f32 v[56:57], v[56:57], v[156:157]
	global_store_dwordx4 v[202:203], v[56:59], off
	v_pk_mul_f32 v[208:209], v[64:65], v[56:57]
	v_pk_mul_f32 v[210:211], v[66:67], v[58:59]
	v_mul_f32_e32 v219, v56, v56
	v_add_u32_e32 v208, 0x8000, v208
	v_add_u32_e32 v209, 0x8000, v209
	v_add_u32_e32 v210, 0x8000, v210
	v_add_u32_e32 v211, 0x8000, v211
	v_fmac_f32_e32 v219, v57, v57
	v_fmac_f32_e32 v219, v58, v58
	v_fmac_f32_e32 v219, v59, v59
	v_perm_b32 v206, v209, v208, s58
	v_perm_b32 v207, v211, v210, s58
	global_store_dwordx2 v[186:187], v[206:207], off
	v_pk_add_f32 v[50:51], v[50:51], v[162:163]
	v_pk_add_f32 v[48:49], v[48:49], v[160:161]
	global_store_dwordx4 v[202:203], v[48:51], off offset:512
	v_pk_mul_f32 v[212:213], v[72:73], v[48:49]
	v_pk_mul_f32 v[214:215], v[74:75], v[50:51]
	v_fmac_f32_e32 v219, v48, v48
	v_add_u32_e32 v212, 0x8000, v212
	v_add_u32_e32 v213, 0x8000, v213
	v_add_u32_e32 v214, 0x8000, v214
	v_add_u32_e32 v215, 0x8000, v215
	v_fmac_f32_e32 v219, v49, v49
	v_fmac_f32_e32 v219, v50, v50
	v_fmac_f32_e32 v219, v51, v51
	v_perm_b32 v216, v213, v212, s58
	v_perm_b32 v217, v215, v214, s58
	global_store_dwordx2 v[186:187], v[216:217], off offset:256
	v_pk_add_f32 v[62:63], v[62:63], v[178:179]
	v_pk_add_f32 v[60:61], v[60:61], v[176:177]
	global_store_dwordx4 v[204:205], v[60:63], off
	v_pk_mul_f32 v[208:209], v[76:77], v[60:61]
	v_pk_mul_f32 v[210:211], v[78:79], v[62:63]
	v_mul_f32_e32 v224, v60, v60
	v_add_u32_e32 v208, 0x8000, v208
	v_add_u32_e32 v209, 0x8000, v209
	v_add_u32_e32 v210, 0x8000, v210
	v_add_u32_e32 v211, 0x8000, v211
	v_fmac_f32_e32 v224, v61, v61
	v_fmac_f32_e32 v224, v62, v62
	v_fmac_f32_e32 v224, v63, v63
	v_perm_b32 v206, v209, v208, s58
	v_perm_b32 v207, v211, v210, s58
	global_store_dwordx2 v[188:189], v[206:207], off
	v_pk_add_f32 v[54:55], v[54:55], v[182:183]
	v_pk_add_f32 v[52:53], v[52:53], v[180:181]
	global_store_dwordx4 v[204:205], v[52:55], off offset:512
	v_pk_mul_f32 v[212:213], v[84:85], v[52:53]
	v_pk_mul_f32 v[214:215], v[86:87], v[54:55]
	v_fmac_f32_e32 v224, v52, v52
	v_add_u32_e32 v212, 0x8000, v212
	v_add_u32_e32 v213, 0x8000, v213
	v_add_u32_e32 v214, 0x8000, v214
	v_add_u32_e32 v215, 0x8000, v215
	v_fmac_f32_e32 v224, v53, v53
	v_fmac_f32_e32 v224, v54, v54
	v_fmac_f32_e32 v224, v55, v55
	v_perm_b32 v216, v213, v212, s58
	v_perm_b32 v217, v215, v214, s58
	global_store_dwordx2 v[188:189], v[216:217], off offset:256
	s_nop 1
	v_mov_b32_dpp v173, v219 row_ror:8 row_mask:0xf bank_mask:0xf
	v_mov_b32_dpp v218, v224 row_ror:8 row_mask:0xf bank_mask:0xf
	v_add_f32_e32 v219, v219, v173
	v_add_f32_e32 v224, v224, v218
	v_cndmask_b32_e64 v219, v224, v219, s[34:35]
	s_nop 0
	ds_bpermute_b32 v173, v225, v219
	global_load_dwordx4 v[156:159], v[174:175], off
	global_load_dwordx4 v[160:163], v[174:175], off offset:512
	global_load_dwordx4 v[176:179], v[184:185], off
	global_load_dwordx4 v[180:183], v[184:185], off offset:512
	s_mov_b64 vcc, 0x20000
	v_lshl_add_u64 v[174:175], v[174:175], 0, vcc
	v_lshl_add_u64 v[184:185], v[184:185], 0, vcc
	s_mov_b64 vcc, 0x20000
	v_lshl_add_u64 v[202:203], v[202:203], 0, vcc
	v_lshl_add_u64 v[204:205], v[204:205], 0, vcc
	s_mov_b64 vcc, 0x10000
	v_lshl_add_u64 v[186:187], v[186:187], 0, vcc
	v_lshl_add_u64 v[188:189], v[188:189], 0, vcc
	s_waitcnt lgkmcnt(0)
	v_add_f32_e32 v219, v219, v173
	s_nop 0
	ds_bpermute_b32 v218, v226, v219
	s_waitcnt lgkmcnt(0)
	v_add_f32_e32 v219, v219, v218
	s_mov_b64 exec, s[0:1]
	global_atomic_add_f32 v[190:191], v219, off
	s_mov_b64 exec, -1
	s_mov_b64 vcc, 64
	v_lshl_add_u64 v[190:191], v[190:191], 0, vcc
	v_mov_b32_dpp v220, v40 row_ror:8 row_mask:0xf bank_mask:0xf
	v_mov_b32_dpp v221, v41 row_ror:8 row_mask:0xf bank_mask:0xf
	v_mov_b32_dpp v222, v42 row_ror:8 row_mask:0xf bank_mask:0xf
	v_mov_b32_dpp v223, v43 row_ror:8 row_mask:0xf bank_mask:0xf
	v_cndmask_b32_e64 v40, v220, v44, s[34:35]
	v_cndmask_b32_e64 v41, v221, v45, s[34:35]
	v_cndmask_b32_e64 v42, v222, v46, s[34:35]
	v_cndmask_b32_e64 v43, v223, v47, s[34:35]
	v_cndmask_b32_e64 v44, v44, v220, s[34:35]
	v_cndmask_b32_e64 v45, v45, v221, s[34:35]
	v_cndmask_b32_e64 v46, v46, v222, s[34:35]
	v_cndmask_b32_e64 v47, v47, v223, s[34:35]
	v_mov_b32_dpp v220, v32 row_ror:8 row_mask:0xf bank_mask:0xf
	v_mov_b32_dpp v221, v33 row_ror:8 row_mask:0xf bank_mask:0xf
	v_mov_b32_dpp v222, v34 row_ror:8 row_mask:0xf bank_mask:0xf
	v_mov_b32_dpp v223, v35 row_ror:8 row_mask:0xf bank_mask:0xf
	v_cndmask_b32_e64 v32, v220, v36, s[34:35]
	v_cndmask_b32_e64 v33, v221, v37, s[34:35]
	v_cndmask_b32_e64 v34, v222, v38, s[34:35]
	v_cndmask_b32_e64 v35, v223, v39, s[34:35]
	v_cndmask_b32_e64 v36, v36, v220, s[34:35]
	v_cndmask_b32_e64 v37, v37, v221, s[34:35]
	v_cndmask_b32_e64 v38, v38, v222, s[34:35]
	v_cndmask_b32_e64 v39, v39, v223, s[34:35]
	s_waitcnt vmcnt(1)
;     __device__ __forceinline__ void operator()(const f32x4 (&acc)[2][2][4][2], const Unit& u, int wr, int wc, int fr, int fq) const {
;         const int row0 = u.pm * BM + wr * 64 + fr, col0 = u.pn * BM + wc * 32 + 4 * fq;
;         const float* rbase = (u.pm * BM < SEQ_P) ? resA : (resB - (size_t)SEQ_P * ldc);
;         f32x4 wv[2][2];
;         if (xn) {
; #pragma unroll
;             for (int bj = 0; bj < 2; ++bj)
; #pragma unroll
;                 for (int n = 0; n < 2; ++n) wv[bj][n] = *(const f32x4*)(wn + col0 + bj * HALF + n * 16);
;         }
; #pragma unroll
;         for (int ai = 0; ai < 2; ++ai)
; #pragma unroll
;             for (int m = 0; m < 4; ++m) {
;                 const int row = row0 + ai * HALF + m * 16;
;                 const size_t off = (size_t)row * ldc + col0;
;                 float q = 0.f;
; #pragma unroll
;                 for (int bj = 0; bj < 2; ++bj)
; #pragma unroll
;                     for (int n = 0; n < 2; ++n) {
;                         const f32x4 rv = *(const f32x4*)(rbase + off + bj * HALF + n * 16);
;                         const f32x4 v = rv + acc[ai][bj][m][n] * scale;
;                         if (out) *(f32x4*)(out + off + bj * HALF + n * 16) = v;
;                         if (xn) { q += (v.x * v.x + v.y * v.y) + (v.z * v.z + v.w * v.w); const f32x4 o = v * wv[bj][n];
;                             u32x2 p; p.x = pk2(o.x, o.y); p.y = pk2(o.z, o.w); *(u32x2*)(xn + off + bj * HALF + n * 16) = p; }
;                     }
;                 if (xn) { q += __shfl_xor(q, 16); q += __shfl_xor(q, 32); if (fq == 0) (void)__hip_atomic_fetch_add(ss + row, q, __ATOMIC_RELAXED, __HIP_MEMORY_SCOPE_AGENT); }
;             }
;     }
	v_pk_add_f32 v[42:43], v[42:43], v[158:159]
	v_pk_add_f32 v[40:41], v[40:41], v[156:157]
	global_store_dwordx4 v[202:203], v[40:43], off
	v_pk_mul_f32 v[208:209], v[64:65], v[40:41]
	v_pk_mul_f32 v[210:211], v[66:67], v[42:43]
	v_mul_f32_e32 v219, v40, v40
	v_add_u32_e32 v208, 0x8000, v208
	v_add_u32_e32 v209, 0x8000, v209
	v_add_u32_e32 v210, 0x8000, v210
	v_add_u32_e32 v211, 0x8000, v211
	v_fmac_f32_e32 v219, v41, v41
	v_fmac_f32_e32 v219, v42, v42
	v_fmac_f32_e32 v219, v43, v43
	v_perm_b32 v206, v209, v208, s58
	v_perm_b32 v207, v211, v210, s58
	global_store_dwordx2 v[186:187], v[206:207], off
	v_pk_add_f32 v[34:35], v[34:35], v[162:163]
	v_pk_add_f32 v[32:33], v[32:33], v[160:161]
	global_store_dwordx4 v[202:203], v[32:35], off offset:512
	v_pk_mul_f32 v[212:213], v[72:73], v[32:33]
	v_pk_mul_f32 v[214:215], v[74:75], v[34:35]
	v_fmac_f32_e32 v219, v32, v32
	v_add_u32_e32 v212, 0x8000, v212
	v_add_u32_e32 v213, 0x8000, v213
	v_add_u32_e32 v214, 0x8000, v214
	v_add_u32_e32 v215, 0x8000, v215
	v_fmac_f32_e32 v219, v33, v33
	v_fmac_f32_e32 v219, v34, v34
	v_fmac_f32_e32 v219, v35, v35
	v_perm_b32 v216, v213, v212, s58
	v_perm_b32 v217, v215, v214, s58
	global_store_dwordx2 v[186:187], v[216:217], off offset:256
	v_pk_add_f32 v[46:47], v[46:47], v[178:179]
	v_pk_add_f32 v[44:45], v[44:45], v[176:177]
	global_store_dwordx4 v[204:205], v[44:47], off
	v_pk_mul_f32 v[208:209], v[76:77], v[44:45]
	v_pk_mul_f32 v[210:211], v[78:79], v[46:47]
	v_mul_f32_e32 v224, v44, v44
	v_add_u32_e32 v208, 0x8000, v208
	v_add_u32_e32 v209, 0x8000, v209
	v_add_u32_e32 v210, 0x8000, v210
	v_add_u32_e32 v211, 0x8000, v211
	v_fmac_f32_e32 v224, v45, v45
	v_fmac_f32_e32 v224, v46, v46
	v_fmac_f32_e32 v224, v47, v47
	v_perm_b32 v206, v209, v208, s58
	v_perm_b32 v207, v211, v210, s58
	global_store_dwordx2 v[188:189], v[206:207], off
	v_pk_add_f32 v[38:39], v[38:39], v[182:183]
	v_pk_add_f32 v[36:37], v[36:37], v[180:181]
	global_store_dwordx4 v[204:205], v[36:39], off offset:512
	v_pk_mul_f32 v[212:213], v[84:85], v[36:37]
	v_pk_mul_f32 v[214:215], v[86:87], v[38:39]
	v_fmac_f32_e32 v224, v36, v36
	v_add_u32_e32 v212, 0x8000, v212
	v_add_u32_e32 v213, 0x8000, v213
	v_add_u32_e32 v214, 0x8000, v214
	v_add_u32_e32 v215, 0x8000, v215
	v_fmac_f32_e32 v224, v37, v37
	v_fmac_f32_e32 v224, v38, v38
	v_fmac_f32_e32 v224, v39, v39
	v_perm_b32 v216, v213, v212, s58
	v_perm_b32 v217, v215, v214, s58
	global_store_dwordx2 v[188:189], v[216:217], off offset:256
	s_nop 1
	v_mov_b32_dpp v173, v219 row_ror:8 row_mask:0xf bank_mask:0xf
	v_mov_b32_dpp v218, v224 row_ror:8 row_mask:0xf bank_mask:0xf
	v_add_f32_e32 v219, v219, v173
	v_add_f32_e32 v224, v224, v218
	v_cndmask_b32_e64 v219, v224, v219, s[34:35]
	s_nop 0
	ds_bpermute_b32 v173, v225, v219
	global_load_dwordx4 v[156:159], v[174:175], off
	global_load_dwordx4 v[160:163], v[174:175], off offset:512
	global_load_dwordx4 v[176:179], v[184:185], off
	global_load_dwordx4 v[180:183], v[184:185], off offset:512
	s_mov_b64 vcc, 0x20000
	v_lshl_add_u64 v[174:175], v[174:175], 0, vcc
	v_lshl_add_u64 v[184:185], v[184:185], 0, vcc
	s_mov_b64 vcc, 0x20000
	v_lshl_add_u64 v[202:203], v[202:203], 0, vcc
	v_lshl_add_u64 v[204:205], v[204:205], 0, vcc
	s_mov_b64 vcc, 0x10000
	v_lshl_add_u64 v[186:187], v[186:187], 0, vcc
	v_lshl_add_u64 v[188:189], v[188:189], 0, vcc
	s_waitcnt lgkmcnt(0)
	v_add_f32_e32 v219, v219, v173
	s_nop 0
	ds_bpermute_b32 v218, v226, v219
	s_waitcnt lgkmcnt(0)
	v_add_f32_e32 v219, v219, v218
	s_mov_b64 exec, s[0:1]
	global_atomic_add_f32 v[190:191], v219, off
	s_mov_b64 exec, -1
	s_mov_b64 vcc, 64
	v_lshl_add_u64 v[190:191], v[190:191], 0, vcc
	v_mov_b32_dpp v220, v24 row_ror:8 row_mask:0xf bank_mask:0xf
	v_mov_b32_dpp v221, v25 row_ror:8 row_mask:0xf bank_mask:0xf
	v_mov_b32_dpp v222, v26 row_ror:8 row_mask:0xf bank_mask:0xf
	v_mov_b32_dpp v223, v27 row_ror:8 row_mask:0xf bank_mask:0xf
	v_cndmask_b32_e64 v24, v220, v28, s[34:35]
	v_cndmask_b32_e64 v25, v221, v29, s[34:35]
	v_cndmask_b32_e64 v26, v222, v30, s[34:35]
	v_cndmask_b32_e64 v27, v223, v31, s[34:35]
	v_cndmask_b32_e64 v28, v28, v220, s[34:35]
	v_cndmask_b32_e64 v29, v29, v221, s[34:35]
	v_cndmask_b32_e64 v30, v30, v222, s[34:35]
	v_cndmask_b32_e64 v31, v31, v223, s[34:35]
	v_mov_b32_dpp v220, v16 row_ror:8 row_mask:0xf bank_mask:0xf
	v_mov_b32_dpp v221, v17 row_ror:8 row_mask:0xf bank_mask:0xf
	v_mov_b32_dpp v222, v18 row_ror:8 row_mask:0xf bank_mask:0xf
	v_mov_b32_dpp v223, v19 row_ror:8 row_mask:0xf bank_mask:0xf
	v_cndmask_b32_e64 v16, v220, v20, s[34:35]
	v_cndmask_b32_e64 v17, v221, v21, s[34:35]
	v_cndmask_b32_e64 v18, v222, v22, s[34:35]
	v_cndmask_b32_e64 v19, v223, v23, s[34:35]
	v_cndmask_b32_e64 v20, v20, v220, s[34:35]
	v_cndmask_b32_e64 v21, v21, v221, s[34:35]
	v_cndmask_b32_e64 v22, v22, v222, s[34:35]
	v_cndmask_b32_e64 v23, v23, v223, s[34:35]
	s_waitcnt vmcnt(1)
;     __device__ __forceinline__ void operator()(const f32x4 (&acc)[2][2][4][2], const Unit& u, int wr, int wc, int fr, int fq) const {
;         const int row0 = u.pm * BM + wr * 64 + fr, col0 = u.pn * BM + wc * 32 + 4 * fq;
;         const float* rbase = (u.pm * BM < SEQ_P) ? resA : (resB - (size_t)SEQ_P * ldc);
;         f32x4 wv[2][2];
;         if (xn) {
; #pragma unroll
;             for (int bj = 0; bj < 2; ++bj)
; #pragma unroll
;                 for (int n = 0; n < 2; ++n) wv[bj][n] = *(const f32x4*)(wn + col0 + bj * HALF + n * 16);
;         }
; #pragma unroll
;         for (int ai = 0; ai < 2; ++ai)
; #pragma unroll
;             for (int m = 0; m < 4; ++m) {
;                 const int row = row0 + ai * HALF + m * 16;
;                 const size_t off = (size_t)row * ldc + col0;
;                 float q = 0.f;
; #pragma unroll
;                 for (int bj = 0; bj < 2; ++bj)
; #pragma unroll
;                     for (int n = 0; n < 2; ++n) {
;                         const f32x4 rv = *(const f32x4*)(rbase + off + bj * HALF + n * 16);
;                         const f32x4 v = rv + acc[ai][bj][m][n] * scale;
;                         if (out) *(f32x4*)(out + off + bj * HALF + n * 16) = v;
;                         if (xn) { q += (v.x * v.x + v.y * v.y) + (v.z * v.z + v.w * v.w); const f32x4 o = v * wv[bj][n];
;                             u32x2 p; p.x = pk2(o.x, o.y); p.y = pk2(o.z, o.w); *(u32x2*)(xn + off + bj * HALF + n * 16) = p; }
;                     }
;                 if (xn) { q += __shfl_xor(q, 16); q += __shfl_xor(q, 32); if (fq == 0) (void)__hip_atomic_fetch_add(ss + row, q, __ATOMIC_RELAXED, __HIP_MEMORY_SCOPE_AGENT); }
;             }
;     }
	v_pk_add_f32 v[26:27], v[26:27], v[158:159]
	v_pk_add_f32 v[24:25], v[24:25], v[156:157]
	global_store_dwordx4 v[202:203], v[24:27], off
	v_pk_mul_f32 v[208:209], v[64:65], v[24:25]
	v_pk_mul_f32 v[210:211], v[66:67], v[26:27]
	v_mul_f32_e32 v219, v24, v24
	v_add_u32_e32 v208, 0x8000, v208
	v_add_u32_e32 v209, 0x8000, v209
	v_add_u32_e32 v210, 0x8000, v210
	v_add_u32_e32 v211, 0x8000, v211
	v_fmac_f32_e32 v219, v25, v25
	v_fmac_f32_e32 v219, v26, v26
	v_fmac_f32_e32 v219, v27, v27
	v_perm_b32 v206, v209, v208, s58
	v_perm_b32 v207, v211, v210, s58
	global_store_dwordx2 v[186:187], v[206:207], off
	v_pk_add_f32 v[18:19], v[18:19], v[162:163]
	v_pk_add_f32 v[16:17], v[16:17], v[160:161]
	global_store_dwordx4 v[202:203], v[16:19], off offset:512
	v_pk_mul_f32 v[212:213], v[72:73], v[16:17]
	v_pk_mul_f32 v[214:215], v[74:75], v[18:19]
	v_fmac_f32_e32 v219, v16, v16
	v_add_u32_e32 v212, 0x8000, v212
	v_add_u32_e32 v213, 0x8000, v213
	v_add_u32_e32 v214, 0x8000, v214
	v_add_u32_e32 v215, 0x8000, v215
	v_fmac_f32_e32 v219, v17, v17
	v_fmac_f32_e32 v219, v18, v18
	v_fmac_f32_e32 v219, v19, v19
	v_perm_b32 v216, v213, v212, s58
	v_perm_b32 v217, v215, v214, s58
	global_store_dwordx2 v[186:187], v[216:217], off offset:256
	v_pk_add_f32 v[30:31], v[30:31], v[178:179]
	v_pk_add_f32 v[28:29], v[28:29], v[176:177]
	global_store_dwordx4 v[204:205], v[28:31], off
	v_pk_mul_f32 v[208:209], v[76:77], v[28:29]
	v_pk_mul_f32 v[210:211], v[78:79], v[30:31]
	v_mul_f32_e32 v224, v28, v28
	v_add_u32_e32 v208, 0x8000, v208
	v_add_u32_e32 v209, 0x8000, v209
	v_add_u32_e32 v210, 0x8000, v210
	v_add_u32_e32 v211, 0x8000, v211
	v_fmac_f32_e32 v224, v29, v29
	v_fmac_f32_e32 v224, v30, v30
	v_fmac_f32_e32 v224, v31, v31
	v_perm_b32 v206, v209, v208, s58
	v_perm_b32 v207, v211, v210, s58
	global_store_dwordx2 v[188:189], v[206:207], off
	v_pk_add_f32 v[22:23], v[22:23], v[182:183]
	v_pk_add_f32 v[20:21], v[20:21], v[180:181]
	global_store_dwordx4 v[204:205], v[20:23], off offset:512
	v_pk_mul_f32 v[212:213], v[84:85], v[20:21]
	v_pk_mul_f32 v[214:215], v[86:87], v[22:23]
	v_fmac_f32_e32 v224, v20, v20
	v_add_u32_e32 v212, 0x8000, v212
	v_add_u32_e32 v213, 0x8000, v213
	v_add_u32_e32 v214, 0x8000, v214
	v_add_u32_e32 v215, 0x8000, v215
	v_fmac_f32_e32 v224, v21, v21
	v_fmac_f32_e32 v224, v22, v22
	v_fmac_f32_e32 v224, v23, v23
	v_perm_b32 v216, v213, v212, s58
	v_perm_b32 v217, v215, v214, s58
	global_store_dwordx2 v[188:189], v[216:217], off offset:256
	s_nop 1
	v_mov_b32_dpp v173, v219 row_ror:8 row_mask:0xf bank_mask:0xf
	v_mov_b32_dpp v218, v224 row_ror:8 row_mask:0xf bank_mask:0xf
	v_add_f32_e32 v219, v219, v173
	v_add_f32_e32 v224, v224, v218
	v_cndmask_b32_e64 v219, v224, v219, s[34:35]
	s_nop 0
	ds_bpermute_b32 v173, v225, v219
	global_load_dwordx4 v[156:159], v[174:175], off
	global_load_dwordx4 v[160:163], v[174:175], off offset:512
	global_load_dwordx4 v[176:179], v[184:185], off
	global_load_dwordx4 v[180:183], v[184:185], off offset:512
	s_mov_b64 vcc, 0x20000
	v_lshl_add_u64 v[202:203], v[202:203], 0, vcc
	v_lshl_add_u64 v[204:205], v[204:205], 0, vcc
	s_mov_b64 vcc, 0x10000
	v_lshl_add_u64 v[186:187], v[186:187], 0, vcc
	v_lshl_add_u64 v[188:189], v[188:189], 0, vcc
	s_waitcnt lgkmcnt(0)
	v_add_f32_e32 v219, v219, v173
	s_nop 0
	ds_bpermute_b32 v218, v226, v219
	s_waitcnt lgkmcnt(0)
;     __device__ __forceinline__ void operator()(const f32x4 (&acc)[2][2][4][2], const Unit& u, int wr, int wc, int fr, int fq) const {
;         const int row0 = u.pm * BM + wr * 64 + fr, col0 = u.pn * BM + wc * 32 + 4 * fq;
;         const float* rbase = (u.pm * BM < SEQ_P) ? resA : (resB - (size_t)SEQ_P * ldc);
;         f32x4 wv[2][2];
;         if (xn) {
; #pragma unroll
;             for (int bj = 0; bj < 2; ++bj)
; #pragma unroll
;                 for (int n = 0; n < 2; ++n) wv[bj][n] = *(const f32x4*)(wn + col0 + bj * HALF + n * 16);
;         }
; #pragma unroll
;         for (int ai = 0; ai < 2; ++ai)
; #pragma unroll
;             for (int m = 0; m < 4; ++m) {
;                 const int row = row0 + ai * HALF + m * 16;
;                 const size_t off = (size_t)row * ldc + col0;
;                 float q = 0.f;
; #pragma unroll
;                 for (int bj = 0; bj < 2; ++bj)
; #pragma unroll
;                     for (int n = 0; n < 2; ++n) {
;                         const f32x4 rv = *(const f32x4*)(rbase + off + bj * HALF + n * 16);
;                         const f32x4 v = rv + acc[ai][bj][m][n] * scale;
;                         if (out) *(f32x4*)(out + off + bj * HALF + n * 16) = v;
;                         if (xn) { q += (v.x * v.x + v.y * v.y) + (v.z * v.z + v.w * v.w); const f32x4 o = v * wv[bj][n];
;                             u32x2 p; p.x = pk2(o.x, o.y); p.y = pk2(o.z, o.w); *(u32x2*)(xn + off + bj * HALF + n * 16) = p; }
;                     }
;                 if (xn) { q += __shfl_xor(q, 16); q += __shfl_xor(q, 32); if (fq == 0) (void)__hip_atomic_fetch_add(ss + row, q, __ATOMIC_RELAXED, __HIP_MEMORY_SCOPE_AGENT); }
;             }
;     }
; template <class Epi, bool ALIGN_EPI>
; __device__ __forceinline__ void gemm_phase(LAS unsigned char* lds, const Gemm g, const StaticOrder& S, const Epi& E) {
;     ...
;         if constexpr (ALIGN_EPI) { if (wr == 0) PG8_BAR; }
;         E(acc, cur, wr, wc, fr, fq);
;         if (!has_next) break;
; #pragma unroll
;         for (int a = 0; a < 2; ++a)
; #pragma unroll
;             for (int b = 0; b < 2; ++b)
; #pragma unroll
;                 for (int m = 0; m < 4; ++m)
; #pragma unroll
;                     for (int n = 0; n < 2; ++n) acc[a][b][m][n] = (f32x4){0.f, 0.f, 0.f, 0.f};
;         cur = nxt; cA = nA; cB = nB; ++ui;
;         if constexpr (ALIGN_EPI) { if (wr == 1) PG8_BAR; }
	v_add_f32_e32 v219, v219, v218
	s_mov_b64 exec, s[0:1]
	global_atomic_add_f32 v[190:191], v219, off
	s_mov_b64 exec, -1
	s_mov_b64 vcc, 64
	v_lshl_add_u64 v[190:191], v[190:191], 0, vcc
	v_mov_b32_dpp v220, v8 row_ror:8 row_mask:0xf bank_mask:0xf
	v_mov_b32_dpp v221, v9 row_ror:8 row_mask:0xf bank_mask:0xf
	v_mov_b32_dpp v222, v10 row_ror:8 row_mask:0xf bank_mask:0xf
	v_mov_b32_dpp v223, v11 row_ror:8 row_mask:0xf bank_mask:0xf
	v_cndmask_b32_e64 v8, v220, v12, s[34:35]
	v_cndmask_b32_e64 v9, v221, v13, s[34:35]
	v_cndmask_b32_e64 v10, v222, v14, s[34:35]
	v_cndmask_b32_e64 v11, v223, v15, s[34:35]
	v_cndmask_b32_e64 v12, v12, v220, s[34:35]
	v_cndmask_b32_e64 v13, v13, v221, s[34:35]
	v_cndmask_b32_e64 v14, v14, v222, s[34:35]
	v_cndmask_b32_e64 v15, v15, v223, s[34:35]
	v_mov_b32_dpp v220, v0 row_ror:8 row_mask:0xf bank_mask:0xf
	v_mov_b32_dpp v221, v1 row_ror:8 row_mask:0xf bank_mask:0xf
	v_mov_b32_dpp v222, v2 row_ror:8 row_mask:0xf bank_mask:0xf
	v_mov_b32_dpp v223, v3 row_ror:8 row_mask:0xf bank_mask:0xf
	v_cndmask_b32_e64 v0, v220, v4, s[34:35]
	v_cndmask_b32_e64 v1, v221, v5, s[34:35]
	v_cndmask_b32_e64 v2, v222, v6, s[34:35]
	v_cndmask_b32_e64 v3, v223, v7, s[34:35]
	v_cndmask_b32_e64 v4, v4, v220, s[34:35]
	v_cndmask_b32_e64 v5, v5, v221, s[34:35]
	v_cndmask_b32_e64 v6, v6, v222, s[34:35]
	v_cndmask_b32_e64 v7, v7, v223, s[34:35]
	s_waitcnt vmcnt(1)
	v_pk_add_f32 v[10:11], v[10:11], v[158:159]
	v_pk_add_f32 v[8:9], v[8:9], v[156:157]
	global_store_dwordx4 v[202:203], v[8:11], off
	v_pk_mul_f32 v[208:209], v[64:65], v[8:9]
	v_pk_mul_f32 v[210:211], v[66:67], v[10:11]
	v_mul_f32_e32 v219, v8, v8
	v_add_u32_e32 v208, 0x8000, v208
	v_add_u32_e32 v209, 0x8000, v209
	v_add_u32_e32 v210, 0x8000, v210
	v_add_u32_e32 v211, 0x8000, v211
	v_fmac_f32_e32 v219, v9, v9
	v_fmac_f32_e32 v219, v10, v10
	v_fmac_f32_e32 v219, v11, v11
	v_perm_b32 v206, v209, v208, s58
	v_perm_b32 v207, v211, v210, s58
	global_store_dwordx2 v[186:187], v[206:207], off
	v_pk_add_f32 v[2:3], v[2:3], v[162:163]
	v_pk_add_f32 v[0:1], v[0:1], v[160:161]
	global_store_dwordx4 v[202:203], v[0:3], off offset:512
	v_pk_mul_f32 v[212:213], v[72:73], v[0:1]
	v_pk_mul_f32 v[214:215], v[74:75], v[2:3]
	v_fmac_f32_e32 v219, v0, v0
	v_add_u32_e32 v212, 0x8000, v212
	v_add_u32_e32 v213, 0x8000, v213
	v_add_u32_e32 v214, 0x8000, v214
	v_add_u32_e32 v215, 0x8000, v215
	v_fmac_f32_e32 v219, v1, v1
	v_fmac_f32_e32 v219, v2, v2
	v_fmac_f32_e32 v219, v3, v3
	v_perm_b32 v216, v213, v212, s58
	v_perm_b32 v217, v215, v214, s58
	global_store_dwordx2 v[186:187], v[216:217], off offset:256
	v_pk_add_f32 v[14:15], v[14:15], v[178:179]
	v_pk_add_f32 v[12:13], v[12:13], v[176:177]
	global_store_dwordx4 v[204:205], v[12:15], off
	v_pk_mul_f32 v[208:209], v[76:77], v[12:13]
	v_pk_mul_f32 v[210:211], v[78:79], v[14:15]
	v_mul_f32_e32 v224, v12, v12
	v_add_u32_e32 v208, 0x8000, v208
	v_add_u32_e32 v209, 0x8000, v209
	v_add_u32_e32 v210, 0x8000, v210
	v_add_u32_e32 v211, 0x8000, v211
	v_fmac_f32_e32 v224, v13, v13
	v_fmac_f32_e32 v224, v14, v14
	v_fmac_f32_e32 v224, v15, v15
	v_perm_b32 v206, v209, v208, s58
	v_perm_b32 v207, v211, v210, s58
	global_store_dwordx2 v[188:189], v[206:207], off
	v_pk_add_f32 v[6:7], v[6:7], v[182:183]
	v_pk_add_f32 v[4:5], v[4:5], v[180:181]
	global_store_dwordx4 v[204:205], v[4:7], off offset:512
	v_pk_mul_f32 v[212:213], v[84:85], v[4:5]
	v_pk_mul_f32 v[214:215], v[86:87], v[6:7]
	v_fmac_f32_e32 v224, v4, v4
	v_add_u32_e32 v212, 0x8000, v212
	v_add_u32_e32 v213, 0x8000, v213
	v_add_u32_e32 v214, 0x8000, v214
	v_add_u32_e32 v215, 0x8000, v215
	v_fmac_f32_e32 v224, v5, v5
	v_fmac_f32_e32 v224, v6, v6
	v_fmac_f32_e32 v224, v7, v7
	v_perm_b32 v216, v213, v212, s58
	v_perm_b32 v217, v215, v214, s58
	global_store_dwordx2 v[188:189], v[216:217], off offset:256
	s_nop 1
	v_mov_b32_dpp v173, v219 row_ror:8 row_mask:0xf bank_mask:0xf
	v_mov_b32_dpp v218, v224 row_ror:8 row_mask:0xf bank_mask:0xf
	v_add_f32_e32 v219, v219, v173
	v_add_f32_e32 v224, v224, v218
	v_cndmask_b32_e64 v219, v224, v219, s[34:35]
	s_nop 0
	ds_bpermute_b32 v173, v225, v219
	s_waitcnt lgkmcnt(0)
	v_add_f32_e32 v219, v219, v173
	s_nop 0
	ds_bpermute_b32 v218, v226, v219
	s_waitcnt lgkmcnt(0)
	v_add_f32_e32 v219, v219, v218
	s_mov_b64 exec, s[0:1]
	global_atomic_add_f32 v[190:191], v219, off
	s_mov_b64 exec, -1
	s_andn2_b64 vcc, exec, s[6:7]
	s_mov_b64 s[4:5], -1
	s_cbranch_vccnz .LBB0_1078
	s_andn2_b64 vcc, exec, s[12:13]
	s_cbranch_vccnz .LBB0_1077
	s_barrier
	s_branch .LBB0_1077

;     __device__ __forceinline__ void operator()(const f32x4 (&acc)[2][2][4][2], const Unit& u, int wr, int wc, int fr, int fq) const {
;         const int row0 = u.pm * BM + wr * 64 + fr, col0 = u.pn * BM + wc * 32 + 4 * fq;
;         const float* rbase = (u.pm * BM < SEQ_P) ? resA : (resB - (size_t)SEQ_P * ldc);
;         f32x4 wv[2][2];
;         if (xn) {
; #pragma unroll
;             for (int bj = 0; bj < 2; ++bj)
; #pragma unroll
;                 for (int n = 0; n < 2; ++n) wv[bj][n] = *(const f32x4*)(wn + col0 + bj * HALF + n * 16);
;         }
; #pragma unroll
;         for (int ai = 0; ai < 2; ++ai)
; #pragma unroll
;             for (int m = 0; m < 4; ++m) {
;                 const int row = row0 + ai * HALF + m * 16;
;                 const size_t off = (size_t)row * ldc + col0;
;                 float q = 0.f;
; #pragma unroll
;                 for (int bj = 0; bj < 2; ++bj)
; #pragma unroll
;                     for (int n = 0; n < 2; ++n) {
;                         const f32x4 rv = *(const f32x4*)(rbase + off + bj * HALF + n * 16);
;                         const f32x4 v = rv + acc[ai][bj][m][n] * scale;
;                         if (out) *(f32x4*)(out + off + bj * HALF + n * 16) = v;
;                         if (xn) { q += (v.x * v.x + v.y * v.y) + (v.z * v.z + v.w * v.w); const f32x4 o = v * wv[bj][n];
;                             u32x2 p; p.x = pk2(o.x, o.y); p.y = pk2(o.z, o.w); *(u32x2*)(xn + off + bj * HALF + n * 16) = p; }
;                     }
;                 if (xn) { q += __shfl_xor(q, 16); q += __shfl_xor(q, 32); if (fq == 0) (void)__hip_atomic_fetch_add(ss + row, q, __ATOMIC_RELAXED, __HIP_MEMORY_SCOPE_AGENT); }
.LBB0_1382:
	v_lshl_add_u32 v194, s54, 8, v160
	v_lshl_or_b32 v196, s53, 8, v162
	v_and_b32_e32 v222, 8, v167
	v_mov_b32_e32 v195, 0
	v_cmp_eq_u32_e64 s[24:25], 0, v222
	v_lshlrev_b32_e32 v218, 1, v222
	v_add_u32_e32 v198, v196, v218
	v_sub_u32_e32 v219, 16, v218
	v_add_u32_e32 v219, v196, v219
	v_mov_b32_e32 v196, v198
	v_mov_b32_e32 v198, v219
	v_mov_b32_e32 v197, 0
	v_mov_b32_e32 v199, 0
	v_sub_u32_e32 v192, v194, v222
	v_mov_b32_e32 v193, 0
	v_lshlrev_b64 v[190:191], 11, v[192:193]
	v_add_u32_e32 v192, 8, v192
	v_lshlrev_b64 v[192:193], 11, v[192:193]
	v_lshl_add_u64 v[190:191], v[190:191], 0, v[196:197]
	v_lshl_add_u64 v[192:193], v[192:193], 0, v[198:199]
	v_lshl_add_u64 v[180:181], v[190:191], 2, s[8:9]
	v_lshl_add_u64 v[182:183], v[192:193], 2, s[8:9]
	v_lshl_add_u64 v[184:185], v[196:197], 2, s[10:11]
	v_lshl_add_u64 v[186:187], v[198:199], 2, s[10:11]
	global_load_dwordx4 v[72:75], v[184:185], off
	global_load_dwordx4 v[84:87], v[184:185], off offset:512
	global_load_dwordx4 v[88:91], v[186:187], off
	global_load_dwordx4 v[96:99], v[186:187], off offset:512
	global_load_dwordx4 v[156:159], v[180:181], off
	global_load_dwordx4 v[168:171], v[180:181], off offset:512
	global_load_dwordx4 v[172:175], v[182:183], off
	global_load_dwordx4 v[176:179], v[182:183], off offset:512
	s_mov_b64 vcc, 0x20000
	v_lshl_add_u64 v[180:181], v[180:181], 0, vcc
	v_lshl_add_u64 v[182:183], v[182:183], 0, vcc
	v_lshl_add_u64 v[184:185], v[190:191], 1, s[14:15]
	v_lshl_add_u64 v[186:187], v[192:193], 1, s[14:15]
	v_lshl_add_u64 v[188:189], v[194:195], 2, s[16:17]
	v_xor_b32_e32 v220, 16, v167
	v_xor_b32_e32 v221, 32, v167
	v_lshlrev_b32_e32 v220, 2, v220
	v_lshlrev_b32_e32 v221, 2, v221
	v_mov_b32_dpp v212, v136 row_ror:8 row_mask:0xf bank_mask:0xf
	v_mov_b32_dpp v213, v137 row_ror:8 row_mask:0xf bank_mask:0xf
	v_mov_b32_dpp v214, v138 row_ror:8 row_mask:0xf bank_mask:0xf
	v_mov_b32_dpp v215, v139 row_ror:8 row_mask:0xf bank_mask:0xf
	v_cndmask_b32_e64 v136, v212, v140, s[24:25]
	v_cndmask_b32_e64 v137, v213, v141, s[24:25]
	v_cndmask_b32_e64 v138, v214, v142, s[24:25]
	v_cndmask_b32_e64 v139, v215, v143, s[24:25]
	v_cndmask_b32_e64 v140, v140, v212, s[24:25]
	v_cndmask_b32_e64 v141, v141, v213, s[24:25]
	v_cndmask_b32_e64 v142, v142, v214, s[24:25]
	v_cndmask_b32_e64 v143, v143, v215, s[24:25]
	v_mov_b32_dpp v212, v128 row_ror:8 row_mask:0xf bank_mask:0xf
	v_mov_b32_dpp v213, v129 row_ror:8 row_mask:0xf bank_mask:0xf
	v_mov_b32_dpp v214, v130 row_ror:8 row_mask:0xf bank_mask:0xf
	v_mov_b32_dpp v215, v131 row_ror:8 row_mask:0xf bank_mask:0xf
	v_cndmask_b32_e64 v128, v212, v132, s[24:25]
	v_cndmask_b32_e64 v129, v213, v133, s[24:25]
	v_cndmask_b32_e64 v130, v214, v134, s[24:25]
	v_cndmask_b32_e64 v131, v215, v135, s[24:25]
	v_cndmask_b32_e64 v132, v132, v212, s[24:25]
	v_cndmask_b32_e64 v133, v133, v213, s[24:25]
	v_cndmask_b32_e64 v134, v134, v214, s[24:25]
	v_cndmask_b32_e64 v135, v135, v215, s[24:25]
	s_waitcnt vmcnt(0)
	v_pk_fma_f32 v[138:139], v[138:139], 0.5, v[158:159] op_sel_hi:[1,0,1]
	v_pk_fma_f32 v[136:137], v[136:137], 0.5, v[156:157] op_sel_hi:[1,0,1]
	v_pk_mul_f32 v[200:201], v[72:73], v[136:137]
	v_pk_mul_f32 v[202:203], v[74:75], v[138:139]
	v_mul_f32_e32 v218, v136, v136
	v_add_u32_e32 v200, 0x8000, v200
	v_add_u32_e32 v201, 0x8000, v201
	v_add_u32_e32 v202, 0x8000, v202
	v_add_u32_e32 v203, 0x8000, v203
	v_fmac_f32_e32 v218, v137, v137
	v_fmac_f32_e32 v218, v138, v138
	v_fmac_f32_e32 v218, v139, v139
	v_perm_b32 v208, v201, v200, s50
	v_perm_b32 v209, v203, v202, s50
	global_store_dwordx2 v[184:185], v[208:209], off
	v_pk_fma_f32 v[130:131], v[130:131], 0.5, v[170:171] op_sel_hi:[1,0,1]
	v_pk_fma_f32 v[128:129], v[128:129], 0.5, v[168:169] op_sel_hi:[1,0,1]
	v_pk_mul_f32 v[204:205], v[84:85], v[128:129]
	v_pk_mul_f32 v[206:207], v[86:87], v[130:131]
	v_fmac_f32_e32 v218, v128, v128
	v_add_u32_e32 v204, 0x8000, v204
	v_add_u32_e32 v205, 0x8000, v205
	v_add_u32_e32 v206, 0x8000, v206
	v_add_u32_e32 v207, 0x8000, v207
	v_fmac_f32_e32 v218, v129, v129
	v_fmac_f32_e32 v218, v130, v130
	v_fmac_f32_e32 v218, v131, v131
	v_perm_b32 v210, v205, v204, s50
	v_perm_b32 v211, v207, v206, s50
	global_store_dwordx2 v[184:185], v[210:211], off offset:256
	v_pk_fma_f32 v[142:143], v[142:143], 0.5, v[174:175] op_sel_hi:[1,0,1]
	v_pk_fma_f32 v[140:141], v[140:141], 0.5, v[172:173] op_sel_hi:[1,0,1]
	v_pk_mul_f32 v[200:201], v[88:89], v[140:141]
	v_pk_mul_f32 v[202:203], v[90:91], v[142:143]
	v_mul_f32_e32 v219, v140, v140
	v_add_u32_e32 v200, 0x8000, v200
	v_add_u32_e32 v201, 0x8000, v201
	v_add_u32_e32 v202, 0x8000, v202
	v_add_u32_e32 v203, 0x8000, v203
	v_fmac_f32_e32 v219, v141, v141
	v_fmac_f32_e32 v219, v142, v142
	v_fmac_f32_e32 v219, v143, v143
	v_perm_b32 v208, v201, v200, s50
	v_perm_b32 v209, v203, v202, s50
	global_store_dwordx2 v[186:187], v[208:209], off
	v_pk_fma_f32 v[134:135], v[134:135], 0.5, v[178:179] op_sel_hi:[1,0,1]
	v_pk_fma_f32 v[132:133], v[132:133], 0.5, v[176:177] op_sel_hi:[1,0,1]
	v_pk_mul_f32 v[204:205], v[96:97], v[132:133]
	v_pk_mul_f32 v[206:207], v[98:99], v[134:135]
	v_fmac_f32_e32 v219, v132, v132
	v_add_u32_e32 v204, 0x8000, v204
	v_add_u32_e32 v205, 0x8000, v205
	v_add_u32_e32 v206, 0x8000, v206
	v_add_u32_e32 v207, 0x8000, v207
	v_fmac_f32_e32 v219, v133, v133
	v_fmac_f32_e32 v219, v134, v134
	v_fmac_f32_e32 v219, v135, v135
	v_perm_b32 v210, v205, v204, s50
	v_perm_b32 v211, v207, v206, s50
	global_store_dwordx2 v[186:187], v[210:211], off offset:256
	s_nop 1
	v_mov_b32_dpp v216, v218 row_ror:8 row_mask:0xf bank_mask:0xf
	v_mov_b32_dpp v217, v219 row_ror:8 row_mask:0xf bank_mask:0xf
	v_add_f32_e32 v218, v218, v216
	v_add_f32_e32 v219, v219, v217
	v_cndmask_b32_e64 v218, v219, v218, s[24:25]
	s_nop 0
	ds_bpermute_b32 v216, v220, v218
	global_load_dwordx4 v[156:159], v[180:181], off
	global_load_dwordx4 v[168:171], v[180:181], off offset:512
	global_load_dwordx4 v[172:175], v[182:183], off
	global_load_dwordx4 v[176:179], v[182:183], off offset:512
	s_mov_b64 vcc, 0x20000
	v_lshl_add_u64 v[180:181], v[180:181], 0, vcc
	v_lshl_add_u64 v[182:183], v[182:183], 0, vcc
	s_mov_b64 vcc, 0x20000
	s_mov_b64 vcc, 0x10000
	v_lshl_add_u64 v[184:185], v[184:185], 0, vcc
	v_lshl_add_u64 v[186:187], v[186:187], 0, vcc
	s_waitcnt lgkmcnt(0)
;     __device__ __forceinline__ void operator()(const f32x4 (&acc)[2][2][4][2], const Unit& u, int wr, int wc, int fr, int fq) const {
;     ...
;         for (int ai = 0; ai < 2; ++ai)
; #pragma unroll
;             for (int m = 0; m < 4; ++m) {
;                 const int row = row0 + ai * HALF + m * 16;
;                 const size_t off = (size_t)row * ldc + col0;
;                 float q = 0.f;
; #pragma unroll
;                 for (int bj = 0; bj < 2; ++bj)
; #pragma unroll
;                     for (int n = 0; n < 2; ++n) {
;                         const f32x4 rv = *(const f32x4*)(rbase + off + bj * HALF + n * 16);
;                         const f32x4 v = rv + acc[ai][bj][m][n] * scale;
;                         if (out) *(f32x4*)(out + off + bj * HALF + n * 16) = v;
;                         if (xn) { q += (v.x * v.x + v.y * v.y) + (v.z * v.z + v.w * v.w); const f32x4 o = v * wv[bj][n];
;                             u32x2 p; p.x = pk2(o.x, o.y); p.y = pk2(o.z, o.w); *(u32x2*)(xn + off + bj * HALF + n * 16) = p; }
;                     }
;                 if (xn) { q += __shfl_xor(q, 16); q += __shfl_xor(q, 32); if (fq == 0) (void)__hip_atomic_fetch_add(ss + row, q, __ATOMIC_RELAXED, __HIP_MEMORY_SCOPE_AGENT); }
;             }
	v_add_f32_e32 v218, v218, v216
	s_nop 0
	ds_bpermute_b32 v217, v221, v218
	s_waitcnt lgkmcnt(0)
	v_add_f32_e32 v218, v218, v217
	s_mov_b64 exec, s[0:1]
	global_atomic_add_f32 v[188:189], v218, off
	s_mov_b64 exec, -1
	s_mov_b64 vcc, 64
	v_lshl_add_u64 v[188:189], v[188:189], 0, vcc
	v_mov_b32_dpp v212, v120 row_ror:8 row_mask:0xf bank_mask:0xf
	v_mov_b32_dpp v213, v121 row_ror:8 row_mask:0xf bank_mask:0xf
	v_mov_b32_dpp v214, v122 row_ror:8 row_mask:0xf bank_mask:0xf
	v_mov_b32_dpp v215, v123 row_ror:8 row_mask:0xf bank_mask:0xf
	v_cndmask_b32_e64 v120, v212, v124, s[24:25]
	v_cndmask_b32_e64 v121, v213, v125, s[24:25]
	v_cndmask_b32_e64 v122, v214, v126, s[24:25]
	v_cndmask_b32_e64 v123, v215, v127, s[24:25]
	v_cndmask_b32_e64 v124, v124, v212, s[24:25]
	v_cndmask_b32_e64 v125, v125, v213, s[24:25]
	v_cndmask_b32_e64 v126, v126, v214, s[24:25]
	v_cndmask_b32_e64 v127, v127, v215, s[24:25]
	v_mov_b32_dpp v212, v112 row_ror:8 row_mask:0xf bank_mask:0xf
	v_mov_b32_dpp v213, v113 row_ror:8 row_mask:0xf bank_mask:0xf
	v_mov_b32_dpp v214, v114 row_ror:8 row_mask:0xf bank_mask:0xf
	v_mov_b32_dpp v215, v115 row_ror:8 row_mask:0xf bank_mask:0xf
	v_cndmask_b32_e64 v112, v212, v116, s[24:25]
	v_cndmask_b32_e64 v113, v213, v117, s[24:25]
	v_cndmask_b32_e64 v114, v214, v118, s[24:25]
	v_cndmask_b32_e64 v115, v215, v119, s[24:25]
	v_cndmask_b32_e64 v116, v116, v212, s[24:25]
	v_cndmask_b32_e64 v117, v117, v213, s[24:25]
	v_cndmask_b32_e64 v118, v118, v214, s[24:25]
	v_cndmask_b32_e64 v119, v119, v215, s[24:25]
	s_waitcnt vmcnt(1)
	v_pk_fma_f32 v[122:123], v[122:123], 0.5, v[158:159] op_sel_hi:[1,0,1]
	v_pk_fma_f32 v[120:121], v[120:121], 0.5, v[156:157] op_sel_hi:[1,0,1]
	v_pk_mul_f32 v[200:201], v[72:73], v[120:121]
	v_pk_mul_f32 v[202:203], v[74:75], v[122:123]
	v_mul_f32_e32 v218, v120, v120
	v_add_u32_e32 v200, 0x8000, v200
	v_add_u32_e32 v201, 0x8000, v201
	v_add_u32_e32 v202, 0x8000, v202
	v_add_u32_e32 v203, 0x8000, v203
	v_fmac_f32_e32 v218, v121, v121
	v_fmac_f32_e32 v218, v122, v122
	v_fmac_f32_e32 v218, v123, v123
	v_perm_b32 v208, v201, v200, s50
	v_perm_b32 v209, v203, v202, s50
	global_store_dwordx2 v[184:185], v[208:209], off
	v_pk_fma_f32 v[114:115], v[114:115], 0.5, v[170:171] op_sel_hi:[1,0,1]
	v_pk_fma_f32 v[112:113], v[112:113], 0.5, v[168:169] op_sel_hi:[1,0,1]
	v_pk_mul_f32 v[204:205], v[84:85], v[112:113]
	v_pk_mul_f32 v[206:207], v[86:87], v[114:115]
	v_fmac_f32_e32 v218, v112, v112
	v_add_u32_e32 v204, 0x8000, v204
	v_add_u32_e32 v205, 0x8000, v205
	v_add_u32_e32 v206, 0x8000, v206
	v_add_u32_e32 v207, 0x8000, v207
	v_fmac_f32_e32 v218, v113, v113
	v_fmac_f32_e32 v218, v114, v114
	v_fmac_f32_e32 v218, v115, v115
	v_perm_b32 v210, v205, v204, s50
	v_perm_b32 v211, v207, v206, s50
	global_store_dwordx2 v[184:185], v[210:211], off offset:256
	v_pk_fma_f32 v[126:127], v[126:127], 0.5, v[174:175] op_sel_hi:[1,0,1]
	v_pk_fma_f32 v[124:125], v[124:125], 0.5, v[172:173] op_sel_hi:[1,0,1]
	v_pk_mul_f32 v[200:201], v[88:89], v[124:125]
	v_pk_mul_f32 v[202:203], v[90:91], v[126:127]
	v_mul_f32_e32 v219, v124, v124
	v_add_u32_e32 v200, 0x8000, v200
	v_add_u32_e32 v201, 0x8000, v201
	v_add_u32_e32 v202, 0x8000, v202
	v_add_u32_e32 v203, 0x8000, v203
	v_fmac_f32_e32 v219, v125, v125
	v_fmac_f32_e32 v219, v126, v126
	v_fmac_f32_e32 v219, v127, v127
	v_perm_b32 v208, v201, v200, s50
	v_perm_b32 v209, v203, v202, s50
	global_store_dwordx2 v[186:187], v[208:209], off
	v_pk_fma_f32 v[118:119], v[118:119], 0.5, v[178:179] op_sel_hi:[1,0,1]
	v_pk_fma_f32 v[116:117], v[116:117], 0.5, v[176:177] op_sel_hi:[1,0,1]
	v_pk_mul_f32 v[204:205], v[96:97], v[116:117]
	v_pk_mul_f32 v[206:207], v[98:99], v[118:119]
	v_fmac_f32_e32 v219, v116, v116
	v_add_u32_e32 v204, 0x8000, v204
	v_add_u32_e32 v205, 0x8000, v205
	v_add_u32_e32 v206, 0x8000, v206
	v_add_u32_e32 v207, 0x8000, v207
	v_fmac_f32_e32 v219, v117, v117
	v_fmac_f32_e32 v219, v118, v118
	v_fmac_f32_e32 v219, v119, v119
	v_perm_b32 v210, v205, v204, s50
	v_perm_b32 v211, v207, v206, s50
	global_store_dwordx2 v[186:187], v[210:211], off offset:256
	s_nop 1
	v_mov_b32_dpp v216, v218 row_ror:8 row_mask:0xf bank_mask:0xf
	v_mov_b32_dpp v217, v219 row_ror:8 row_mask:0xf bank_mask:0xf
	v_add_f32_e32 v218, v218, v216
	v_add_f32_e32 v219, v219, v217
	v_cndmask_b32_e64 v218, v219, v218, s[24:25]
	s_nop 0
	ds_bpermute_b32 v216, v220, v218
	global_load_dwordx4 v[156:159], v[180:181], off
	global_load_dwordx4 v[168:171], v[180:181], off offset:512
	global_load_dwordx4 v[172:175], v[182:183], off
	global_load_dwordx4 v[176:179], v[182:183], off offset:512
	s_mov_b64 vcc, 0x20000
	v_lshl_add_u64 v[180:181], v[180:181], 0, vcc
	v_lshl_add_u64 v[182:183], v[182:183], 0, vcc
	s_mov_b64 vcc, 0x20000
	s_mov_b64 vcc, 0x10000
	v_lshl_add_u64 v[184:185], v[184:185], 0, vcc
	v_lshl_add_u64 v[186:187], v[186:187], 0, vcc
	s_waitcnt lgkmcnt(0)
	v_add_f32_e32 v218, v218, v216
	s_nop 0
	ds_bpermute_b32 v217, v221, v218
	s_waitcnt lgkmcnt(0)
;     __device__ __forceinline__ void operator()(const f32x4 (&acc)[2][2][4][2], const Unit& u, int wr, int wc, int fr, int fq) const {
;     ...
;         for (int ai = 0; ai < 2; ++ai)
; #pragma unroll
;             for (int m = 0; m < 4; ++m) {
;                 const int row = row0 + ai * HALF + m * 16;
;                 const size_t off = (size_t)row * ldc + col0;
;                 float q = 0.f;
; #pragma unroll
;                 for (int bj = 0; bj < 2; ++bj)
; #pragma unroll
;                     for (int n = 0; n < 2; ++n) {
;                         const f32x4 rv = *(const f32x4*)(rbase + off + bj * HALF + n * 16);
;                         const f32x4 v = rv + acc[ai][bj][m][n] * scale;
;                         if (out) *(f32x4*)(out + off + bj * HALF + n * 16) = v;
;                         if (xn) { q += (v.x * v.x + v.y * v.y) + (v.z * v.z + v.w * v.w); const f32x4 o = v * wv[bj][n];
;                             u32x2 p; p.x = pk2(o.x, o.y); p.y = pk2(o.z, o.w); *(u32x2*)(xn + off + bj * HALF + n * 16) = p; }
;                     }
;                 if (xn) { q += __shfl_xor(q, 16); q += __shfl_xor(q, 32); if (fq == 0) (void)__hip_atomic_fetch_add(ss + row, q, __ATOMIC_RELAXED, __HIP_MEMORY_SCOPE_AGENT); }
;             }
	v_add_f32_e32 v218, v218, v217
	s_mov_b64 exec, s[0:1]
	global_atomic_add_f32 v[188:189], v218, off
	s_mov_b64 exec, -1
	s_mov_b64 vcc, 64
	v_lshl_add_u64 v[188:189], v[188:189], 0, vcc
	v_mov_b32_dpp v212, v104 row_ror:8 row_mask:0xf bank_mask:0xf
	v_mov_b32_dpp v213, v105 row_ror:8 row_mask:0xf bank_mask:0xf
	v_mov_b32_dpp v214, v106 row_ror:8 row_mask:0xf bank_mask:0xf
	v_mov_b32_dpp v215, v107 row_ror:8 row_mask:0xf bank_mask:0xf
	v_cndmask_b32_e64 v104, v212, v108, s[24:25]
	v_cndmask_b32_e64 v105, v213, v109, s[24:25]
	v_cndmask_b32_e64 v106, v214, v110, s[24:25]
	v_cndmask_b32_e64 v107, v215, v111, s[24:25]
	v_cndmask_b32_e64 v108, v108, v212, s[24:25]
	v_cndmask_b32_e64 v109, v109, v213, s[24:25]
	v_cndmask_b32_e64 v110, v110, v214, s[24:25]
	v_cndmask_b32_e64 v111, v111, v215, s[24:25]
	v_mov_b32_dpp v212, v92 row_ror:8 row_mask:0xf bank_mask:0xf
	v_mov_b32_dpp v213, v93 row_ror:8 row_mask:0xf bank_mask:0xf
	v_mov_b32_dpp v214, v94 row_ror:8 row_mask:0xf bank_mask:0xf
	v_mov_b32_dpp v215, v95 row_ror:8 row_mask:0xf bank_mask:0xf
	v_cndmask_b32_e64 v92, v212, v100, s[24:25]
	v_cndmask_b32_e64 v93, v213, v101, s[24:25]
	v_cndmask_b32_e64 v94, v214, v102, s[24:25]
	v_cndmask_b32_e64 v95, v215, v103, s[24:25]
	v_cndmask_b32_e64 v100, v100, v212, s[24:25]
	v_cndmask_b32_e64 v101, v101, v213, s[24:25]
	v_cndmask_b32_e64 v102, v102, v214, s[24:25]
	v_cndmask_b32_e64 v103, v103, v215, s[24:25]
	s_waitcnt vmcnt(1)
	v_pk_fma_f32 v[106:107], v[106:107], 0.5, v[158:159] op_sel_hi:[1,0,1]
	v_pk_fma_f32 v[104:105], v[104:105], 0.5, v[156:157] op_sel_hi:[1,0,1]
	v_pk_mul_f32 v[200:201], v[72:73], v[104:105]
	v_pk_mul_f32 v[202:203], v[74:75], v[106:107]
	v_mul_f32_e32 v218, v104, v104
	v_add_u32_e32 v200, 0x8000, v200
	v_add_u32_e32 v201, 0x8000, v201
	v_add_u32_e32 v202, 0x8000, v202
	v_add_u32_e32 v203, 0x8000, v203
	v_fmac_f32_e32 v218, v105, v105
	v_fmac_f32_e32 v218, v106, v106
	v_fmac_f32_e32 v218, v107, v107
	v_perm_b32 v208, v201, v200, s50
	v_perm_b32 v209, v203, v202, s50
	global_store_dwordx2 v[184:185], v[208:209], off
	v_pk_fma_f32 v[94:95], v[94:95], 0.5, v[170:171] op_sel_hi:[1,0,1]
	v_pk_fma_f32 v[92:93], v[92:93], 0.5, v[168:169] op_sel_hi:[1,0,1]
	v_pk_mul_f32 v[204:205], v[84:85], v[92:93]
	v_pk_mul_f32 v[206:207], v[86:87], v[94:95]
	v_fmac_f32_e32 v218, v92, v92
	v_add_u32_e32 v204, 0x8000, v204
	v_add_u32_e32 v205, 0x8000, v205
	v_add_u32_e32 v206, 0x8000, v206
	v_add_u32_e32 v207, 0x8000, v207
	v_fmac_f32_e32 v218, v93, v93
	v_fmac_f32_e32 v218, v94, v94
	v_fmac_f32_e32 v218, v95, v95
	v_perm_b32 v210, v205, v204, s50
	v_perm_b32 v211, v207, v206, s50
	global_store_dwordx2 v[184:185], v[210:211], off offset:256
	v_pk_fma_f32 v[110:111], v[110:111], 0.5, v[174:175] op_sel_hi:[1,0,1]
	v_pk_fma_f32 v[108:109], v[108:109], 0.5, v[172:173] op_sel_hi:[1,0,1]
	v_pk_mul_f32 v[200:201], v[88:89], v[108:109]
	v_pk_mul_f32 v[202:203], v[90:91], v[110:111]
	v_mul_f32_e32 v219, v108, v108
	v_add_u32_e32 v200, 0x8000, v200
	v_add_u32_e32 v201, 0x8000, v201
	v_add_u32_e32 v202, 0x8000, v202
	v_add_u32_e32 v203, 0x8000, v203
	v_fmac_f32_e32 v219, v109, v109
	v_fmac_f32_e32 v219, v110, v110
	v_fmac_f32_e32 v219, v111, v111
	v_perm_b32 v208, v201, v200, s50
	v_perm_b32 v209, v203, v202, s50
	global_store_dwordx2 v[186:187], v[208:209], off
	v_pk_fma_f32 v[102:103], v[102:103], 0.5, v[178:179] op_sel_hi:[1,0,1]
	v_pk_fma_f32 v[100:101], v[100:101], 0.5, v[176:177] op_sel_hi:[1,0,1]
	v_pk_mul_f32 v[204:205], v[96:97], v[100:101]
	v_pk_mul_f32 v[206:207], v[98:99], v[102:103]
	v_fmac_f32_e32 v219, v100, v100
	v_add_u32_e32 v204, 0x8000, v204
	v_add_u32_e32 v205, 0x8000, v205
	v_add_u32_e32 v206, 0x8000, v206
	v_add_u32_e32 v207, 0x8000, v207
	v_fmac_f32_e32 v219, v101, v101
	v_fmac_f32_e32 v219, v102, v102
	v_fmac_f32_e32 v219, v103, v103
	v_perm_b32 v210, v205, v204, s50
	v_perm_b32 v211, v207, v206, s50
	global_store_dwordx2 v[186:187], v[210:211], off offset:256
	s_nop 1
	v_mov_b32_dpp v216, v218 row_ror:8 row_mask:0xf bank_mask:0xf
	v_mov_b32_dpp v217, v219 row_ror:8 row_mask:0xf bank_mask:0xf
	v_add_f32_e32 v218, v218, v216
	v_add_f32_e32 v219, v219, v217
	v_cndmask_b32_e64 v218, v219, v218, s[24:25]
	s_nop 0
	ds_bpermute_b32 v216, v220, v218
	global_load_dwordx4 v[156:159], v[180:181], off
	global_load_dwordx4 v[168:171], v[180:181], off offset:512
	global_load_dwordx4 v[172:175], v[182:183], off
	global_load_dwordx4 v[176:179], v[182:183], off offset:512
	s_mov_b64 vcc, 0xa0000
	v_lshl_add_u64 v[180:181], v[180:181], 0, vcc
	v_lshl_add_u64 v[182:183], v[182:183], 0, vcc
	s_mov_b64 vcc, 0x20000
	s_mov_b64 vcc, 0x10000
	v_lshl_add_u64 v[184:185], v[184:185], 0, vcc
	v_lshl_add_u64 v[186:187], v[186:187], 0, vcc
	s_waitcnt lgkmcnt(0)
	v_add_f32_e32 v218, v218, v216
	s_nop 0
	ds_bpermute_b32 v217, v221, v218
	s_waitcnt lgkmcnt(0)
	v_add_f32_e32 v218, v218, v217
	s_mov_b64 exec, s[0:1]
	global_atomic_add_f32 v[188:189], v218, off
	s_mov_b64 exec, -1
	s_mov_b64 vcc, 64
	v_lshl_add_u64 v[188:189], v[188:189], 0, vcc
	v_mov_b32_dpp v212, v76 row_ror:8 row_mask:0xf bank_mask:0xf
	v_mov_b32_dpp v213, v77 row_ror:8 row_mask:0xf bank_mask:0xf
	v_mov_b32_dpp v214, v78 row_ror:8 row_mask:0xf bank_mask:0xf
	v_mov_b32_dpp v215, v79 row_ror:8 row_mask:0xf bank_mask:0xf
	v_cndmask_b32_e64 v76, v212, v80, s[24:25]
	v_cndmask_b32_e64 v77, v213, v81, s[24:25]
	v_cndmask_b32_e64 v78, v214, v82, s[24:25]
	v_cndmask_b32_e64 v79, v215, v83, s[24:25]
	v_cndmask_b32_e64 v80, v80, v212, s[24:25]
	v_cndmask_b32_e64 v81, v81, v213, s[24:25]
	v_cndmask_b32_e64 v82, v82, v214, s[24:25]
	v_cndmask_b32_e64 v83, v83, v215, s[24:25]
	v_mov_b32_dpp v212, v64 row_ror:8 row_mask:0xf bank_mask:0xf
	v_mov_b32_dpp v213, v65 row_ror:8 row_mask:0xf bank_mask:0xf
	v_mov_b32_dpp v214, v66 row_ror:8 row_mask:0xf bank_mask:0xf
	v_mov_b32_dpp v215, v67 row_ror:8 row_mask:0xf bank_mask:0xf
	v_cndmask_b32_e64 v64, v212, v68, s[24:25]
	v_cndmask_b32_e64 v65, v213, v69, s[24:25]
	v_cndmask_b32_e64 v66, v214, v70, s[24:25]
	v_cndmask_b32_e64 v67, v215, v71, s[24:25]
	v_cndmask_b32_e64 v68, v68, v212, s[24:25]
	v_cndmask_b32_e64 v69, v69, v213, s[24:25]
	v_cndmask_b32_e64 v70, v70, v214, s[24:25]
	v_cndmask_b32_e64 v71, v71, v215, s[24:25]
	s_waitcnt vmcnt(1)
;     __device__ __forceinline__ void operator()(const f32x4 (&acc)[2][2][4][2], const Unit& u, int wr, int wc, int fr, int fq) const {
;     ...
;         for (int ai = 0; ai < 2; ++ai)
; #pragma unroll
;             for (int m = 0; m < 4; ++m) {
;                 const int row = row0 + ai * HALF + m * 16;
;                 const size_t off = (size_t)row * ldc + col0;
;                 float q = 0.f;
; #pragma unroll
;                 for (int bj = 0; bj < 2; ++bj)
; #pragma unroll
;                     for (int n = 0; n < 2; ++n) {
;                         const f32x4 rv = *(const f32x4*)(rbase + off + bj * HALF + n * 16);
;                         const f32x4 v = rv + acc[ai][bj][m][n] * scale;
;                         if (out) *(f32x4*)(out + off + bj * HALF + n * 16) = v;
;                         if (xn) { q += (v.x * v.x + v.y * v.y) + (v.z * v.z + v.w * v.w); const f32x4 o = v * wv[bj][n];
;                             u32x2 p; p.x = pk2(o.x, o.y); p.y = pk2(o.z, o.w); *(u32x2*)(xn + off + bj * HALF + n * 16) = p; }
;                     }
;                 if (xn) { q += __shfl_xor(q, 16); q += __shfl_xor(q, 32); if (fq == 0) (void)__hip_atomic_fetch_add(ss + row, q, __ATOMIC_RELAXED, __HIP_MEMORY_SCOPE_AGENT); }
;             }
	v_pk_fma_f32 v[78:79], v[78:79], 0.5, v[158:159] op_sel_hi:[1,0,1]
	v_pk_fma_f32 v[76:77], v[76:77], 0.5, v[156:157] op_sel_hi:[1,0,1]
	v_pk_mul_f32 v[200:201], v[72:73], v[76:77]
	v_pk_mul_f32 v[202:203], v[74:75], v[78:79]
	v_mul_f32_e32 v218, v76, v76
	v_add_u32_e32 v200, 0x8000, v200
	v_add_u32_e32 v201, 0x8000, v201
	v_add_u32_e32 v202, 0x8000, v202
	v_add_u32_e32 v203, 0x8000, v203
	v_fmac_f32_e32 v218, v77, v77
	v_fmac_f32_e32 v218, v78, v78
	v_fmac_f32_e32 v218, v79, v79
	v_perm_b32 v208, v201, v200, s50
	v_perm_b32 v209, v203, v202, s50
	global_store_dwordx2 v[184:185], v[208:209], off
	v_pk_fma_f32 v[66:67], v[66:67], 0.5, v[170:171] op_sel_hi:[1,0,1]
	v_pk_fma_f32 v[64:65], v[64:65], 0.5, v[168:169] op_sel_hi:[1,0,1]
	v_pk_mul_f32 v[204:205], v[84:85], v[64:65]
	v_pk_mul_f32 v[206:207], v[86:87], v[66:67]
	v_fmac_f32_e32 v218, v64, v64
	v_add_u32_e32 v204, 0x8000, v204
	v_add_u32_e32 v205, 0x8000, v205
	v_add_u32_e32 v206, 0x8000, v206
	v_add_u32_e32 v207, 0x8000, v207
	v_fmac_f32_e32 v218, v65, v65
	v_fmac_f32_e32 v218, v66, v66
	v_fmac_f32_e32 v218, v67, v67
	v_perm_b32 v210, v205, v204, s50
	v_perm_b32 v211, v207, v206, s50
	global_store_dwordx2 v[184:185], v[210:211], off offset:256
	v_pk_fma_f32 v[82:83], v[82:83], 0.5, v[174:175] op_sel_hi:[1,0,1]
	v_pk_fma_f32 v[80:81], v[80:81], 0.5, v[172:173] op_sel_hi:[1,0,1]
	v_pk_mul_f32 v[200:201], v[88:89], v[80:81]
	v_pk_mul_f32 v[202:203], v[90:91], v[82:83]
	v_mul_f32_e32 v219, v80, v80
	v_add_u32_e32 v200, 0x8000, v200
	v_add_u32_e32 v201, 0x8000, v201
	v_add_u32_e32 v202, 0x8000, v202
	v_add_u32_e32 v203, 0x8000, v203
	v_fmac_f32_e32 v219, v81, v81
	v_fmac_f32_e32 v219, v82, v82
	v_fmac_f32_e32 v219, v83, v83
	v_perm_b32 v208, v201, v200, s50
	v_perm_b32 v209, v203, v202, s50
	global_store_dwordx2 v[186:187], v[208:209], off
	v_pk_fma_f32 v[70:71], v[70:71], 0.5, v[178:179] op_sel_hi:[1,0,1]
	v_pk_fma_f32 v[68:69], v[68:69], 0.5, v[176:177] op_sel_hi:[1,0,1]
	v_pk_mul_f32 v[204:205], v[96:97], v[68:69]
	v_pk_mul_f32 v[206:207], v[98:99], v[70:71]
	v_fmac_f32_e32 v219, v68, v68
	v_add_u32_e32 v204, 0x8000, v204
	v_add_u32_e32 v205, 0x8000, v205
	v_add_u32_e32 v206, 0x8000, v206
	v_add_u32_e32 v207, 0x8000, v207
	v_fmac_f32_e32 v219, v69, v69
	v_fmac_f32_e32 v219, v70, v70
	v_fmac_f32_e32 v219, v71, v71
	v_perm_b32 v210, v205, v204, s50
	v_perm_b32 v211, v207, v206, s50
	global_store_dwordx2 v[186:187], v[210:211], off offset:256
	s_nop 1
	v_mov_b32_dpp v216, v218 row_ror:8 row_mask:0xf bank_mask:0xf
	v_mov_b32_dpp v217, v219 row_ror:8 row_mask:0xf bank_mask:0xf
	v_add_f32_e32 v218, v218, v216
	v_add_f32_e32 v219, v219, v217
	v_cndmask_b32_e64 v218, v219, v218, s[24:25]
	s_nop 0
	ds_bpermute_b32 v216, v220, v218
	global_load_dwordx4 v[156:159], v[180:181], off
	global_load_dwordx4 v[168:171], v[180:181], off offset:512
	global_load_dwordx4 v[172:175], v[182:183], off
	global_load_dwordx4 v[176:179], v[182:183], off offset:512
	s_mov_b64 vcc, 0x20000
	v_lshl_add_u64 v[180:181], v[180:181], 0, vcc
	v_lshl_add_u64 v[182:183], v[182:183], 0, vcc
	s_mov_b64 vcc, 0xa0000
	s_mov_b64 vcc, 0x50000
	v_lshl_add_u64 v[184:185], v[184:185], 0, vcc
	v_lshl_add_u64 v[186:187], v[186:187], 0, vcc
	s_waitcnt lgkmcnt(0)
	v_add_f32_e32 v218, v218, v216
	s_nop 0
	ds_bpermute_b32 v217, v221, v218
	s_waitcnt lgkmcnt(0)
	v_add_f32_e32 v218, v218, v217
	s_mov_b64 exec, s[0:1]
	global_atomic_add_f32 v[188:189], v218, off
	s_mov_b64 exec, -1
	s_mov_b64 vcc, 320
	v_lshl_add_u64 v[188:189], v[188:189], 0, vcc
	v_mov_b32_dpp v212, v56 row_ror:8 row_mask:0xf bank_mask:0xf
	v_mov_b32_dpp v213, v57 row_ror:8 row_mask:0xf bank_mask:0xf
	v_mov_b32_dpp v214, v58 row_ror:8 row_mask:0xf bank_mask:0xf
	v_mov_b32_dpp v215, v59 row_ror:8 row_mask:0xf bank_mask:0xf
	v_cndmask_b32_e64 v56, v212, v60, s[24:25]
	v_cndmask_b32_e64 v57, v213, v61, s[24:25]
	v_cndmask_b32_e64 v58, v214, v62, s[24:25]
	v_cndmask_b32_e64 v59, v215, v63, s[24:25]
	v_cndmask_b32_e64 v60, v60, v212, s[24:25]
	v_cndmask_b32_e64 v61, v61, v213, s[24:25]
	v_cndmask_b32_e64 v62, v62, v214, s[24:25]
	v_cndmask_b32_e64 v63, v63, v215, s[24:25]
	v_mov_b32_dpp v212, v48 row_ror:8 row_mask:0xf bank_mask:0xf
	v_mov_b32_dpp v213, v49 row_ror:8 row_mask:0xf bank_mask:0xf
	v_mov_b32_dpp v214, v50 row_ror:8 row_mask:0xf bank_mask:0xf
	v_mov_b32_dpp v215, v51 row_ror:8 row_mask:0xf bank_mask:0xf
	v_cndmask_b32_e64 v48, v212, v52, s[24:25]
	v_cndmask_b32_e64 v49, v213, v53, s[24:25]
	v_cndmask_b32_e64 v50, v214, v54, s[24:25]
	v_cndmask_b32_e64 v51, v215, v55, s[24:25]
	v_cndmask_b32_e64 v52, v52, v212, s[24:25]
	v_cndmask_b32_e64 v53, v53, v213, s[24:25]
	v_cndmask_b32_e64 v54, v54, v214, s[24:25]
	v_cndmask_b32_e64 v55, v55, v215, s[24:25]
	s_waitcnt vmcnt(1)
;     __device__ __forceinline__ void operator()(const f32x4 (&acc)[2][2][4][2], const Unit& u, int wr, int wc, int fr, int fq) const {
;     ...
;         for (int ai = 0; ai < 2; ++ai)
; #pragma unroll
;             for (int m = 0; m < 4; ++m) {
;                 const int row = row0 + ai * HALF + m * 16;
;                 const size_t off = (size_t)row * ldc + col0;
;                 float q = 0.f;
; #pragma unroll
;                 for (int bj = 0; bj < 2; ++bj)
; #pragma unroll
;                     for (int n = 0; n < 2; ++n) {
;                         const f32x4 rv = *(const f32x4*)(rbase + off + bj * HALF + n * 16);
;                         const f32x4 v = rv + acc[ai][bj][m][n] * scale;
;                         if (out) *(f32x4*)(out + off + bj * HALF + n * 16) = v;
;                         if (xn) { q += (v.x * v.x + v.y * v.y) + (v.z * v.z + v.w * v.w); const f32x4 o = v * wv[bj][n];
;                             u32x2 p; p.x = pk2(o.x, o.y); p.y = pk2(o.z, o.w); *(u32x2*)(xn + off + bj * HALF + n * 16) = p; }
;                     }
;                 if (xn) { q += __shfl_xor(q, 16); q += __shfl_xor(q, 32); if (fq == 0) (void)__hip_atomic_fetch_add(ss + row, q, __ATOMIC_RELAXED, __HIP_MEMORY_SCOPE_AGENT); }
;             }
	v_pk_fma_f32 v[58:59], v[58:59], 0.5, v[158:159] op_sel_hi:[1,0,1]
	v_pk_fma_f32 v[56:57], v[56:57], 0.5, v[156:157] op_sel_hi:[1,0,1]
	v_pk_mul_f32 v[200:201], v[72:73], v[56:57]
	v_pk_mul_f32 v[202:203], v[74:75], v[58:59]
	v_mul_f32_e32 v218, v56, v56
	v_add_u32_e32 v200, 0x8000, v200
	v_add_u32_e32 v201, 0x8000, v201
	v_add_u32_e32 v202, 0x8000, v202
	v_add_u32_e32 v203, 0x8000, v203
	v_fmac_f32_e32 v218, v57, v57
	v_fmac_f32_e32 v218, v58, v58
	v_fmac_f32_e32 v218, v59, v59
	v_perm_b32 v208, v201, v200, s50
	v_perm_b32 v209, v203, v202, s50
	global_store_dwordx2 v[184:185], v[208:209], off
	v_pk_fma_f32 v[50:51], v[50:51], 0.5, v[170:171] op_sel_hi:[1,0,1]
	v_pk_fma_f32 v[48:49], v[48:49], 0.5, v[168:169] op_sel_hi:[1,0,1]
	v_pk_mul_f32 v[204:205], v[84:85], v[48:49]
	v_pk_mul_f32 v[206:207], v[86:87], v[50:51]
	v_fmac_f32_e32 v218, v48, v48
	v_add_u32_e32 v204, 0x8000, v204
	v_add_u32_e32 v205, 0x8000, v205
	v_add_u32_e32 v206, 0x8000, v206
	v_add_u32_e32 v207, 0x8000, v207
	v_fmac_f32_e32 v218, v49, v49
	v_fmac_f32_e32 v218, v50, v50
	v_fmac_f32_e32 v218, v51, v51
	v_perm_b32 v210, v205, v204, s50
	v_perm_b32 v211, v207, v206, s50
	global_store_dwordx2 v[184:185], v[210:211], off offset:256
	v_pk_fma_f32 v[62:63], v[62:63], 0.5, v[174:175] op_sel_hi:[1,0,1]
	v_pk_fma_f32 v[60:61], v[60:61], 0.5, v[172:173] op_sel_hi:[1,0,1]
	v_pk_mul_f32 v[200:201], v[88:89], v[60:61]
	v_pk_mul_f32 v[202:203], v[90:91], v[62:63]
	v_mul_f32_e32 v219, v60, v60
	v_add_u32_e32 v200, 0x8000, v200
	v_add_u32_e32 v201, 0x8000, v201
	v_add_u32_e32 v202, 0x8000, v202
	v_add_u32_e32 v203, 0x8000, v203
	v_fmac_f32_e32 v219, v61, v61
	v_fmac_f32_e32 v219, v62, v62
	v_fmac_f32_e32 v219, v63, v63
	v_perm_b32 v208, v201, v200, s50
	v_perm_b32 v209, v203, v202, s50
	global_store_dwordx2 v[186:187], v[208:209], off
	v_pk_fma_f32 v[54:55], v[54:55], 0.5, v[178:179] op_sel_hi:[1,0,1]
	v_pk_fma_f32 v[52:53], v[52:53], 0.5, v[176:177] op_sel_hi:[1,0,1]
	v_pk_mul_f32 v[204:205], v[96:97], v[52:53]
	v_pk_mul_f32 v[206:207], v[98:99], v[54:55]
	v_fmac_f32_e32 v219, v52, v52
	v_add_u32_e32 v204, 0x8000, v204
	v_add_u32_e32 v205, 0x8000, v205
	v_add_u32_e32 v206, 0x8000, v206
	v_add_u32_e32 v207, 0x8000, v207
	v_fmac_f32_e32 v219, v53, v53
	v_fmac_f32_e32 v219, v54, v54
	v_fmac_f32_e32 v219, v55, v55
	v_perm_b32 v210, v205, v204, s50
	v_perm_b32 v211, v207, v206, s50
	global_store_dwordx2 v[186:187], v[210:211], off offset:256
	s_nop 1
	v_mov_b32_dpp v216, v218 row_ror:8 row_mask:0xf bank_mask:0xf
	v_mov_b32_dpp v217, v219 row_ror:8 row_mask:0xf bank_mask:0xf
	v_add_f32_e32 v218, v218, v216
	v_add_f32_e32 v219, v219, v217
	v_cndmask_b32_e64 v218, v219, v218, s[24:25]
	s_nop 0
	ds_bpermute_b32 v216, v220, v218
	global_load_dwordx4 v[156:159], v[180:181], off
	global_load_dwordx4 v[168:171], v[180:181], off offset:512
	global_load_dwordx4 v[172:175], v[182:183], off
	global_load_dwordx4 v[176:179], v[182:183], off offset:512
	s_mov_b64 vcc, 0x20000
	v_lshl_add_u64 v[180:181], v[180:181], 0, vcc
	v_lshl_add_u64 v[182:183], v[182:183], 0, vcc
	s_mov_b64 vcc, 0x20000
	s_mov_b64 vcc, 0x10000
	v_lshl_add_u64 v[184:185], v[184:185], 0, vcc
	v_lshl_add_u64 v[186:187], v[186:187], 0, vcc
	s_waitcnt lgkmcnt(0)
	v_add_f32_e32 v218, v218, v216
	s_nop 0
	ds_bpermute_b32 v217, v221, v218
	s_waitcnt lgkmcnt(0)
	v_add_f32_e32 v218, v218, v217
	s_mov_b64 exec, s[0:1]
	global_atomic_add_f32 v[188:189], v218, off
	s_mov_b64 exec, -1
	s_mov_b64 vcc, 64
	v_lshl_add_u64 v[188:189], v[188:189], 0, vcc
	v_mov_b32_dpp v212, v40 row_ror:8 row_mask:0xf bank_mask:0xf
	v_mov_b32_dpp v213, v41 row_ror:8 row_mask:0xf bank_mask:0xf
	v_mov_b32_dpp v214, v42 row_ror:8 row_mask:0xf bank_mask:0xf
	v_mov_b32_dpp v215, v43 row_ror:8 row_mask:0xf bank_mask:0xf
	v_cndmask_b32_e64 v40, v212, v44, s[24:25]
	v_cndmask_b32_e64 v41, v213, v45, s[24:25]
	v_cndmask_b32_e64 v42, v214, v46, s[24:25]
	v_cndmask_b32_e64 v43, v215, v47, s[24:25]
	v_cndmask_b32_e64 v44, v44, v212, s[24:25]
	v_cndmask_b32_e64 v45, v45, v213, s[24:25]
	v_cndmask_b32_e64 v46, v46, v214, s[24:25]
	v_cndmask_b32_e64 v47, v47, v215, s[24:25]
	v_mov_b32_dpp v212, v32 row_ror:8 row_mask:0xf bank_mask:0xf
	v_mov_b32_dpp v213, v33 row_ror:8 row_mask:0xf bank_mask:0xf
	v_mov_b32_dpp v214, v34 row_ror:8 row_mask:0xf bank_mask:0xf
	v_mov_b32_dpp v215, v35 row_ror:8 row_mask:0xf bank_mask:0xf
	v_cndmask_b32_e64 v32, v212, v36, s[24:25]
	v_cndmask_b32_e64 v33, v213, v37, s[24:25]
	v_cndmask_b32_e64 v34, v214, v38, s[24:25]
	v_cndmask_b32_e64 v35, v215, v39, s[24:25]
	v_cndmask_b32_e64 v36, v36, v212, s[24:25]
	v_cndmask_b32_e64 v37, v37, v213, s[24:25]
	v_cndmask_b32_e64 v38, v38, v214, s[24:25]
	v_cndmask_b32_e64 v39, v39, v215, s[24:25]
	s_waitcnt vmcnt(1)
;     __device__ __forceinline__ void operator()(const f32x4 (&acc)[2][2][4][2], const Unit& u, int wr, int wc, int fr, int fq) const {
;     ...
;         for (int ai = 0; ai < 2; ++ai)
; #pragma unroll
;             for (int m = 0; m < 4; ++m) {
;                 const int row = row0 + ai * HALF + m * 16;
;                 const size_t off = (size_t)row * ldc + col0;
;                 float q = 0.f;
; #pragma unroll
;                 for (int bj = 0; bj < 2; ++bj)
; #pragma unroll
;                     for (int n = 0; n < 2; ++n) {
;                         const f32x4 rv = *(const f32x4*)(rbase + off + bj * HALF + n * 16);
;                         const f32x4 v = rv + acc[ai][bj][m][n] * scale;
;                         if (out) *(f32x4*)(out + off + bj * HALF + n * 16) = v;
;                         if (xn) { q += (v.x * v.x + v.y * v.y) + (v.z * v.z + v.w * v.w); const f32x4 o = v * wv[bj][n];
;                             u32x2 p; p.x = pk2(o.x, o.y); p.y = pk2(o.z, o.w); *(u32x2*)(xn + off + bj * HALF + n * 16) = p; }
;                     }
;                 if (xn) { q += __shfl_xor(q, 16); q += __shfl_xor(q, 32); if (fq == 0) (void)__hip_atomic_fetch_add(ss + row, q, __ATOMIC_RELAXED, __HIP_MEMORY_SCOPE_AGENT); }
;             }
	v_pk_fma_f32 v[42:43], v[42:43], 0.5, v[158:159] op_sel_hi:[1,0,1]
	v_pk_fma_f32 v[40:41], v[40:41], 0.5, v[156:157] op_sel_hi:[1,0,1]
	v_pk_mul_f32 v[200:201], v[72:73], v[40:41]
	v_pk_mul_f32 v[202:203], v[74:75], v[42:43]
	v_mul_f32_e32 v218, v40, v40
	v_add_u32_e32 v200, 0x8000, v200
	v_add_u32_e32 v201, 0x8000, v201
	v_add_u32_e32 v202, 0x8000, v202
	v_add_u32_e32 v203, 0x8000, v203
	v_fmac_f32_e32 v218, v41, v41
	v_fmac_f32_e32 v218, v42, v42
	v_fmac_f32_e32 v218, v43, v43
	v_perm_b32 v208, v201, v200, s50
	v_perm_b32 v209, v203, v202, s50
	global_store_dwordx2 v[184:185], v[208:209], off
	v_pk_fma_f32 v[34:35], v[34:35], 0.5, v[170:171] op_sel_hi:[1,0,1]
	v_pk_fma_f32 v[32:33], v[32:33], 0.5, v[168:169] op_sel_hi:[1,0,1]
	v_pk_mul_f32 v[204:205], v[84:85], v[32:33]
	v_pk_mul_f32 v[206:207], v[86:87], v[34:35]
	v_fmac_f32_e32 v218, v32, v32
	v_add_u32_e32 v204, 0x8000, v204
	v_add_u32_e32 v205, 0x8000, v205
	v_add_u32_e32 v206, 0x8000, v206
	v_add_u32_e32 v207, 0x8000, v207
	v_fmac_f32_e32 v218, v33, v33
	v_fmac_f32_e32 v218, v34, v34
	v_fmac_f32_e32 v218, v35, v35
	v_perm_b32 v210, v205, v204, s50
	v_perm_b32 v211, v207, v206, s50
	global_store_dwordx2 v[184:185], v[210:211], off offset:256
	v_pk_fma_f32 v[46:47], v[46:47], 0.5, v[174:175] op_sel_hi:[1,0,1]
	v_pk_fma_f32 v[44:45], v[44:45], 0.5, v[172:173] op_sel_hi:[1,0,1]
	v_pk_mul_f32 v[200:201], v[88:89], v[44:45]
	v_pk_mul_f32 v[202:203], v[90:91], v[46:47]
	v_mul_f32_e32 v219, v44, v44
	v_add_u32_e32 v200, 0x8000, v200
	v_add_u32_e32 v201, 0x8000, v201
	v_add_u32_e32 v202, 0x8000, v202
	v_add_u32_e32 v203, 0x8000, v203
	v_fmac_f32_e32 v219, v45, v45
	v_fmac_f32_e32 v219, v46, v46
	v_fmac_f32_e32 v219, v47, v47
	v_perm_b32 v208, v201, v200, s50
	v_perm_b32 v209, v203, v202, s50
	global_store_dwordx2 v[186:187], v[208:209], off
	v_pk_fma_f32 v[38:39], v[38:39], 0.5, v[178:179] op_sel_hi:[1,0,1]
	v_pk_fma_f32 v[36:37], v[36:37], 0.5, v[176:177] op_sel_hi:[1,0,1]
	v_pk_mul_f32 v[204:205], v[96:97], v[36:37]
	v_pk_mul_f32 v[206:207], v[98:99], v[38:39]
	v_fmac_f32_e32 v219, v36, v36
	v_add_u32_e32 v204, 0x8000, v204
	v_add_u32_e32 v205, 0x8000, v205
	v_add_u32_e32 v206, 0x8000, v206
	v_add_u32_e32 v207, 0x8000, v207
	v_fmac_f32_e32 v219, v37, v37
	v_fmac_f32_e32 v219, v38, v38
	v_fmac_f32_e32 v219, v39, v39
	v_perm_b32 v210, v205, v204, s50
	v_perm_b32 v211, v207, v206, s50
	global_store_dwordx2 v[186:187], v[210:211], off offset:256
	s_nop 1
	v_mov_b32_dpp v216, v218 row_ror:8 row_mask:0xf bank_mask:0xf
	v_mov_b32_dpp v217, v219 row_ror:8 row_mask:0xf bank_mask:0xf
	v_add_f32_e32 v218, v218, v216
	v_add_f32_e32 v219, v219, v217
	v_cndmask_b32_e64 v218, v219, v218, s[24:25]
	s_nop 0
	ds_bpermute_b32 v216, v220, v218
	global_load_dwordx4 v[156:159], v[180:181], off
	global_load_dwordx4 v[168:171], v[180:181], off offset:512
	global_load_dwordx4 v[172:175], v[182:183], off
	global_load_dwordx4 v[176:179], v[182:183], off offset:512
	s_mov_b64 vcc, 0x20000
	v_lshl_add_u64 v[180:181], v[180:181], 0, vcc
	v_lshl_add_u64 v[182:183], v[182:183], 0, vcc
	s_mov_b64 vcc, 0x20000
	s_mov_b64 vcc, 0x10000
	v_lshl_add_u64 v[184:185], v[184:185], 0, vcc
	v_lshl_add_u64 v[186:187], v[186:187], 0, vcc
	s_waitcnt lgkmcnt(0)
	v_add_f32_e32 v218, v218, v216
	s_nop 0
	ds_bpermute_b32 v217, v221, v218
	s_waitcnt lgkmcnt(0)
	v_add_f32_e32 v218, v218, v217
	s_mov_b64 exec, s[0:1]
	global_atomic_add_f32 v[188:189], v218, off
	s_mov_b64 exec, -1
	s_mov_b64 vcc, 64
	v_lshl_add_u64 v[188:189], v[188:189], 0, vcc
	v_mov_b32_dpp v212, v24 row_ror:8 row_mask:0xf bank_mask:0xf
	v_mov_b32_dpp v213, v25 row_ror:8 row_mask:0xf bank_mask:0xf
	v_mov_b32_dpp v214, v26 row_ror:8 row_mask:0xf bank_mask:0xf
	v_mov_b32_dpp v215, v27 row_ror:8 row_mask:0xf bank_mask:0xf
	v_cndmask_b32_e64 v24, v212, v28, s[24:25]
	v_cndmask_b32_e64 v25, v213, v29, s[24:25]
	v_cndmask_b32_e64 v26, v214, v30, s[24:25]
	v_cndmask_b32_e64 v27, v215, v31, s[24:25]
	v_cndmask_b32_e64 v28, v28, v212, s[24:25]
	v_cndmask_b32_e64 v29, v29, v213, s[24:25]
	v_cndmask_b32_e64 v30, v30, v214, s[24:25]
	v_cndmask_b32_e64 v31, v31, v215, s[24:25]
	v_mov_b32_dpp v212, v16 row_ror:8 row_mask:0xf bank_mask:0xf
	v_mov_b32_dpp v213, v17 row_ror:8 row_mask:0xf bank_mask:0xf
	v_mov_b32_dpp v214, v18 row_ror:8 row_mask:0xf bank_mask:0xf
	v_mov_b32_dpp v215, v19 row_ror:8 row_mask:0xf bank_mask:0xf
	v_cndmask_b32_e64 v16, v212, v20, s[24:25]
	v_cndmask_b32_e64 v17, v213, v21, s[24:25]
	v_cndmask_b32_e64 v18, v214, v22, s[24:25]
	v_cndmask_b32_e64 v19, v215, v23, s[24:25]
	v_cndmask_b32_e64 v20, v20, v212, s[24:25]
	v_cndmask_b32_e64 v21, v21, v213, s[24:25]
	v_cndmask_b32_e64 v22, v22, v214, s[24:25]
	v_cndmask_b32_e64 v23, v23, v215, s[24:25]
	s_waitcnt vmcnt(1)
;     __device__ __forceinline__ void operator()(const f32x4 (&acc)[2][2][4][2], const Unit& u, int wr, int wc, int fr, int fq) const {
;     ...
;         for (int ai = 0; ai < 2; ++ai)
; #pragma unroll
;             for (int m = 0; m < 4; ++m) {
;                 const int row = row0 + ai * HALF + m * 16;
;                 const size_t off = (size_t)row * ldc + col0;
;                 float q = 0.f;
; #pragma unroll
;                 for (int bj = 0; bj < 2; ++bj)
; #pragma unroll
;                     for (int n = 0; n < 2; ++n) {
;                         const f32x4 rv = *(const f32x4*)(rbase + off + bj * HALF + n * 16);
;                         const f32x4 v = rv + acc[ai][bj][m][n] * scale;
;                         if (out) *(f32x4*)(out + off + bj * HALF + n * 16) = v;
;                         if (xn) { q += (v.x * v.x + v.y * v.y) + (v.z * v.z + v.w * v.w); const f32x4 o = v * wv[bj][n];
;                             u32x2 p; p.x = pk2(o.x, o.y); p.y = pk2(o.z, o.w); *(u32x2*)(xn + off + bj * HALF + n * 16) = p; }
;                     }
;                 if (xn) { q += __shfl_xor(q, 16); q += __shfl_xor(q, 32); if (fq == 0) (void)__hip_atomic_fetch_add(ss + row, q, __ATOMIC_RELAXED, __HIP_MEMORY_SCOPE_AGENT); }
;             }
	v_pk_fma_f32 v[26:27], v[26:27], 0.5, v[158:159] op_sel_hi:[1,0,1]
	v_pk_fma_f32 v[24:25], v[24:25], 0.5, v[156:157] op_sel_hi:[1,0,1]
	v_pk_mul_f32 v[200:201], v[72:73], v[24:25]
	v_pk_mul_f32 v[202:203], v[74:75], v[26:27]
	v_mul_f32_e32 v218, v24, v24
	v_add_u32_e32 v200, 0x8000, v200
	v_add_u32_e32 v201, 0x8000, v201
	v_add_u32_e32 v202, 0x8000, v202
	v_add_u32_e32 v203, 0x8000, v203
	v_fmac_f32_e32 v218, v25, v25
	v_fmac_f32_e32 v218, v26, v26
	v_fmac_f32_e32 v218, v27, v27
	v_perm_b32 v208, v201, v200, s50
	v_perm_b32 v209, v203, v202, s50
	global_store_dwordx2 v[184:185], v[208:209], off
	v_pk_fma_f32 v[18:19], v[18:19], 0.5, v[170:171] op_sel_hi:[1,0,1]
	v_pk_fma_f32 v[16:17], v[16:17], 0.5, v[168:169] op_sel_hi:[1,0,1]
	v_pk_mul_f32 v[204:205], v[84:85], v[16:17]
	v_pk_mul_f32 v[206:207], v[86:87], v[18:19]
	v_fmac_f32_e32 v218, v16, v16
	v_add_u32_e32 v204, 0x8000, v204
	v_add_u32_e32 v205, 0x8000, v205
	v_add_u32_e32 v206, 0x8000, v206
	v_add_u32_e32 v207, 0x8000, v207
	v_fmac_f32_e32 v218, v17, v17
	v_fmac_f32_e32 v218, v18, v18
	v_fmac_f32_e32 v218, v19, v19
	v_perm_b32 v210, v205, v204, s50
	v_perm_b32 v211, v207, v206, s50
	global_store_dwordx2 v[184:185], v[210:211], off offset:256
	v_pk_fma_f32 v[30:31], v[30:31], 0.5, v[174:175] op_sel_hi:[1,0,1]
	v_pk_fma_f32 v[28:29], v[28:29], 0.5, v[172:173] op_sel_hi:[1,0,1]
	v_pk_mul_f32 v[200:201], v[88:89], v[28:29]
	v_pk_mul_f32 v[202:203], v[90:91], v[30:31]
	v_mul_f32_e32 v219, v28, v28
	v_add_u32_e32 v200, 0x8000, v200
	v_add_u32_e32 v201, 0x8000, v201
	v_add_u32_e32 v202, 0x8000, v202
	v_add_u32_e32 v203, 0x8000, v203
	v_fmac_f32_e32 v219, v29, v29
	v_fmac_f32_e32 v219, v30, v30
	v_fmac_f32_e32 v219, v31, v31
	v_perm_b32 v208, v201, v200, s50
	v_perm_b32 v209, v203, v202, s50
	global_store_dwordx2 v[186:187], v[208:209], off
	v_pk_fma_f32 v[22:23], v[22:23], 0.5, v[178:179] op_sel_hi:[1,0,1]
	v_pk_fma_f32 v[20:21], v[20:21], 0.5, v[176:177] op_sel_hi:[1,0,1]
	v_pk_mul_f32 v[204:205], v[96:97], v[20:21]
	v_pk_mul_f32 v[206:207], v[98:99], v[22:23]
	v_fmac_f32_e32 v219, v20, v20
	v_add_u32_e32 v204, 0x8000, v204
	v_add_u32_e32 v205, 0x8000, v205
	v_add_u32_e32 v206, 0x8000, v206
	v_add_u32_e32 v207, 0x8000, v207
	v_fmac_f32_e32 v219, v21, v21
	v_fmac_f32_e32 v219, v22, v22
	v_fmac_f32_e32 v219, v23, v23
	v_perm_b32 v210, v205, v204, s50
	v_perm_b32 v211, v207, v206, s50
	global_store_dwordx2 v[186:187], v[210:211], off offset:256
	s_nop 1
	v_mov_b32_dpp v216, v218 row_ror:8 row_mask:0xf bank_mask:0xf
	v_mov_b32_dpp v217, v219 row_ror:8 row_mask:0xf bank_mask:0xf
	v_add_f32_e32 v218, v218, v216
	v_add_f32_e32 v219, v219, v217
	v_cndmask_b32_e64 v218, v219, v218, s[24:25]
	s_nop 0
	ds_bpermute_b32 v216, v220, v218
	global_load_dwordx4 v[156:159], v[180:181], off
	global_load_dwordx4 v[168:171], v[180:181], off offset:512
	global_load_dwordx4 v[172:175], v[182:183], off
	global_load_dwordx4 v[176:179], v[182:183], off offset:512
	s_mov_b64 vcc, 0x20000
	s_mov_b64 vcc, 0x10000
	v_lshl_add_u64 v[184:185], v[184:185], 0, vcc
	v_lshl_add_u64 v[186:187], v[186:187], 0, vcc
	s_waitcnt lgkmcnt(0)
	v_add_f32_e32 v218, v218, v216
	s_nop 0
	ds_bpermute_b32 v217, v221, v218
	s_waitcnt lgkmcnt(0)
;     __device__ __forceinline__ void operator()(const f32x4 (&acc)[2][2][4][2], const Unit& u, int wr, int wc, int fr, int fq) const {
;     ...
;         for (int ai = 0; ai < 2; ++ai)
; #pragma unroll
;             for (int m = 0; m < 4; ++m) {
;                 const int row = row0 + ai * HALF + m * 16;
;                 const size_t off = (size_t)row * ldc + col0;
;                 float q = 0.f;
; #pragma unroll
;                 for (int bj = 0; bj < 2; ++bj)
; #pragma unroll
;                     for (int n = 0; n < 2; ++n) {
;                         const f32x4 rv = *(const f32x4*)(rbase + off + bj * HALF + n * 16);
;                         const f32x4 v = rv + acc[ai][bj][m][n] * scale;
;                         if (out) *(f32x4*)(out + off + bj * HALF + n * 16) = v;
;                         if (xn) { q += (v.x * v.x + v.y * v.y) + (v.z * v.z + v.w * v.w); const f32x4 o = v * wv[bj][n];
;                             u32x2 p; p.x = pk2(o.x, o.y); p.y = pk2(o.z, o.w); *(u32x2*)(xn + off + bj * HALF + n * 16) = p; }
;                     }
;                 if (xn) { q += __shfl_xor(q, 16); q += __shfl_xor(q, 32); if (fq == 0) (void)__hip_atomic_fetch_add(ss + row, q, __ATOMIC_RELAXED, __HIP_MEMORY_SCOPE_AGENT); }
;             }
; template <class Epi, bool ALIGN_EPI>
; __device__ __forceinline__ void gemm_phase(LAS unsigned char* lds, const Gemm g, const StaticOrder& S, const Epi& E) {
;     ...
;         if (!has_next) break;
	v_add_f32_e32 v218, v218, v217
	s_mov_b64 exec, s[0:1]
	global_atomic_add_f32 v[188:189], v218, off
	s_mov_b64 exec, -1
	s_mov_b64 vcc, 64
	v_lshl_add_u64 v[188:189], v[188:189], 0, vcc
	v_mov_b32_dpp v212, v8 row_ror:8 row_mask:0xf bank_mask:0xf
	v_mov_b32_dpp v213, v9 row_ror:8 row_mask:0xf bank_mask:0xf
	v_mov_b32_dpp v214, v10 row_ror:8 row_mask:0xf bank_mask:0xf
	v_mov_b32_dpp v215, v11 row_ror:8 row_mask:0xf bank_mask:0xf
	v_cndmask_b32_e64 v8, v212, v12, s[24:25]
	v_cndmask_b32_e64 v9, v213, v13, s[24:25]
	v_cndmask_b32_e64 v10, v214, v14, s[24:25]
	v_cndmask_b32_e64 v11, v215, v15, s[24:25]
	v_cndmask_b32_e64 v12, v12, v212, s[24:25]
	v_cndmask_b32_e64 v13, v13, v213, s[24:25]
	v_cndmask_b32_e64 v14, v14, v214, s[24:25]
	v_cndmask_b32_e64 v15, v15, v215, s[24:25]
	v_mov_b32_dpp v212, v0 row_ror:8 row_mask:0xf bank_mask:0xf
	v_mov_b32_dpp v213, v1 row_ror:8 row_mask:0xf bank_mask:0xf
	v_mov_b32_dpp v214, v2 row_ror:8 row_mask:0xf bank_mask:0xf
	v_mov_b32_dpp v215, v3 row_ror:8 row_mask:0xf bank_mask:0xf
	v_cndmask_b32_e64 v0, v212, v4, s[24:25]
	v_cndmask_b32_e64 v1, v213, v5, s[24:25]
	v_cndmask_b32_e64 v2, v214, v6, s[24:25]
	v_cndmask_b32_e64 v3, v215, v7, s[24:25]
	v_cndmask_b32_e64 v4, v4, v212, s[24:25]
	v_cndmask_b32_e64 v5, v5, v213, s[24:25]
	v_cndmask_b32_e64 v6, v6, v214, s[24:25]
	v_cndmask_b32_e64 v7, v7, v215, s[24:25]
	s_waitcnt vmcnt(1)
	v_pk_fma_f32 v[10:11], v[10:11], 0.5, v[158:159] op_sel_hi:[1,0,1]
	v_pk_fma_f32 v[8:9], v[8:9], 0.5, v[156:157] op_sel_hi:[1,0,1]
	v_pk_mul_f32 v[200:201], v[72:73], v[8:9]
	v_pk_mul_f32 v[202:203], v[74:75], v[10:11]
	v_mul_f32_e32 v218, v8, v8
	v_add_u32_e32 v200, 0x8000, v200
	v_add_u32_e32 v201, 0x8000, v201
	v_add_u32_e32 v202, 0x8000, v202
	v_add_u32_e32 v203, 0x8000, v203
	v_fmac_f32_e32 v218, v9, v9
	v_fmac_f32_e32 v218, v10, v10
	v_fmac_f32_e32 v218, v11, v11
	v_perm_b32 v208, v201, v200, s50
	v_perm_b32 v209, v203, v202, s50
	global_store_dwordx2 v[184:185], v[208:209], off
	v_pk_fma_f32 v[2:3], v[2:3], 0.5, v[170:171] op_sel_hi:[1,0,1]
	v_pk_fma_f32 v[0:1], v[0:1], 0.5, v[168:169] op_sel_hi:[1,0,1]
	v_pk_mul_f32 v[204:205], v[84:85], v[0:1]
	v_pk_mul_f32 v[206:207], v[86:87], v[2:3]
	v_fmac_f32_e32 v218, v0, v0
	v_add_u32_e32 v204, 0x8000, v204
	v_add_u32_e32 v205, 0x8000, v205
	v_add_u32_e32 v206, 0x8000, v206
	v_add_u32_e32 v207, 0x8000, v207
	v_fmac_f32_e32 v218, v1, v1
	v_fmac_f32_e32 v218, v2, v2
	v_fmac_f32_e32 v218, v3, v3
	v_perm_b32 v210, v205, v204, s50
	v_perm_b32 v211, v207, v206, s50
	global_store_dwordx2 v[184:185], v[210:211], off offset:256
	v_pk_fma_f32 v[14:15], v[14:15], 0.5, v[174:175] op_sel_hi:[1,0,1]
	v_pk_fma_f32 v[12:13], v[12:13], 0.5, v[172:173] op_sel_hi:[1,0,1]
	v_pk_mul_f32 v[200:201], v[88:89], v[12:13]
	v_pk_mul_f32 v[202:203], v[90:91], v[14:15]
	v_mul_f32_e32 v219, v12, v12
	v_add_u32_e32 v200, 0x8000, v200
	v_add_u32_e32 v201, 0x8000, v201
	v_add_u32_e32 v202, 0x8000, v202
	v_add_u32_e32 v203, 0x8000, v203
	v_fmac_f32_e32 v219, v13, v13
	v_fmac_f32_e32 v219, v14, v14
	v_fmac_f32_e32 v219, v15, v15
	v_perm_b32 v208, v201, v200, s50
	v_perm_b32 v209, v203, v202, s50
	global_store_dwordx2 v[186:187], v[208:209], off
	v_pk_fma_f32 v[6:7], v[6:7], 0.5, v[178:179] op_sel_hi:[1,0,1]
	v_pk_fma_f32 v[4:5], v[4:5], 0.5, v[176:177] op_sel_hi:[1,0,1]
	v_pk_mul_f32 v[204:205], v[96:97], v[4:5]
	v_pk_mul_f32 v[206:207], v[98:99], v[6:7]
	v_fmac_f32_e32 v219, v4, v4
	v_add_u32_e32 v204, 0x8000, v204
	v_add_u32_e32 v205, 0x8000, v205
	v_add_u32_e32 v206, 0x8000, v206
	v_add_u32_e32 v207, 0x8000, v207
	v_fmac_f32_e32 v219, v5, v5
	v_fmac_f32_e32 v219, v6, v6
	v_fmac_f32_e32 v219, v7, v7
	v_perm_b32 v210, v205, v204, s50
	v_perm_b32 v211, v207, v206, s50
	global_store_dwordx2 v[186:187], v[210:211], off offset:256
	s_nop 1
	v_mov_b32_dpp v216, v218 row_ror:8 row_mask:0xf bank_mask:0xf
	v_mov_b32_dpp v217, v219 row_ror:8 row_mask:0xf bank_mask:0xf
	v_add_f32_e32 v218, v218, v216
	v_add_f32_e32 v219, v219, v217
	v_cndmask_b32_e64 v218, v219, v218, s[24:25]
	s_nop 0
	ds_bpermute_b32 v216, v220, v218
	s_waitcnt lgkmcnt(0)
	v_add_f32_e32 v218, v218, v216
	s_nop 0
	ds_bpermute_b32 v217, v221, v218
	s_waitcnt lgkmcnt(0)
	v_add_f32_e32 v218, v218, v217
	s_mov_b64 exec, s[0:1]
	global_atomic_add_f32 v[188:189], v218, off
	s_mov_b64 exec, -1
	s_and_b64 vcc, exec, s[6:7]
	s_mov_b64 s[6:7], -1
	s_cbranch_vccnz .LBB0_1371
	s_andn2_b64 vcc, exec, s[12:13]
	s_cbranch_vccnz .LBB0_1370
	s_barrier
	s_branch .LBB0_1370
